# hoisted per-row-group operand loads ahead of their consumers in the G gate epilogue, projA rope epilogue and Y gate epilogue (counted vmcnt instead of load-wait-use chains)
# speedup vs baseline: 1.0120x; 1.0021x over previous
; template <int NI>
; DEV void projA_epiN(const Params& p, f32x4 (&acc)[NI][8], int seg, int cw, int trow0, int lr, int lg) {
;     ...
;     const int t = trow0 + i * 16 + lr;
;     if (seg == 0) {
;       const float2* tab = R128 + (size_t)t * 64;
; #pragma unroll
;       for (int j = 0; j < 4; j++)
; #pragma unroll
;         for (int r = 0; r < 4; r++) {
;           float2 cs = tab[j * 16 + lg * 4 + r];
;           float x1 = acc[i][j][r], x2 = acc[i][j + 4][r];
;           acc[i][j][r] = x1 * cs.x - x2 * cs.y;
;           acc[i][j + 4][r] = x2 * cs.x + x1 * cs.y;
;         }
.LBB0_202:
	v_lshlrev_b64 v[34:35], 9, v[42:43]
	v_lshl_add_u64 v[34:35], s[64:65], 0, v[34:35]
	v_mov_b32_e32 v131, v1
	v_lshl_add_u64 v[36:37], v[34:35], 0, v[130:131]
	global_load_dwordx4 v[220:223], v[36:37], off offset:16
	global_load_dwordx4 v[224:227], v[36:37], off
	global_load_dwordx4 v[228:231], v[36:37], off offset:144
	global_load_dwordx4 v[232:235], v[36:37], off offset:128
	global_load_dwordx4 v[236:239], v[36:37], off offset:272
	global_load_dwordx4 v[240:243], v[36:37], off offset:256
	global_load_dwordx4 v[244:247], v[36:37], off offset:400
	global_load_dwordx4 v[248:251], v[36:37], off offset:384
	s_waitcnt vmcnt(7)
	v_mul_f32_e32 v50, v32, v220
	s_waitcnt vmcnt(6)
	v_mov_b32_e32 v35, v226
	v_mov_b32_e32 v46, v225
	v_mul_f32_e32 v52, v28, v221
	v_mul_f32_e32 v38, v28, v220
	v_mov_b32_e32 v28, v33
	v_mov_b32_e32 v34, v224
	v_mov_b32_e32 v47, v227
	v_pk_mul_f32 v[48:49], v[30:31], v[46:47]
	v_pk_mul_f32 v[44:45], v[26:27], v[46:47]
	v_mul_f32_e32 v54, v32, v221
	v_pk_mul_f32 v[46:47], v[28:29], v[222:223]
	v_mov_b32_e32 v32, v29
	v_mov_b32_e32 v51, v46
	v_mov_b32_e32 v53, v47
	v_pk_mul_f32 v[28:29], v[32:33], v[222:223]
	v_pk_fma_f32 v[46:47], v[30:31], v[34:35], v[44:45] neg_lo:[0,0,1] neg_hi:[0,0,1]
	v_pk_add_f32 v[44:45], v[50:51], v[52:53] neg_lo:[0,1] neg_hi:[0,1]
	v_mov_b32_e32 v39, v28
	v_mov_b32_e32 v55, v29
	v_pk_fma_f32 v[50:51], v[26:27], v[34:35], v[48:49]
	v_pk_add_f32 v[48:49], v[38:39], v[54:55]
	s_waitcnt vmcnt(5)
	v_mul_f32_e32 v34, v24, v228
	s_waitcnt vmcnt(4)
	v_mov_b32_e32 v41, v234
	v_mov_b32_e32 v32, v233
	v_mul_f32_e32 v52, v20, v229
	v_mul_f32_e32 v26, v20, v228
	v_mul_f32_e32 v54, v24, v229
	v_mov_b32_e32 v20, v25
	v_mov_b32_e32 v24, v21
	v_mov_b32_e32 v40, v232
	v_mov_b32_e32 v33, v235
	v_pk_mul_f32 v[30:31], v[22:23], v[32:33]
	v_pk_mul_f32 v[32:33], v[18:19], v[32:33]
	v_pk_mul_f32 v[38:39], v[20:21], v[230:231]
	v_pk_mul_f32 v[20:21], v[24:25], v[230:231]
	v_mov_b32_e32 v35, v38
	v_mov_b32_e32 v53, v39
	v_pk_fma_f32 v[38:39], v[22:23], v[40:41], v[32:33] neg_lo:[0,0,1] neg_hi:[0,0,1]
	v_mov_b32_e32 v27, v20
	v_mov_b32_e32 v55, v21
	v_pk_fma_f32 v[60:61], v[18:19], v[40:41], v[30:31]
	v_pk_add_f32 v[40:41], v[26:27], v[54:55]
	v_pk_add_f32 v[34:35], v[34:35], v[52:53] neg_lo:[0,1] neg_hi:[0,1]
	s_waitcnt vmcnt(3)
	v_mul_f32_e32 v28, v16, v236
	s_waitcnt vmcnt(2)
	v_mov_b32_e32 v27, v242
	v_mov_b32_e32 v24, v241
	v_mul_f32_e32 v30, v12, v237
	v_mul_f32_e32 v18, v12, v236
	v_mul_f32_e32 v32, v16, v237
	v_mov_b32_e32 v12, v17
	v_mov_b32_e32 v16, v13
	v_mov_b32_e32 v26, v240
	v_mov_b32_e32 v25, v243
	v_pk_mul_f32 v[22:23], v[14:15], v[24:25]
	v_pk_mul_f32 v[24:25], v[10:11], v[24:25]
	v_pk_mul_f32 v[52:53], v[12:13], v[238:239]
	v_pk_mul_f32 v[12:13], v[16:17], v[238:239]
	v_pk_fma_f32 v[54:55], v[14:15], v[26:27], v[24:25] neg_lo:[0,0,1] neg_hi:[0,0,1]
	v_mov_b32_e32 v19, v12
	v_mov_b32_e32 v33, v13
	v_pk_fma_f32 v[58:59], v[10:11], v[26:27], v[22:23]
	v_pk_add_f32 v[56:57], v[18:19], v[32:33]
	v_mov_b32_e32 v29, v52
	v_mov_b32_e32 v31, v53
	v_pk_add_f32 v[52:53], v[28:29], v[30:31] neg_lo:[0,1] neg_hi:[0,1]
	s_waitcnt vmcnt(1)
	v_mul_f32_e32 v20, v8, v244
	v_mul_f32_e32 v22, v4, v245
	v_mul_f32_e32 v10, v4, v244
	v_mul_f32_e32 v24, v8, v245
	v_mov_b32_e32 v4, v9
	v_mov_b32_e32 v8, v5
	s_waitcnt vmcnt(0)
	v_mov_b32_e32 v19, v250
	v_mov_b32_e32 v16, v249
	v_pk_mul_f32 v[26:27], v[4:5], v[246:247]
	v_pk_mul_f32 v[4:5], v[8:9], v[246:247]
	v_mov_b32_e32 v18, v248
	v_mov_b32_e32 v17, v251
	v_pk_mul_f32 v[14:15], v[6:7], v[16:17]
	v_pk_mul_f32 v[16:17], v[2:3], v[16:17]
	v_mov_b32_e32 v21, v26
	v_mov_b32_e32 v23, v27
	v_mov_b32_e32 v11, v4
	v_mov_b32_e32 v25, v5
	v_pk_fma_f32 v[76:77], v[6:7], v[18:19], v[16:17] neg_lo:[0,0,1] neg_hi:[0,0,1]
	v_pk_add_f32 v[62:63], v[20:21], v[22:23] neg_lo:[0,1] neg_hi:[0,1]
	v_pk_fma_f32 v[64:65], v[2:3], v[18:19], v[14:15]
	v_pk_add_f32 v[36:37], v[10:11], v[24:25]
	v_mov_b32_e32 v12, v246
	v_mov_b32_e32 v13, v247

; template <int NI>
; DEV void projA_epiN(const Params& p, f32x4 (&acc)[NI][8], int seg, int cw, int trow0, int lr, int lg) {
;     ...
;     const int t = trow0 + i * 16 + lr;
;     if (seg == 0) {
;       const float2* tab = R128 + (size_t)t * 64;
; #pragma unroll
;       for (int j = 0; j < 4; j++)
; #pragma unroll
;         for (int r = 0; r < 4; r++) {
;           float2 cs = tab[j * 16 + lg * 4 + r];
;           float x1 = acc[i][j][r], x2 = acc[i][j + 4][r];
;           acc[i][j][r] = x1 * cs.x - x2 * cs.y;
;           acc[i][j + 4][r] = x2 * cs.x + x1 * cs.y;
;         }
.LBB0_323:
	v_lshlrev_b64 v[132:133], 9, v[140:141]
	v_lshl_add_u64 v[132:133], s[64:65], 0, v[132:133]
	v_mov_b32_e32 v131, v1
	v_lshl_add_u64 v[132:133], v[132:133], 0, v[130:131]
	global_load_dwordx4 v[220:223], v[132:133], off offset:16
	global_load_dwordx4 v[224:227], v[132:133], off
	global_load_dwordx4 v[228:231], v[132:133], off offset:144
	global_load_dwordx4 v[232:235], v[132:133], off offset:128
	global_load_dwordx4 v[236:239], v[132:133], off offset:272
	global_load_dwordx4 v[240:243], v[132:133], off offset:256
	global_load_dwordx4 v[244:247], v[132:133], off offset:400
	global_load_dwordx4 v[248:251], v[132:133], off offset:384
	s_waitcnt vmcnt(7)
	v_mul_f32_e32 v150, v128, v220
	s_waitcnt vmcnt(6)
	v_mov_b32_e32 v147, v226
	v_mov_b32_e32 v144, v225
	v_mul_f32_e32 v152, v124, v221
	v_mul_f32_e32 v134, v124, v220
	v_mul_f32_e32 v154, v128, v221
	v_mov_b32_e32 v124, v129
	v_mov_b32_e32 v128, v125
	v_mov_b32_e32 v146, v224
	v_mov_b32_e32 v145, v227
	v_pk_mul_f32 v[148:149], v[126:127], v[144:145]
	v_pk_mul_f32 v[142:143], v[122:123], v[144:145]
	v_pk_mul_f32 v[144:145], v[124:125], v[222:223]
	v_pk_mul_f32 v[124:125], v[128:129], v[222:223]
	v_mov_b32_e32 v151, v144
	v_mov_b32_e32 v153, v145
	v_pk_fma_f32 v[144:145], v[126:127], v[146:147], v[142:143] neg_lo:[0,0,1] neg_hi:[0,0,1]
	v_mov_b32_e32 v135, v124
	v_mov_b32_e32 v155, v125
	v_pk_fma_f32 v[148:149], v[122:123], v[146:147], v[148:149]
	v_pk_add_f32 v[142:143], v[150:151], v[152:153] neg_lo:[0,1] neg_hi:[0,1]
	v_pk_add_f32 v[146:147], v[134:135], v[154:155]
	s_waitcnt vmcnt(5)
	v_mul_f32_e32 v134, v120, v228
	s_waitcnt vmcnt(4)
	v_mov_b32_e32 v151, v234
	v_mov_b32_e32 v128, v233
	v_mul_f32_e32 v152, v116, v229
	v_mul_f32_e32 v122, v116, v228
	v_mul_f32_e32 v154, v120, v229
	v_mov_b32_e32 v116, v121
	v_mov_b32_e32 v120, v117
	v_mov_b32_e32 v150, v232
	v_mov_b32_e32 v129, v235
	v_pk_mul_f32 v[126:127], v[118:119], v[128:129]
	v_pk_mul_f32 v[128:129], v[114:115], v[128:129]
	v_pk_mul_f32 v[136:137], v[116:117], v[230:231]
	v_pk_mul_f32 v[116:117], v[120:121], v[230:231]
	v_mov_b32_e32 v135, v136
	v_mov_b32_e32 v153, v137
	v_pk_fma_f32 v[136:137], v[118:119], v[150:151], v[128:129] neg_lo:[0,0,1] neg_hi:[0,0,1]
	v_mov_b32_e32 v123, v116
	v_mov_b32_e32 v155, v117
	v_pk_fma_f32 v[160:161], v[114:115], v[150:151], v[126:127]
	v_pk_add_f32 v[158:159], v[122:123], v[154:155]
	v_pk_add_f32 v[134:135], v[134:135], v[152:153] neg_lo:[0,1] neg_hi:[0,1]
	s_waitcnt vmcnt(3)
	v_mul_f32_e32 v124, v112, v236
	s_waitcnt vmcnt(2)
	v_mov_b32_e32 v123, v242
	v_mov_b32_e32 v120, v241
	v_mul_f32_e32 v126, v108, v237
	v_mul_f32_e32 v114, v108, v236
	v_mul_f32_e32 v128, v112, v237
	v_mov_b32_e32 v108, v113
	v_mov_b32_e32 v112, v109
	v_mov_b32_e32 v122, v240
	v_mov_b32_e32 v121, v243
	v_pk_mul_f32 v[118:119], v[110:111], v[120:121]
	v_pk_mul_f32 v[120:121], v[106:107], v[120:121]
	v_pk_mul_f32 v[150:151], v[108:109], v[238:239]
	v_pk_mul_f32 v[108:109], v[112:113], v[238:239]
	v_pk_fma_f32 v[152:153], v[110:111], v[122:123], v[120:121] neg_lo:[0,0,1] neg_hi:[0,0,1]
	v_mov_b32_e32 v115, v108
	v_mov_b32_e32 v129, v109
	v_pk_fma_f32 v[156:157], v[106:107], v[122:123], v[118:119]
	v_pk_add_f32 v[154:155], v[114:115], v[128:129]
	v_mov_b32_e32 v125, v150
	v_mov_b32_e32 v127, v151
	v_pk_add_f32 v[150:151], v[124:125], v[126:127] neg_lo:[0,1] neg_hi:[0,1]
	s_waitcnt vmcnt(1)
	v_mul_f32_e32 v116, v104, v244
	v_mul_f32_e32 v118, v100, v245
	v_mul_f32_e32 v106, v100, v244
	v_mul_f32_e32 v120, v104, v245
	v_mov_b32_e32 v100, v105
	v_mov_b32_e32 v104, v101
	s_waitcnt vmcnt(0)
	v_mov_b32_e32 v115, v250
	v_mov_b32_e32 v112, v249
	v_pk_mul_f32 v[122:123], v[100:101], v[246:247]
	v_pk_mul_f32 v[100:101], v[104:105], v[246:247]
	v_mov_b32_e32 v114, v248
	v_mov_b32_e32 v113, v251
	v_pk_mul_f32 v[110:111], v[102:103], v[112:113]
	v_pk_mul_f32 v[112:113], v[98:99], v[112:113]
	v_mov_b32_e32 v117, v122
	v_mov_b32_e32 v119, v123
	v_mov_b32_e32 v107, v100
	v_mov_b32_e32 v121, v101
	v_pk_fma_f32 v[168:169], v[102:103], v[114:115], v[112:113] neg_lo:[0,0,1] neg_hi:[0,0,1]
	v_pk_add_f32 v[164:165], v[116:117], v[118:119] neg_lo:[0,1] neg_hi:[0,1]
	v_pk_fma_f32 v[162:163], v[98:99], v[114:115], v[110:111]
	v_pk_add_f32 v[132:133], v[106:107], v[120:121]
	v_mov_b32_e32 v108, v246
	v_mov_b32_e32 v109, v247

; template <int NI>
; DEV void projA_epiN(const Params& p, f32x4 (&acc)[NI][8], int seg, int cw, int trow0, int lr, int lg) {
;     ...
;     const int t = trow0 + i * 16 + lr;
;     if (seg == 0) {
;       const float2* tab = R128 + (size_t)t * 64;
; #pragma unroll
;       for (int j = 0; j < 4; j++)
; #pragma unroll
;         for (int r = 0; r < 4; r++) {
;           float2 cs = tab[j * 16 + lg * 4 + r];
;           float x1 = acc[i][j][r], x2 = acc[i][j + 4][r];
;           acc[i][j][r] = x1 * cs.x - x2 * cs.y;
;           acc[i][j + 4][r] = x2 * cs.x + x1 * cs.y;
;         }
.LBB0_328:
	v_lshlrev_b64 v[98:99], 9, v[108:109]
	v_lshl_add_u64 v[98:99], s[64:65], 0, v[98:99]
	v_mov_b32_e32 v131, v1
	v_lshl_add_u64 v[100:101], v[98:99], 0, v[130:131]
	global_load_dwordx4 v[220:223], v[100:101], off offset:16
	global_load_dwordx4 v[224:227], v[100:101], off
	global_load_dwordx4 v[228:231], v[100:101], off offset:144
	global_load_dwordx4 v[232:235], v[100:101], off offset:128
	global_load_dwordx4 v[236:239], v[100:101], off offset:272
	global_load_dwordx4 v[240:243], v[100:101], off offset:256
	global_load_dwordx4 v[244:247], v[100:101], off offset:400
	global_load_dwordx4 v[248:251], v[100:101], off offset:384
	s_waitcnt vmcnt(7)
	v_mul_f32_e32 v116, v96, v220
	s_waitcnt vmcnt(6)
	v_mov_b32_e32 v99, v226
	v_mov_b32_e32 v112, v225
	v_mul_f32_e32 v118, v92, v221
	v_mul_f32_e32 v102, v92, v220
	v_mov_b32_e32 v92, v97
	v_mov_b32_e32 v98, v224
	v_mov_b32_e32 v113, v227
	v_pk_mul_f32 v[114:115], v[94:95], v[112:113]
	v_pk_mul_f32 v[110:111], v[90:91], v[112:113]
	v_mul_f32_e32 v120, v96, v221
	v_pk_mul_f32 v[112:113], v[92:93], v[222:223]
	v_mov_b32_e32 v96, v93
	v_mov_b32_e32 v117, v112
	v_mov_b32_e32 v119, v113
	v_pk_mul_f32 v[92:93], v[96:97], v[222:223]
	v_pk_fma_f32 v[112:113], v[94:95], v[98:99], v[110:111] neg_lo:[0,0,1] neg_hi:[0,0,1]
	v_pk_add_f32 v[110:111], v[116:117], v[118:119] neg_lo:[0,1] neg_hi:[0,1]
	v_mov_b32_e32 v103, v92
	v_mov_b32_e32 v121, v93
	v_pk_fma_f32 v[116:117], v[90:91], v[98:99], v[114:115]
	v_pk_add_f32 v[114:115], v[102:103], v[120:121]
	s_waitcnt vmcnt(5)
	v_mul_f32_e32 v98, v88, v228
	s_waitcnt vmcnt(4)
	v_mov_b32_e32 v105, v234
	v_mov_b32_e32 v96, v233
	v_mul_f32_e32 v118, v84, v229
	v_mul_f32_e32 v90, v84, v228
	v_mul_f32_e32 v120, v88, v229
	v_mov_b32_e32 v84, v89
	v_mov_b32_e32 v88, v85
	v_mov_b32_e32 v104, v232
	v_mov_b32_e32 v97, v235
	v_pk_mul_f32 v[94:95], v[86:87], v[96:97]
	v_pk_mul_f32 v[96:97], v[82:83], v[96:97]
	v_pk_mul_f32 v[102:103], v[84:85], v[230:231]
	v_pk_mul_f32 v[84:85], v[88:89], v[230:231]
	v_mov_b32_e32 v99, v102
	v_mov_b32_e32 v119, v103
	v_pk_fma_f32 v[102:103], v[86:87], v[104:105], v[96:97] neg_lo:[0,0,1] neg_hi:[0,0,1]
	v_mov_b32_e32 v91, v84
	v_mov_b32_e32 v121, v85
	v_pk_fma_f32 v[126:127], v[82:83], v[104:105], v[94:95]
	v_pk_add_f32 v[104:105], v[90:91], v[120:121]
	v_pk_add_f32 v[98:99], v[98:99], v[118:119] neg_lo:[0,1] neg_hi:[0,1]
	s_waitcnt vmcnt(3)
	v_mul_f32_e32 v92, v80, v236
	s_waitcnt vmcnt(2)
	v_mov_b32_e32 v91, v242
	v_mov_b32_e32 v88, v241
	v_mul_f32_e32 v94, v76, v237
	v_mul_f32_e32 v82, v76, v236
	v_mul_f32_e32 v96, v80, v237
	v_mov_b32_e32 v76, v81
	v_mov_b32_e32 v80, v77
	v_mov_b32_e32 v90, v240
	v_mov_b32_e32 v89, v243
	v_pk_mul_f32 v[86:87], v[78:79], v[88:89]
	v_pk_mul_f32 v[88:89], v[74:75], v[88:89]
	v_pk_mul_f32 v[118:119], v[76:77], v[238:239]
	v_pk_mul_f32 v[76:77], v[80:81], v[238:239]
	v_pk_fma_f32 v[120:121], v[78:79], v[90:91], v[88:89] neg_lo:[0,0,1] neg_hi:[0,0,1]
	v_mov_b32_e32 v83, v76
	v_mov_b32_e32 v97, v77
	v_pk_fma_f32 v[124:125], v[74:75], v[90:91], v[86:87]
	v_pk_add_f32 v[122:123], v[82:83], v[96:97]
	v_mov_b32_e32 v93, v118
	v_mov_b32_e32 v95, v119
	v_pk_add_f32 v[118:119], v[92:93], v[94:95] neg_lo:[0,1] neg_hi:[0,1]
	s_waitcnt vmcnt(1)
	v_mul_f32_e32 v84, v72, v244
	v_mul_f32_e32 v86, v68, v245
	v_mul_f32_e32 v74, v68, v244
	v_mul_f32_e32 v88, v72, v245
	v_mov_b32_e32 v68, v73
	v_mov_b32_e32 v72, v69
	s_waitcnt vmcnt(0)
	v_mov_b32_e32 v83, v250
	v_mov_b32_e32 v80, v249
	v_pk_mul_f32 v[90:91], v[68:69], v[246:247]
	v_pk_mul_f32 v[68:69], v[72:73], v[246:247]
	v_mov_b32_e32 v82, v248
	v_mov_b32_e32 v81, v251
	v_pk_mul_f32 v[78:79], v[70:71], v[80:81]
	v_pk_mul_f32 v[80:81], v[66:67], v[80:81]
	v_mov_b32_e32 v85, v90
	v_mov_b32_e32 v87, v91
	v_mov_b32_e32 v75, v68
	v_mov_b32_e32 v89, v69
	v_pk_fma_f32 v[148:149], v[70:71], v[82:83], v[80:81] neg_lo:[0,0,1] neg_hi:[0,0,1]
	v_pk_add_f32 v[128:129], v[84:85], v[86:87] neg_lo:[0,1] neg_hi:[0,1]
	v_pk_fma_f32 v[132:133], v[66:67], v[82:83], v[78:79]
	v_pk_add_f32 v[100:101], v[74:75], v[88:89]
	v_mov_b32_e32 v76, v246
	v_mov_b32_e32 v77, v247

; template <int NI>
; DEV void projA_epiN(const Params& p, f32x4 (&acc)[NI][8], int seg, int cw, int trow0, int lr, int lg) {
;     ...
;     const int t = trow0 + i * 16 + lr;
;     if (seg == 0) {
;       const float2* tab = R128 + (size_t)t * 64;
; #pragma unroll
;       for (int j = 0; j < 4; j++)
; #pragma unroll
;         for (int r = 0; r < 4; r++) {
;           float2 cs = tab[j * 16 + lg * 4 + r];
;           float x1 = acc[i][j][r], x2 = acc[i][j + 4][r];
;           acc[i][j][r] = x1 * cs.x - x2 * cs.y;
;           acc[i][j + 4][r] = x2 * cs.x + x1 * cs.y;
;         }
.LBB0_333:
	v_lshlrev_b64 v[66:67], 9, v[74:75]
	v_lshl_add_u64 v[66:67], s[64:65], 0, v[66:67]
	v_mov_b32_e32 v131, v1
	v_lshl_add_u64 v[68:69], v[66:67], 0, v[130:131]
	global_load_dwordx4 v[220:223], v[68:69], off offset:16
	global_load_dwordx4 v[224:227], v[68:69], off
	global_load_dwordx4 v[228:231], v[68:69], off offset:144
	global_load_dwordx4 v[232:235], v[68:69], off offset:128
	global_load_dwordx4 v[236:239], v[68:69], off offset:272
	global_load_dwordx4 v[240:243], v[68:69], off offset:256
	global_load_dwordx4 v[244:247], v[68:69], off offset:400
	global_load_dwordx4 v[248:251], v[68:69], off offset:384
	s_waitcnt vmcnt(7)
	v_mul_f32_e32 v82, v64, v220
	s_waitcnt vmcnt(6)
	v_mov_b32_e32 v67, v226
	v_mov_b32_e32 v78, v225
	v_mul_f32_e32 v84, v60, v221
	v_mul_f32_e32 v70, v60, v220
	v_mov_b32_e32 v60, v65
	v_mov_b32_e32 v66, v224
	v_mov_b32_e32 v79, v227
	v_pk_mul_f32 v[80:81], v[62:63], v[78:79]
	v_pk_mul_f32 v[76:77], v[58:59], v[78:79]
	v_mul_f32_e32 v86, v64, v221
	v_pk_mul_f32 v[78:79], v[60:61], v[222:223]
	v_mov_b32_e32 v64, v61
	v_mov_b32_e32 v83, v78
	v_mov_b32_e32 v85, v79
	v_pk_mul_f32 v[60:61], v[64:65], v[222:223]
	v_pk_fma_f32 v[78:79], v[62:63], v[66:67], v[76:77] neg_lo:[0,0,1] neg_hi:[0,0,1]
	v_pk_add_f32 v[76:77], v[82:83], v[84:85] neg_lo:[0,1] neg_hi:[0,1]
	v_mov_b32_e32 v71, v60
	v_mov_b32_e32 v87, v61
	v_pk_fma_f32 v[82:83], v[58:59], v[66:67], v[80:81]
	v_pk_add_f32 v[80:81], v[70:71], v[86:87]
	s_waitcnt vmcnt(5)
	v_mul_f32_e32 v66, v56, v228
	s_waitcnt vmcnt(4)
	v_mov_b32_e32 v73, v234
	v_mov_b32_e32 v64, v233
	v_mul_f32_e32 v84, v52, v229
	v_mul_f32_e32 v58, v52, v228
	v_mul_f32_e32 v86, v56, v229
	v_mov_b32_e32 v52, v57
	v_mov_b32_e32 v56, v53
	v_mov_b32_e32 v72, v232
	v_mov_b32_e32 v65, v235
	v_pk_mul_f32 v[62:63], v[54:55], v[64:65]
	v_pk_mul_f32 v[64:65], v[50:51], v[64:65]
	v_pk_mul_f32 v[70:71], v[52:53], v[230:231]
	v_pk_mul_f32 v[52:53], v[56:57], v[230:231]
	v_mov_b32_e32 v67, v70
	v_mov_b32_e32 v85, v71
	v_pk_fma_f32 v[70:71], v[54:55], v[72:73], v[64:65] neg_lo:[0,0,1] neg_hi:[0,0,1]
	v_mov_b32_e32 v59, v52
	v_mov_b32_e32 v87, v53
	v_pk_fma_f32 v[92:93], v[50:51], v[72:73], v[62:63]
	v_pk_add_f32 v[72:73], v[58:59], v[86:87]
	v_pk_add_f32 v[66:67], v[66:67], v[84:85] neg_lo:[0,1] neg_hi:[0,1]
	s_waitcnt vmcnt(3)
	v_mul_f32_e32 v60, v48, v236
	s_waitcnt vmcnt(2)
	v_mov_b32_e32 v59, v242
	v_mov_b32_e32 v56, v241
	v_mul_f32_e32 v62, v44, v237
	v_mul_f32_e32 v50, v44, v236
	v_mul_f32_e32 v64, v48, v237
	v_mov_b32_e32 v44, v49
	v_mov_b32_e32 v48, v45
	v_mov_b32_e32 v58, v240
	v_mov_b32_e32 v57, v243
	v_pk_mul_f32 v[54:55], v[46:47], v[56:57]
	v_pk_mul_f32 v[56:57], v[42:43], v[56:57]
	v_pk_mul_f32 v[84:85], v[44:45], v[238:239]
	v_pk_mul_f32 v[44:45], v[48:49], v[238:239]
	v_pk_fma_f32 v[86:87], v[46:47], v[58:59], v[56:57] neg_lo:[0,0,1] neg_hi:[0,0,1]
	v_mov_b32_e32 v51, v44
	v_mov_b32_e32 v65, v45
	v_pk_fma_f32 v[90:91], v[42:43], v[58:59], v[54:55]
	v_pk_add_f32 v[88:89], v[50:51], v[64:65]
	v_mov_b32_e32 v61, v84
	v_mov_b32_e32 v63, v85
	v_pk_add_f32 v[84:85], v[60:61], v[62:63] neg_lo:[0,1] neg_hi:[0,1]
	s_waitcnt vmcnt(1)
	v_mul_f32_e32 v52, v40, v244
	v_mul_f32_e32 v54, v36, v245
	v_mul_f32_e32 v42, v36, v244
	v_mul_f32_e32 v56, v40, v245
	v_mov_b32_e32 v36, v41
	v_mov_b32_e32 v40, v37
	s_waitcnt vmcnt(0)
	v_mov_b32_e32 v51, v250
	v_mov_b32_e32 v48, v249
	v_pk_mul_f32 v[58:59], v[36:37], v[246:247]
	v_pk_mul_f32 v[36:37], v[40:41], v[246:247]
	v_mov_b32_e32 v50, v248
	v_mov_b32_e32 v49, v251
	v_pk_mul_f32 v[46:47], v[38:39], v[48:49]
	v_pk_mul_f32 v[48:49], v[34:35], v[48:49]
	v_mov_b32_e32 v53, v58
	v_mov_b32_e32 v55, v59
	v_mov_b32_e32 v43, v36
	v_mov_b32_e32 v57, v37
	v_pk_fma_f32 v[110:111], v[38:39], v[50:51], v[48:49] neg_lo:[0,0,1] neg_hi:[0,0,1]
	v_pk_add_f32 v[94:95], v[52:53], v[54:55] neg_lo:[0,1] neg_hi:[0,1]
	v_pk_fma_f32 v[96:97], v[34:35], v[50:51], v[46:47]
	v_pk_add_f32 v[68:69], v[42:43], v[56:57]
	v_mov_b32_e32 v44, v246
	v_mov_b32_e32 v45, v247

; template <int NI>
; DEV void projA_epiN(const Params& p, f32x4 (&acc)[NI][8], int seg, int cw, int trow0, int lr, int lg) {
;     ...
;     const int t = trow0 + i * 16 + lr;
;     if (seg == 0) {
;       const float2* tab = R128 + (size_t)t * 64;
; #pragma unroll
;       for (int j = 0; j < 4; j++)
; #pragma unroll
;         for (int r = 0; r < 4; r++) {
;           float2 cs = tab[j * 16 + lg * 4 + r];
;           float x1 = acc[i][j][r], x2 = acc[i][j + 4][r];
;           acc[i][j][r] = x1 * cs.x - x2 * cs.y;
;           acc[i][j + 4][r] = x2 * cs.x + x1 * cs.y;
;         }
.LBB0_342:
	v_lshlrev_b64 v[34:35], 9, v[44:45]
	v_lshl_add_u64 v[34:35], s[64:65], 0, v[34:35]
	v_mov_b32_e32 v67, v1
	v_lshl_add_u64 v[36:37], v[34:35], 0, v[66:67]
	global_load_dwordx4 v[220:223], v[36:37], off offset:16
	global_load_dwordx4 v[224:227], v[36:37], off
	global_load_dwordx4 v[228:231], v[36:37], off offset:144
	global_load_dwordx4 v[232:235], v[36:37], off offset:128
	global_load_dwordx4 v[236:239], v[36:37], off offset:272
	global_load_dwordx4 v[240:243], v[36:37], off offset:256
	global_load_dwordx4 v[244:247], v[36:37], off offset:400
	global_load_dwordx4 v[248:251], v[36:37], off offset:384
	s_waitcnt vmcnt(7)
	v_mul_f32_e32 v52, v32, v220
	s_waitcnt vmcnt(6)
	v_mov_b32_e32 v35, v226
	v_mov_b32_e32 v48, v225
	v_mul_f32_e32 v54, v28, v221
	v_mul_f32_e32 v38, v28, v220
	v_mov_b32_e32 v28, v33
	v_mov_b32_e32 v34, v224
	v_mov_b32_e32 v49, v227
	v_pk_mul_f32 v[50:51], v[30:31], v[48:49]
	v_pk_mul_f32 v[46:47], v[26:27], v[48:49]
	v_mul_f32_e32 v56, v32, v221
	v_pk_mul_f32 v[48:49], v[28:29], v[222:223]
	v_mov_b32_e32 v32, v29
	v_mov_b32_e32 v53, v48
	v_mov_b32_e32 v55, v49
	v_pk_mul_f32 v[28:29], v[32:33], v[222:223]
	v_pk_fma_f32 v[48:49], v[30:31], v[34:35], v[46:47] neg_lo:[0,0,1] neg_hi:[0,0,1]
	v_pk_add_f32 v[46:47], v[52:53], v[54:55] neg_lo:[0,1] neg_hi:[0,1]
	v_mov_b32_e32 v39, v28
	v_mov_b32_e32 v57, v29
	v_pk_fma_f32 v[52:53], v[26:27], v[34:35], v[50:51]
	v_pk_add_f32 v[50:51], v[38:39], v[56:57]
	s_waitcnt vmcnt(5)
	v_mul_f32_e32 v34, v24, v228
	s_waitcnt vmcnt(4)
	v_mov_b32_e32 v41, v234
	v_mov_b32_e32 v32, v233
	v_mul_f32_e32 v54, v16, v229
	v_mul_f32_e32 v26, v16, v228
	v_mul_f32_e32 v56, v24, v229
	v_mov_b32_e32 v16, v25
	v_mov_b32_e32 v24, v17
	v_mov_b32_e32 v40, v232
	v_mov_b32_e32 v33, v235
	v_pk_mul_f32 v[30:31], v[22:23], v[32:33]
	v_pk_mul_f32 v[32:33], v[14:15], v[32:33]
	v_pk_mul_f32 v[38:39], v[16:17], v[230:231]
	v_pk_mul_f32 v[16:17], v[24:25], v[230:231]
	v_mov_b32_e32 v35, v38
	v_mov_b32_e32 v55, v39
	v_pk_fma_f32 v[38:39], v[22:23], v[40:41], v[32:33] neg_lo:[0,0,1] neg_hi:[0,0,1]
	v_mov_b32_e32 v27, v16
	v_mov_b32_e32 v57, v17
	v_pk_fma_f32 v[62:63], v[14:15], v[40:41], v[30:31]
	v_pk_add_f32 v[34:35], v[34:35], v[54:55] neg_lo:[0,1] neg_hi:[0,1]
	v_pk_add_f32 v[40:41], v[26:27], v[56:57]
	s_waitcnt vmcnt(3)
	v_mul_f32_e32 v28, v20, v236
	v_mul_f32_e32 v30, v12, v237
	v_mul_f32_e32 v14, v12, v236
	v_mul_f32_e32 v32, v20, v237
	v_mov_b32_e32 v12, v21
	v_mov_b32_e32 v20, v13
	s_waitcnt vmcnt(2)
	v_mov_b32_e32 v27, v242
	v_mov_b32_e32 v24, v241
	v_pk_mul_f32 v[54:55], v[12:13], v[238:239]
	v_pk_mul_f32 v[12:13], v[20:21], v[238:239]
	v_mov_b32_e32 v26, v240
	v_mov_b32_e32 v25, v243
	v_pk_mul_f32 v[22:23], v[18:19], v[24:25]
	v_mov_b32_e32 v15, v12
	v_mov_b32_e32 v33, v13
	v_pk_mul_f32 v[24:25], v[10:11], v[24:25]
	v_pk_fma_f32 v[60:61], v[10:11], v[26:27], v[22:23]
	v_pk_add_f32 v[58:59], v[14:15], v[32:33]
	v_pk_fma_f32 v[56:57], v[18:19], v[26:27], v[24:25] neg_lo:[0,0,1] neg_hi:[0,0,1]
	v_mov_b32_e32 v29, v54
	v_mov_b32_e32 v31, v55
	v_pk_add_f32 v[54:55], v[28:29], v[30:31] neg_lo:[0,1] neg_hi:[0,1]
	s_waitcnt vmcnt(1)
	v_mul_f32_e32 v20, v8, v244
	v_mul_f32_e32 v22, v4, v245
	v_mul_f32_e32 v10, v4, v244
	v_mul_f32_e32 v24, v8, v245
	v_mov_b32_e32 v4, v9
	v_mov_b32_e32 v8, v5
	s_waitcnt vmcnt(0)
	v_mov_b32_e32 v19, v250
	v_mov_b32_e32 v16, v249
	v_pk_mul_f32 v[26:27], v[4:5], v[246:247]
	v_pk_mul_f32 v[4:5], v[8:9], v[246:247]
	v_mov_b32_e32 v18, v248
	v_mov_b32_e32 v17, v251
	v_pk_mul_f32 v[14:15], v[6:7], v[16:17]
	v_pk_mul_f32 v[16:17], v[2:3], v[16:17]
	v_mov_b32_e32 v21, v26
	v_mov_b32_e32 v23, v27
	v_mov_b32_e32 v11, v4
	v_mov_b32_e32 v25, v5
	v_pk_fma_f32 v[82:83], v[6:7], v[18:19], v[16:17] neg_lo:[0,0,1] neg_hi:[0,0,1]
	v_pk_add_f32 v[64:65], v[20:21], v[22:23] neg_lo:[0,1] neg_hi:[0,1]
	v_pk_fma_f32 v[68:69], v[2:3], v[18:19], v[14:15]
	v_pk_add_f32 v[36:37], v[10:11], v[24:25]
	v_mov_b32_e32 v12, v246
	v_mov_b32_e32 v13, v247

; template <int NI>
; DEV void projA_epiN(const Params& p, f32x4 (&acc)[NI][8], int seg, int cw, int trow0, int lr, int lg) {
;     ...
;     const int t = trow0 + i * 16 + lr;
;     if (seg == 0) {
;       const float2* tab = R128 + (size_t)t * 64;
; #pragma unroll
;       for (int j = 0; j < 4; j++)
; #pragma unroll
;         for (int r = 0; r < 4; r++) {
;           float2 cs = tab[j * 16 + lg * 4 + r];
;           float x1 = acc[i][j][r], x2 = acc[i][j + 4][r];
;           acc[i][j][r] = x1 * cs.x - x2 * cs.y;
;           acc[i][j + 4][r] = x2 * cs.x + x1 * cs.y;
;         }
.LBB0_471:
	v_lshlrev_b64 v[68:69], 9, v[76:77]
	v_lshl_add_u64 v[68:69], s[64:65], 0, v[68:69]
	v_mov_b32_e32 v67, v1
	v_lshl_add_u64 v[68:69], v[68:69], 0, v[66:67]
	global_load_dwordx4 v[220:223], v[68:69], off offset:16
	global_load_dwordx4 v[224:227], v[68:69], off
	global_load_dwordx4 v[228:231], v[68:69], off offset:144
	global_load_dwordx4 v[232:235], v[68:69], off offset:128
	global_load_dwordx4 v[236:239], v[68:69], off offset:272
	global_load_dwordx4 v[240:243], v[68:69], off offset:256
	global_load_dwordx4 v[244:247], v[68:69], off offset:400
	global_load_dwordx4 v[248:251], v[68:69], off offset:384
	s_waitcnt vmcnt(7)
	v_mul_f32_e32 v86, v64, v220
	s_waitcnt vmcnt(6)
	v_mov_b32_e32 v83, v226
	v_mov_b32_e32 v80, v225
	v_mul_f32_e32 v88, v60, v221
	v_mul_f32_e32 v70, v60, v220
	v_mul_f32_e32 v90, v64, v221
	v_mov_b32_e32 v60, v65
	v_mov_b32_e32 v64, v61
	v_mov_b32_e32 v82, v224
	v_mov_b32_e32 v81, v227
	v_pk_mul_f32 v[84:85], v[62:63], v[80:81]
	v_pk_mul_f32 v[78:79], v[58:59], v[80:81]
	v_pk_mul_f32 v[80:81], v[60:61], v[222:223]
	v_pk_mul_f32 v[60:61], v[64:65], v[222:223]
	v_mov_b32_e32 v87, v80
	v_mov_b32_e32 v89, v81
	v_pk_fma_f32 v[80:81], v[62:63], v[82:83], v[78:79] neg_lo:[0,0,1] neg_hi:[0,0,1]
	v_mov_b32_e32 v71, v60
	v_mov_b32_e32 v91, v61
	v_pk_fma_f32 v[84:85], v[58:59], v[82:83], v[84:85]
	v_pk_add_f32 v[78:79], v[86:87], v[88:89] neg_lo:[0,1] neg_hi:[0,1]
	v_pk_add_f32 v[82:83], v[70:71], v[90:91]
	s_waitcnt vmcnt(5)
	v_mul_f32_e32 v70, v56, v228
	s_waitcnt vmcnt(4)
	v_mov_b32_e32 v87, v234
	v_mov_b32_e32 v64, v233
	v_mul_f32_e32 v88, v52, v229
	v_mul_f32_e32 v58, v52, v228
	v_mul_f32_e32 v90, v56, v229
	v_mov_b32_e32 v52, v57
	v_mov_b32_e32 v56, v53
	v_mov_b32_e32 v86, v232
	v_mov_b32_e32 v65, v235
	v_pk_mul_f32 v[62:63], v[54:55], v[64:65]
	v_pk_mul_f32 v[64:65], v[50:51], v[64:65]
	v_pk_mul_f32 v[72:73], v[52:53], v[230:231]
	v_pk_mul_f32 v[52:53], v[56:57], v[230:231]
	v_mov_b32_e32 v71, v72
	v_mov_b32_e32 v89, v73
	v_pk_fma_f32 v[72:73], v[54:55], v[86:87], v[64:65] neg_lo:[0,0,1] neg_hi:[0,0,1]
	v_mov_b32_e32 v59, v52
	v_mov_b32_e32 v91, v53
	v_pk_fma_f32 v[96:97], v[50:51], v[86:87], v[62:63]
	v_pk_add_f32 v[94:95], v[58:59], v[90:91]
	v_pk_add_f32 v[70:71], v[70:71], v[88:89] neg_lo:[0,1] neg_hi:[0,1]
	s_waitcnt vmcnt(3)
	v_mul_f32_e32 v60, v48, v236
	s_waitcnt vmcnt(2)
	v_mov_b32_e32 v59, v242
	v_mov_b32_e32 v56, v241
	v_mul_f32_e32 v62, v44, v237
	v_mul_f32_e32 v50, v44, v236
	v_mul_f32_e32 v64, v48, v237
	v_mov_b32_e32 v44, v49
	v_mov_b32_e32 v48, v45
	v_mov_b32_e32 v58, v240
	v_mov_b32_e32 v57, v243
	v_pk_mul_f32 v[54:55], v[46:47], v[56:57]
	v_pk_mul_f32 v[56:57], v[42:43], v[56:57]
	v_pk_mul_f32 v[86:87], v[44:45], v[238:239]
	v_pk_mul_f32 v[44:45], v[48:49], v[238:239]
	v_pk_fma_f32 v[88:89], v[46:47], v[58:59], v[56:57] neg_lo:[0,0,1] neg_hi:[0,0,1]
	v_mov_b32_e32 v51, v44
	v_mov_b32_e32 v65, v45
	v_pk_fma_f32 v[92:93], v[42:43], v[58:59], v[54:55]
	v_pk_add_f32 v[90:91], v[50:51], v[64:65]
	v_mov_b32_e32 v61, v86
	v_mov_b32_e32 v63, v87
	v_pk_add_f32 v[86:87], v[60:61], v[62:63] neg_lo:[0,1] neg_hi:[0,1]
	s_waitcnt vmcnt(1)
	v_mul_f32_e32 v52, v40, v244
	v_mul_f32_e32 v54, v36, v245
	v_mul_f32_e32 v42, v36, v244
	v_mul_f32_e32 v56, v40, v245
	v_mov_b32_e32 v36, v41
	v_mov_b32_e32 v40, v37
	s_waitcnt vmcnt(0)
	v_mov_b32_e32 v51, v250
	v_mov_b32_e32 v48, v249
	v_pk_mul_f32 v[58:59], v[36:37], v[246:247]
	v_pk_mul_f32 v[36:37], v[40:41], v[246:247]
	v_mov_b32_e32 v50, v248
	v_mov_b32_e32 v49, v251
	v_pk_mul_f32 v[46:47], v[38:39], v[48:49]
	v_pk_mul_f32 v[48:49], v[34:35], v[48:49]
	v_mov_b32_e32 v53, v58
	v_mov_b32_e32 v55, v59
	v_mov_b32_e32 v43, v36
	v_mov_b32_e32 v57, v37
	v_pk_fma_f32 v[104:105], v[38:39], v[50:51], v[48:49] neg_lo:[0,0,1] neg_hi:[0,0,1]
	v_pk_add_f32 v[100:101], v[52:53], v[54:55] neg_lo:[0,1] neg_hi:[0,1]
	v_pk_fma_f32 v[98:99], v[34:35], v[50:51], v[46:47]
	v_pk_add_f32 v[68:69], v[42:43], v[56:57]
	v_mov_b32_e32 v44, v246
	v_mov_b32_e32 v45, v247

; DEV float bf2f(bf16_t h) { return __uint_as_float(((unsigned)h) << 16); }
; DEV float silu_f(float x) { return x / (1.f + __expf(-x)); }
; DEV void phase_G(const Params& p, int b, unsigned char* ldsraw) {
;     ...
;     for (int i = 0; i < 4; i++) {
;       const int t = mt * 256 + wm * 64 + i * 16 + lr;
;       if (t < LT) {
; #pragma unroll
;         for (int j = 0; j < 8; j++) {
;           bf16_t* d = dst + (size_t)t * ld + cb + wn * 128 + j * 16 + lg * 4;
;           f32x4 v;
;           if (gate) {
;             uint2 ov = *(const uint2*)d;
;             v[0] = bf2f((bf16_t)(ov.x & 0xffff)) * silu_f(acc[i][j][0]);
;             v[1] = bf2f((bf16_t)(ov.x >> 16)) * silu_f(acc[i][j][1]);
;             v[2] = bf2f((bf16_t)(ov.y & 0xffff)) * silu_f(acc[i][j][2]);
;             v[3] = bf2f((bf16_t)(ov.y >> 16)) * silu_f(acc[i][j][3]);
.LBB0_789:
	v_ashrrev_i32_e32 v0, 31, v142
	v_mul_lo_u32 v143, s1, v142
	v_mul_lo_u32 v0, s0, v0
	v_mad_u64_u32 v[136:137], s[8:9], s0, v142, 0
	v_add3_u32 v137, v137, v0, v143
	s_andn2_b64 vcc, exec, s[2:3]
	v_lshl_add_u64 v[136:137], v[136:137], 1, v[134:135]
	s_cbranch_vccnz .Lgskip_0
	global_load_dwordx2 v[220:221], v[136:137], off
	global_load_dwordx2 v[222:223], v[136:137], off offset:32
	global_load_dwordx2 v[224:225], v[136:137], off offset:64
	global_load_dwordx2 v[226:227], v[136:137], off offset:96
	global_load_dwordx2 v[228:229], v[136:137], off offset:128
	global_load_dwordx2 v[230:231], v[136:137], off offset:160
	global_load_dwordx2 v[232:233], v[136:137], off offset:192
	global_load_dwordx2 v[234:235], v[136:137], off offset:224
.Lgskip_0:
	s_cbranch_vccnz .LBB0_791
	v_pk_add_f32 v[140:141], v[140:141], 1.0 op_sel_hi:[1,0]
	v_pk_add_f32 v[138:139], v[138:139], 1.0 op_sel_hi:[1,0]
	v_div_scale_f32 v0, s[2:3], v141, v141, v127
	v_rcp_f32_e32 v143, v0
	s_waitcnt vmcnt(7)
	v_lshlrev_b32_e32 v130, 16, v220
	v_fma_f32 v144, -v0, v143, 1.0
	v_fmac_f32_e32 v143, v144, v143
	v_div_scale_f32 v144, vcc, v127, v141, v127
	v_mul_f32_e32 v145, v144, v143
	v_fma_f32 v146, -v0, v145, v144
	v_fmac_f32_e32 v145, v146, v143
	v_fma_f32 v0, -v0, v145, v144
	v_div_fmas_f32 v0, v0, v143, v145
	v_div_fixup_f32 v127, v0, v141, v127
	v_div_scale_f32 v0, s[2:3], v140, v140, v126
	v_rcp_f32_e32 v141, v0
	v_and_b32_e32 v131, 0xffff0000, v220
	v_lshlrev_b32_e32 v132, 16, v221
	v_and_b32_e32 v133, 0xffff0000, v221
	v_fma_f32 v143, -v0, v141, 1.0
	v_fmac_f32_e32 v141, v143, v141
	v_div_scale_f32 v143, vcc, v126, v140, v126
	v_mul_f32_e32 v144, v143, v141
	v_fma_f32 v145, -v0, v144, v143
	v_fmac_f32_e32 v144, v145, v141
	v_fma_f32 v0, -v0, v144, v143
	v_div_fmas_f32 v0, v0, v141, v144
	v_div_fixup_f32 v126, v0, v140, v126
	v_div_scale_f32 v0, s[2:3], v139, v139, v129
	v_rcp_f32_e32 v140, v0
	v_pk_mul_f32 v[130:131], v[126:127], v[130:131]
	v_fma_f32 v141, -v0, v140, 1.0
	v_fmac_f32_e32 v140, v141, v140
	v_div_scale_f32 v141, vcc, v129, v139, v129
	v_mul_f32_e32 v143, v141, v140
	v_fma_f32 v144, -v0, v143, v141
	v_fmac_f32_e32 v143, v144, v140
	v_fma_f32 v0, -v0, v143, v141
	v_div_fmas_f32 v0, v0, v140, v143
	v_div_fixup_f32 v129, v0, v139, v129
	v_div_scale_f32 v0, s[2:3], v138, v138, v128
	v_rcp_f32_e32 v139, v0
	s_nop 0
	v_fma_f32 v140, -v0, v139, 1.0
	v_fmac_f32_e32 v139, v140, v139
	v_div_scale_f32 v140, vcc, v128, v138, v128
	v_mul_f32_e32 v141, v140, v139
	v_fma_f32 v143, -v0, v141, v140
	v_fmac_f32_e32 v141, v143, v139
	v_fma_f32 v0, -v0, v141, v140
	v_div_fmas_f32 v0, v0, v139, v141
	v_div_fixup_f32 v128, v0, v138, v128
	v_pk_mul_f32 v[132:133], v[128:129], v[132:133]

; DEV float bf2f(bf16_t h) { return __uint_as_float(((unsigned)h) << 16); }
; DEV float silu_f(float x) { return x / (1.f + __expf(-x)); }
; DEV void phase_G(const Params& p, int b, unsigned char* ldsraw) {
;     ...
;           if (gate) {
;             uint2 ov = *(const uint2*)d;
;             v[0] = bf2f((bf16_t)(ov.x & 0xffff)) * silu_f(acc[i][j][0]);
;             v[1] = bf2f((bf16_t)(ov.x >> 16)) * silu_f(acc[i][j][1]);
;             v[2] = bf2f((bf16_t)(ov.y & 0xffff)) * silu_f(acc[i][j][2]);
;             v[3] = bf2f((bf16_t)(ov.y >> 16)) * silu_f(acc[i][j][3]);
.LBB0_793:
	s_andn2_b64 vcc, exec, s[2:3]
	s_cbranch_vccnz .LBB0_795
	v_pk_add_f32 v[132:133], v[132:133], 1.0 op_sel_hi:[1,0]
	v_pk_add_f32 v[130:131], v[130:131], 1.0 op_sel_hi:[1,0]
	v_div_scale_f32 v0, s[2:3], v133, v133, v123
	v_rcp_f32_e32 v138, v0
	s_waitcnt vmcnt(7)
	v_lshlrev_b32_e32 v126, 16, v222
	v_fma_f32 v139, -v0, v138, 1.0
	v_fmac_f32_e32 v138, v139, v138
	v_div_scale_f32 v139, vcc, v123, v133, v123
	v_mul_f32_e32 v140, v139, v138
	v_fma_f32 v141, -v0, v140, v139
	v_fmac_f32_e32 v140, v141, v138
	v_fma_f32 v0, -v0, v140, v139
	v_div_fmas_f32 v0, v0, v138, v140
	v_div_fixup_f32 v123, v0, v133, v123
	v_div_scale_f32 v0, s[2:3], v132, v132, v122
	v_rcp_f32_e32 v133, v0
	v_and_b32_e32 v127, 0xffff0000, v222
	v_lshlrev_b32_e32 v128, 16, v223
	v_and_b32_e32 v129, 0xffff0000, v223
	v_fma_f32 v138, -v0, v133, 1.0
	v_fmac_f32_e32 v133, v138, v133
	v_div_scale_f32 v138, vcc, v122, v132, v122
	v_mul_f32_e32 v139, v138, v133
	v_fma_f32 v140, -v0, v139, v138
	v_fmac_f32_e32 v139, v140, v133
	v_fma_f32 v0, -v0, v139, v138
	v_div_fmas_f32 v0, v0, v133, v139
	v_div_fixup_f32 v122, v0, v132, v122
	v_div_scale_f32 v0, s[2:3], v131, v131, v125
	v_rcp_f32_e32 v132, v0
	v_pk_mul_f32 v[126:127], v[122:123], v[126:127]
	v_fma_f32 v133, -v0, v132, 1.0
	v_fmac_f32_e32 v132, v133, v132
	v_div_scale_f32 v133, vcc, v125, v131, v125
	v_mul_f32_e32 v138, v133, v132
	v_fma_f32 v139, -v0, v138, v133
	v_fmac_f32_e32 v138, v139, v132
	v_fma_f32 v0, -v0, v138, v133
	v_div_fmas_f32 v0, v0, v132, v138
	v_div_fixup_f32 v125, v0, v131, v125
	v_div_scale_f32 v0, s[2:3], v130, v130, v124
	v_rcp_f32_e32 v131, v0
	s_nop 0
	v_fma_f32 v132, -v0, v131, 1.0
	v_fmac_f32_e32 v131, v132, v131
	v_div_scale_f32 v132, vcc, v124, v130, v124
	v_mul_f32_e32 v133, v132, v131
	v_fma_f32 v138, -v0, v133, v132
	v_fmac_f32_e32 v133, v138, v131
	v_fma_f32 v0, -v0, v133, v132
	v_div_fmas_f32 v0, v0, v131, v133
	v_div_fixup_f32 v124, v0, v130, v124
	v_pk_mul_f32 v[128:129], v[124:125], v[128:129]

; DEV float bf2f(bf16_t h) { return __uint_as_float(((unsigned)h) << 16); }
; DEV float silu_f(float x) { return x / (1.f + __expf(-x)); }
; DEV void phase_G(const Params& p, int b, unsigned char* ldsraw) {
;     ...
;           if (gate) {
;             uint2 ov = *(const uint2*)d;
;             v[0] = bf2f((bf16_t)(ov.x & 0xffff)) * silu_f(acc[i][j][0]);
;             v[1] = bf2f((bf16_t)(ov.x >> 16)) * silu_f(acc[i][j][1]);
;             v[2] = bf2f((bf16_t)(ov.y & 0xffff)) * silu_f(acc[i][j][2]);
;             v[3] = bf2f((bf16_t)(ov.y >> 16)) * silu_f(acc[i][j][3]);
.LBB0_797:
	s_andn2_b64 vcc, exec, s[2:3]
	s_cbranch_vccnz .LBB0_799
	v_pk_add_f32 v[128:129], v[128:129], 1.0 op_sel_hi:[1,0]
	v_pk_add_f32 v[126:127], v[126:127], 1.0 op_sel_hi:[1,0]
	v_div_scale_f32 v0, s[2:3], v129, v129, v119
	v_rcp_f32_e32 v130, v0
	s_waitcnt vmcnt(7)
	v_lshlrev_b32_e32 v122, 16, v224
	v_fma_f32 v131, -v0, v130, 1.0
	v_fmac_f32_e32 v130, v131, v130
	v_div_scale_f32 v131, vcc, v119, v129, v119
	v_mul_f32_e32 v132, v131, v130
	v_fma_f32 v133, -v0, v132, v131
	v_fmac_f32_e32 v132, v133, v130
	v_fma_f32 v0, -v0, v132, v131
	v_div_fmas_f32 v0, v0, v130, v132
	v_div_fixup_f32 v119, v0, v129, v119
	v_div_scale_f32 v0, s[2:3], v128, v128, v118
	v_rcp_f32_e32 v129, v0
	v_and_b32_e32 v123, 0xffff0000, v224
	v_lshlrev_b32_e32 v124, 16, v225
	v_and_b32_e32 v125, 0xffff0000, v225
	v_fma_f32 v130, -v0, v129, 1.0
	v_fmac_f32_e32 v129, v130, v129
	v_div_scale_f32 v130, vcc, v118, v128, v118
	v_mul_f32_e32 v131, v130, v129
	v_fma_f32 v132, -v0, v131, v130
	v_fmac_f32_e32 v131, v132, v129
	v_fma_f32 v0, -v0, v131, v130
	v_div_fmas_f32 v0, v0, v129, v131
	v_div_fixup_f32 v118, v0, v128, v118
	v_div_scale_f32 v0, s[2:3], v127, v127, v121
	v_rcp_f32_e32 v128, v0
	v_pk_mul_f32 v[122:123], v[118:119], v[122:123]
	v_fma_f32 v129, -v0, v128, 1.0
	v_fmac_f32_e32 v128, v129, v128
	v_div_scale_f32 v129, vcc, v121, v127, v121
	v_mul_f32_e32 v130, v129, v128
	v_fma_f32 v131, -v0, v130, v129
	v_fmac_f32_e32 v130, v131, v128
	v_fma_f32 v0, -v0, v130, v129
	v_div_fmas_f32 v0, v0, v128, v130
	v_div_fixup_f32 v121, v0, v127, v121
	v_div_scale_f32 v0, s[2:3], v126, v126, v120
	v_rcp_f32_e32 v127, v0
	s_nop 0
	v_fma_f32 v128, -v0, v127, 1.0
	v_fmac_f32_e32 v127, v128, v127
	v_div_scale_f32 v128, vcc, v120, v126, v120
	v_mul_f32_e32 v129, v128, v127
	v_fma_f32 v130, -v0, v129, v128
	v_fmac_f32_e32 v129, v130, v127
	v_fma_f32 v0, -v0, v129, v128
	v_div_fmas_f32 v0, v0, v127, v129
	v_div_fixup_f32 v120, v0, v126, v120
	v_pk_mul_f32 v[124:125], v[120:121], v[124:125]

; DEV float bf2f(bf16_t h) { return __uint_as_float(((unsigned)h) << 16); }
; DEV float silu_f(float x) { return x / (1.f + __expf(-x)); }
; DEV void phase_G(const Params& p, int b, unsigned char* ldsraw) {
;     ...
;           if (gate) {
;             uint2 ov = *(const uint2*)d;
;             v[0] = bf2f((bf16_t)(ov.x & 0xffff)) * silu_f(acc[i][j][0]);
;             v[1] = bf2f((bf16_t)(ov.x >> 16)) * silu_f(acc[i][j][1]);
;             v[2] = bf2f((bf16_t)(ov.y & 0xffff)) * silu_f(acc[i][j][2]);
;             v[3] = bf2f((bf16_t)(ov.y >> 16)) * silu_f(acc[i][j][3]);
.LBB0_801:
	s_andn2_b64 vcc, exec, s[2:3]
	s_cbranch_vccnz .LBB0_803
	v_pk_add_f32 v[124:125], v[124:125], 1.0 op_sel_hi:[1,0]
	v_pk_add_f32 v[122:123], v[122:123], 1.0 op_sel_hi:[1,0]
	v_div_scale_f32 v0, s[2:3], v125, v125, v115
	v_rcp_f32_e32 v126, v0
	s_waitcnt vmcnt(7)
	v_lshlrev_b32_e32 v118, 16, v226
	v_fma_f32 v127, -v0, v126, 1.0
	v_fmac_f32_e32 v126, v127, v126
	v_div_scale_f32 v127, vcc, v115, v125, v115
	v_mul_f32_e32 v128, v127, v126
	v_fma_f32 v129, -v0, v128, v127
	v_fmac_f32_e32 v128, v129, v126
	v_fma_f32 v0, -v0, v128, v127
	v_div_fmas_f32 v0, v0, v126, v128
	v_div_fixup_f32 v115, v0, v125, v115
	v_div_scale_f32 v0, s[2:3], v124, v124, v114
	v_rcp_f32_e32 v125, v0
	v_and_b32_e32 v119, 0xffff0000, v226
	v_lshlrev_b32_e32 v120, 16, v227
	v_and_b32_e32 v121, 0xffff0000, v227
	v_fma_f32 v126, -v0, v125, 1.0
	v_fmac_f32_e32 v125, v126, v125
	v_div_scale_f32 v126, vcc, v114, v124, v114
	v_mul_f32_e32 v127, v126, v125
	v_fma_f32 v128, -v0, v127, v126
	v_fmac_f32_e32 v127, v128, v125
	v_fma_f32 v0, -v0, v127, v126
	v_div_fmas_f32 v0, v0, v125, v127
	v_div_fixup_f32 v114, v0, v124, v114
	v_div_scale_f32 v0, s[2:3], v123, v123, v117
	v_rcp_f32_e32 v124, v0
	v_pk_mul_f32 v[118:119], v[114:115], v[118:119]
	v_fma_f32 v125, -v0, v124, 1.0
	v_fmac_f32_e32 v124, v125, v124
	v_div_scale_f32 v125, vcc, v117, v123, v117
	v_mul_f32_e32 v126, v125, v124
	v_fma_f32 v127, -v0, v126, v125
	v_fmac_f32_e32 v126, v127, v124
	v_fma_f32 v0, -v0, v126, v125
	v_div_fmas_f32 v0, v0, v124, v126
	v_div_fixup_f32 v117, v0, v123, v117
	v_div_scale_f32 v0, s[2:3], v122, v122, v116
	v_rcp_f32_e32 v123, v0
	s_nop 0
	v_fma_f32 v124, -v0, v123, 1.0
	v_fmac_f32_e32 v123, v124, v123
	v_div_scale_f32 v124, vcc, v116, v122, v116
	v_mul_f32_e32 v125, v124, v123
	v_fma_f32 v126, -v0, v125, v124
	v_fmac_f32_e32 v125, v126, v123
	v_fma_f32 v0, -v0, v125, v124
	v_div_fmas_f32 v0, v0, v123, v125
	v_div_fixup_f32 v116, v0, v122, v116
	v_pk_mul_f32 v[120:121], v[116:117], v[120:121]

; DEV float bf2f(bf16_t h) { return __uint_as_float(((unsigned)h) << 16); }
; DEV float silu_f(float x) { return x / (1.f + __expf(-x)); }
; DEV void phase_G(const Params& p, int b, unsigned char* ldsraw) {
;     ...
;           if (gate) {
;             uint2 ov = *(const uint2*)d;
;             v[0] = bf2f((bf16_t)(ov.x & 0xffff)) * silu_f(acc[i][j][0]);
;             v[1] = bf2f((bf16_t)(ov.x >> 16)) * silu_f(acc[i][j][1]);
;             v[2] = bf2f((bf16_t)(ov.y & 0xffff)) * silu_f(acc[i][j][2]);
;             v[3] = bf2f((bf16_t)(ov.y >> 16)) * silu_f(acc[i][j][3]);
.LBB0_805:
	s_andn2_b64 vcc, exec, s[2:3]
	s_cbranch_vccnz .LBB0_807
	v_pk_add_f32 v[120:121], v[120:121], 1.0 op_sel_hi:[1,0]
	v_pk_add_f32 v[118:119], v[118:119], 1.0 op_sel_hi:[1,0]
	v_div_scale_f32 v0, s[2:3], v121, v121, v111
	v_rcp_f32_e32 v122, v0
	s_waitcnt vmcnt(7)
	v_lshlrev_b32_e32 v114, 16, v228
	v_fma_f32 v123, -v0, v122, 1.0
	v_fmac_f32_e32 v122, v123, v122
	v_div_scale_f32 v123, vcc, v111, v121, v111
	v_mul_f32_e32 v124, v123, v122
	v_fma_f32 v125, -v0, v124, v123
	v_fmac_f32_e32 v124, v125, v122
	v_fma_f32 v0, -v0, v124, v123
	v_div_fmas_f32 v0, v0, v122, v124
	v_div_fixup_f32 v111, v0, v121, v111
	v_div_scale_f32 v0, s[2:3], v120, v120, v110
	v_rcp_f32_e32 v121, v0
	v_and_b32_e32 v115, 0xffff0000, v228
	v_lshlrev_b32_e32 v116, 16, v229
	v_and_b32_e32 v117, 0xffff0000, v229
	v_fma_f32 v122, -v0, v121, 1.0
	v_fmac_f32_e32 v121, v122, v121
	v_div_scale_f32 v122, vcc, v110, v120, v110
	v_mul_f32_e32 v123, v122, v121
	v_fma_f32 v124, -v0, v123, v122
	v_fmac_f32_e32 v123, v124, v121
	v_fma_f32 v0, -v0, v123, v122
	v_div_fmas_f32 v0, v0, v121, v123
	v_div_fixup_f32 v110, v0, v120, v110
	v_div_scale_f32 v0, s[2:3], v119, v119, v113
	v_rcp_f32_e32 v120, v0
	v_pk_mul_f32 v[114:115], v[110:111], v[114:115]
	v_fma_f32 v121, -v0, v120, 1.0
	v_fmac_f32_e32 v120, v121, v120
	v_div_scale_f32 v121, vcc, v113, v119, v113
	v_mul_f32_e32 v122, v121, v120
	v_fma_f32 v123, -v0, v122, v121
	v_fmac_f32_e32 v122, v123, v120
	v_fma_f32 v0, -v0, v122, v121
	v_div_fmas_f32 v0, v0, v120, v122
	v_div_fixup_f32 v113, v0, v119, v113
	v_div_scale_f32 v0, s[2:3], v118, v118, v112
	v_rcp_f32_e32 v119, v0
	s_nop 0
	v_fma_f32 v120, -v0, v119, 1.0
	v_fmac_f32_e32 v119, v120, v119
	v_div_scale_f32 v120, vcc, v112, v118, v112
	v_mul_f32_e32 v121, v120, v119
	v_fma_f32 v122, -v0, v121, v120
	v_fmac_f32_e32 v121, v122, v119
	v_fma_f32 v0, -v0, v121, v120
	v_div_fmas_f32 v0, v0, v119, v121
	v_div_fixup_f32 v112, v0, v118, v112
	v_pk_mul_f32 v[116:117], v[112:113], v[116:117]

; DEV float bf2f(bf16_t h) { return __uint_as_float(((unsigned)h) << 16); }
; DEV float silu_f(float x) { return x / (1.f + __expf(-x)); }
; DEV void phase_G(const Params& p, int b, unsigned char* ldsraw) {
;     ...
;           if (gate) {
;             uint2 ov = *(const uint2*)d;
;             v[0] = bf2f((bf16_t)(ov.x & 0xffff)) * silu_f(acc[i][j][0]);
;             v[1] = bf2f((bf16_t)(ov.x >> 16)) * silu_f(acc[i][j][1]);
;             v[2] = bf2f((bf16_t)(ov.y & 0xffff)) * silu_f(acc[i][j][2]);
;             v[3] = bf2f((bf16_t)(ov.y >> 16)) * silu_f(acc[i][j][3]);
.LBB0_809:
	s_andn2_b64 vcc, exec, s[2:3]
	s_cbranch_vccnz .LBB0_811
	v_pk_add_f32 v[116:117], v[116:117], 1.0 op_sel_hi:[1,0]
	v_pk_add_f32 v[114:115], v[114:115], 1.0 op_sel_hi:[1,0]
	v_div_scale_f32 v0, s[2:3], v117, v117, v107
	v_rcp_f32_e32 v118, v0
	s_waitcnt vmcnt(7)
	v_lshlrev_b32_e32 v110, 16, v230
	v_fma_f32 v119, -v0, v118, 1.0
	v_fmac_f32_e32 v118, v119, v118
	v_div_scale_f32 v119, vcc, v107, v117, v107
	v_mul_f32_e32 v120, v119, v118
	v_fma_f32 v121, -v0, v120, v119
	v_fmac_f32_e32 v120, v121, v118
	v_fma_f32 v0, -v0, v120, v119
	v_div_fmas_f32 v0, v0, v118, v120
	v_div_fixup_f32 v107, v0, v117, v107
	v_div_scale_f32 v0, s[2:3], v116, v116, v106
	v_rcp_f32_e32 v117, v0
	v_and_b32_e32 v111, 0xffff0000, v230
	v_lshlrev_b32_e32 v112, 16, v231
	v_and_b32_e32 v113, 0xffff0000, v231
	v_fma_f32 v118, -v0, v117, 1.0
	v_fmac_f32_e32 v117, v118, v117
	v_div_scale_f32 v118, vcc, v106, v116, v106
	v_mul_f32_e32 v119, v118, v117
	v_fma_f32 v120, -v0, v119, v118
	v_fmac_f32_e32 v119, v120, v117
	v_fma_f32 v0, -v0, v119, v118
	v_div_fmas_f32 v0, v0, v117, v119
	v_div_fixup_f32 v106, v0, v116, v106
	v_div_scale_f32 v0, s[2:3], v115, v115, v109
	v_rcp_f32_e32 v116, v0
	v_pk_mul_f32 v[110:111], v[106:107], v[110:111]
	v_fma_f32 v117, -v0, v116, 1.0
	v_fmac_f32_e32 v116, v117, v116
	v_div_scale_f32 v117, vcc, v109, v115, v109
	v_mul_f32_e32 v118, v117, v116
	v_fma_f32 v119, -v0, v118, v117
	v_fmac_f32_e32 v118, v119, v116
	v_fma_f32 v0, -v0, v118, v117
	v_div_fmas_f32 v0, v0, v116, v118
	v_div_fixup_f32 v109, v0, v115, v109
	v_div_scale_f32 v0, s[2:3], v114, v114, v108
	v_rcp_f32_e32 v115, v0
	s_nop 0
	v_fma_f32 v116, -v0, v115, 1.0
	v_fmac_f32_e32 v115, v116, v115
	v_div_scale_f32 v116, vcc, v108, v114, v108
	v_mul_f32_e32 v117, v116, v115
	v_fma_f32 v118, -v0, v117, v116
	v_fmac_f32_e32 v117, v118, v115
	v_fma_f32 v0, -v0, v117, v116
	v_div_fmas_f32 v0, v0, v115, v117
	v_div_fixup_f32 v108, v0, v114, v108
	v_pk_mul_f32 v[112:113], v[108:109], v[112:113]

; DEV float bf2f(bf16_t h) { return __uint_as_float(((unsigned)h) << 16); }
; DEV float silu_f(float x) { return x / (1.f + __expf(-x)); }
; DEV void phase_G(const Params& p, int b, unsigned char* ldsraw) {
;     ...
;           if (gate) {
;             uint2 ov = *(const uint2*)d;
;             v[0] = bf2f((bf16_t)(ov.x & 0xffff)) * silu_f(acc[i][j][0]);
;             v[1] = bf2f((bf16_t)(ov.x >> 16)) * silu_f(acc[i][j][1]);
;             v[2] = bf2f((bf16_t)(ov.y & 0xffff)) * silu_f(acc[i][j][2]);
;             v[3] = bf2f((bf16_t)(ov.y >> 16)) * silu_f(acc[i][j][3]);
.LBB0_813:
	s_andn2_b64 vcc, exec, s[2:3]
	s_cbranch_vccnz .LBB0_815
	v_pk_add_f32 v[112:113], v[112:113], 1.0 op_sel_hi:[1,0]
	v_pk_add_f32 v[110:111], v[110:111], 1.0 op_sel_hi:[1,0]
	v_div_scale_f32 v0, s[2:3], v113, v113, v103
	v_rcp_f32_e32 v114, v0
	s_waitcnt vmcnt(7)
	v_lshlrev_b32_e32 v106, 16, v232
	v_fma_f32 v115, -v0, v114, 1.0
	v_fmac_f32_e32 v114, v115, v114
	v_div_scale_f32 v115, vcc, v103, v113, v103
	v_mul_f32_e32 v116, v115, v114
	v_fma_f32 v117, -v0, v116, v115
	v_fmac_f32_e32 v116, v117, v114
	v_fma_f32 v0, -v0, v116, v115
	v_div_fmas_f32 v0, v0, v114, v116
	v_div_fixup_f32 v103, v0, v113, v103
	v_div_scale_f32 v0, s[2:3], v112, v112, v102
	v_rcp_f32_e32 v113, v0
	v_and_b32_e32 v107, 0xffff0000, v232
	v_lshlrev_b32_e32 v108, 16, v233
	v_and_b32_e32 v109, 0xffff0000, v233
	v_fma_f32 v114, -v0, v113, 1.0
	v_fmac_f32_e32 v113, v114, v113
	v_div_scale_f32 v114, vcc, v102, v112, v102
	v_mul_f32_e32 v115, v114, v113
	v_fma_f32 v116, -v0, v115, v114
	v_fmac_f32_e32 v115, v116, v113
	v_fma_f32 v0, -v0, v115, v114
	v_div_fmas_f32 v0, v0, v113, v115
	v_div_fixup_f32 v102, v0, v112, v102
	v_div_scale_f32 v0, s[2:3], v111, v111, v105
	v_rcp_f32_e32 v112, v0
	v_pk_mul_f32 v[106:107], v[102:103], v[106:107]
	v_fma_f32 v113, -v0, v112, 1.0
	v_fmac_f32_e32 v112, v113, v112
	v_div_scale_f32 v113, vcc, v105, v111, v105
	v_mul_f32_e32 v114, v113, v112
	v_fma_f32 v115, -v0, v114, v113
	v_fmac_f32_e32 v114, v115, v112
	v_fma_f32 v0, -v0, v114, v113
	v_div_fmas_f32 v0, v0, v112, v114
	v_div_fixup_f32 v105, v0, v111, v105
	v_div_scale_f32 v0, s[2:3], v110, v110, v104
	v_rcp_f32_e32 v111, v0
	s_nop 0
	v_fma_f32 v112, -v0, v111, 1.0
	v_fmac_f32_e32 v111, v112, v111
	v_div_scale_f32 v112, vcc, v104, v110, v104
	v_mul_f32_e32 v113, v112, v111
	v_fma_f32 v114, -v0, v113, v112
	v_fmac_f32_e32 v113, v114, v111
	v_fma_f32 v0, -v0, v113, v112
	v_div_fmas_f32 v0, v0, v111, v113
	v_div_fixup_f32 v104, v0, v110, v104
	v_pk_mul_f32 v[108:109], v[104:105], v[108:109]

; DEV float bf2f(bf16_t h) { return __uint_as_float(((unsigned)h) << 16); }
; DEV float silu_f(float x) { return x / (1.f + __expf(-x)); }
; DEV void phase_G(const Params& p, int b, unsigned char* ldsraw) {
;     ...
;           if (gate) {
;             uint2 ov = *(const uint2*)d;
;             v[0] = bf2f((bf16_t)(ov.x & 0xffff)) * silu_f(acc[i][j][0]);
;             v[1] = bf2f((bf16_t)(ov.x >> 16)) * silu_f(acc[i][j][1]);
;             v[2] = bf2f((bf16_t)(ov.y & 0xffff)) * silu_f(acc[i][j][2]);
;             v[3] = bf2f((bf16_t)(ov.y >> 16)) * silu_f(acc[i][j][3]);
.LBB0_817:
	s_andn2_b64 vcc, exec, s[2:3]
	s_cbranch_vccnz .LBB0_819
	v_pk_add_f32 v[108:109], v[108:109], 1.0 op_sel_hi:[1,0]
	v_pk_add_f32 v[106:107], v[106:107], 1.0 op_sel_hi:[1,0]
	v_div_scale_f32 v0, s[2:3], v109, v109, v99
	v_rcp_f32_e32 v110, v0
	s_waitcnt vmcnt(7)
	v_lshlrev_b32_e32 v102, 16, v234
	v_fma_f32 v111, -v0, v110, 1.0
	v_fmac_f32_e32 v110, v111, v110
	v_div_scale_f32 v111, vcc, v99, v109, v99
	v_mul_f32_e32 v112, v111, v110
	v_fma_f32 v113, -v0, v112, v111
	v_fmac_f32_e32 v112, v113, v110
	v_fma_f32 v0, -v0, v112, v111
	v_div_fmas_f32 v0, v0, v110, v112
	v_div_fixup_f32 v99, v0, v109, v99
	v_div_scale_f32 v0, s[2:3], v108, v108, v98
	v_rcp_f32_e32 v109, v0
	v_and_b32_e32 v103, 0xffff0000, v234
	v_lshlrev_b32_e32 v104, 16, v235
	v_and_b32_e32 v105, 0xffff0000, v235
	v_fma_f32 v110, -v0, v109, 1.0
	v_fmac_f32_e32 v109, v110, v109
	v_div_scale_f32 v110, vcc, v98, v108, v98
	v_mul_f32_e32 v111, v110, v109
	v_fma_f32 v112, -v0, v111, v110
	v_fmac_f32_e32 v111, v112, v109
	v_fma_f32 v0, -v0, v111, v110
	v_div_fmas_f32 v0, v0, v109, v111
	v_div_fixup_f32 v98, v0, v108, v98
	v_div_scale_f32 v0, s[2:3], v107, v107, v101
	v_rcp_f32_e32 v108, v0
	v_pk_mul_f32 v[102:103], v[98:99], v[102:103]
	v_fma_f32 v109, -v0, v108, 1.0
	v_fmac_f32_e32 v108, v109, v108
	v_div_scale_f32 v109, vcc, v101, v107, v101
	v_mul_f32_e32 v110, v109, v108
	v_fma_f32 v111, -v0, v110, v109
	v_fmac_f32_e32 v110, v111, v108
	v_fma_f32 v0, -v0, v110, v109
	v_div_fmas_f32 v0, v0, v108, v110
	v_div_fixup_f32 v101, v0, v107, v101
	v_div_scale_f32 v0, s[2:3], v106, v106, v100
	v_rcp_f32_e32 v107, v0
	s_nop 0
	v_fma_f32 v108, -v0, v107, 1.0
	v_fmac_f32_e32 v107, v108, v107
	v_div_scale_f32 v108, vcc, v100, v106, v100
	v_mul_f32_e32 v109, v108, v107
	v_fma_f32 v110, -v0, v109, v108
	v_fmac_f32_e32 v109, v110, v107
	v_fma_f32 v0, -v0, v109, v108
	v_div_fmas_f32 v0, v0, v107, v109
	v_div_fixup_f32 v100, v0, v106, v100
	v_pk_mul_f32 v[104:105], v[100:101], v[104:105]

; DEV float bf2f(bf16_t h) { return __uint_as_float(((unsigned)h) << 16); }
; DEV float silu_f(float x) { return x / (1.f + __expf(-x)); }
; DEV void phase_G(const Params& p, int b, unsigned char* ldsraw) {
;     ...
;     for (int i = 0; i < 4; i++) {
;       const int t = mt * 256 + wm * 64 + i * 16 + lr;
;       if (t < LT) {
; #pragma unroll
;         for (int j = 0; j < 8; j++) {
;           bf16_t* d = dst + (size_t)t * ld + cb + wn * 128 + j * 16 + lg * 4;
;           f32x4 v;
;           if (gate) {
;             uint2 ov = *(const uint2*)d;
;             v[0] = bf2f((bf16_t)(ov.x & 0xffff)) * silu_f(acc[i][j][0]);
;             v[1] = bf2f((bf16_t)(ov.x >> 16)) * silu_f(acc[i][j][1]);
;             v[2] = bf2f((bf16_t)(ov.y & 0xffff)) * silu_f(acc[i][j][2]);
;             v[3] = bf2f((bf16_t)(ov.y >> 16)) * silu_f(acc[i][j][3]);
.LBB0_823:
	v_ashrrev_i32_e32 v102, 31, v0
	v_mul_lo_u32 v108, s1, v0
	v_mul_lo_u32 v109, s0, v102
	v_mad_u64_u32 v[102:103], s[8:9], s0, v0, 0
	v_add3_u32 v103, v103, v109, v108
	s_andn2_b64 vcc, exec, s[2:3]
	v_lshl_add_u64 v[102:103], v[102:103], 1, v[134:135]
	s_cbranch_vccnz .Lgskip_1
	global_load_dwordx2 v[220:221], v[102:103], off
	global_load_dwordx2 v[222:223], v[102:103], off offset:32
	global_load_dwordx2 v[224:225], v[102:103], off offset:64
	global_load_dwordx2 v[226:227], v[102:103], off offset:96
	global_load_dwordx2 v[228:229], v[102:103], off offset:128
	global_load_dwordx2 v[230:231], v[102:103], off offset:160
	global_load_dwordx2 v[232:233], v[102:103], off offset:192
	global_load_dwordx2 v[234:235], v[102:103], off offset:224
.Lgskip_1:
	s_cbranch_vccnz .LBB0_825
	v_pk_add_f32 v[106:107], v[106:107], 1.0 op_sel_hi:[1,0]
	v_pk_add_f32 v[104:105], v[104:105], 1.0 op_sel_hi:[1,0]
	v_div_scale_f32 v0, s[2:3], v107, v107, v95
	v_rcp_f32_e32 v108, v0
	s_waitcnt vmcnt(7)
	v_lshlrev_b32_e32 v98, 16, v220
	v_fma_f32 v109, -v0, v108, 1.0
	v_fmac_f32_e32 v108, v109, v108
	v_div_scale_f32 v109, vcc, v95, v107, v95
	v_mul_f32_e32 v110, v109, v108
	v_fma_f32 v111, -v0, v110, v109
	v_fmac_f32_e32 v110, v111, v108
	v_fma_f32 v0, -v0, v110, v109
	v_div_fmas_f32 v0, v0, v108, v110
	v_div_fixup_f32 v95, v0, v107, v95
	v_div_scale_f32 v0, s[2:3], v106, v106, v94
	v_rcp_f32_e32 v107, v0
	v_and_b32_e32 v99, 0xffff0000, v220
	v_lshlrev_b32_e32 v100, 16, v221
	v_and_b32_e32 v101, 0xffff0000, v221
	v_fma_f32 v108, -v0, v107, 1.0
	v_fmac_f32_e32 v107, v108, v107
	v_div_scale_f32 v108, vcc, v94, v106, v94
	v_mul_f32_e32 v109, v108, v107
	v_fma_f32 v110, -v0, v109, v108
	v_fmac_f32_e32 v109, v110, v107
	v_fma_f32 v0, -v0, v109, v108
	v_div_fmas_f32 v0, v0, v107, v109
	v_div_fixup_f32 v94, v0, v106, v94
	v_div_scale_f32 v0, s[2:3], v105, v105, v97
	v_rcp_f32_e32 v106, v0
	v_pk_mul_f32 v[98:99], v[94:95], v[98:99]
	v_fma_f32 v107, -v0, v106, 1.0
	v_fmac_f32_e32 v106, v107, v106
	v_div_scale_f32 v107, vcc, v97, v105, v97
	v_mul_f32_e32 v108, v107, v106
	v_fma_f32 v109, -v0, v108, v107
	v_fmac_f32_e32 v108, v109, v106
	v_fma_f32 v0, -v0, v108, v107
	v_div_fmas_f32 v0, v0, v106, v108
	v_div_fixup_f32 v97, v0, v105, v97
	v_div_scale_f32 v0, s[2:3], v104, v104, v96
	v_rcp_f32_e32 v105, v0
	s_nop 0
	v_fma_f32 v106, -v0, v105, 1.0
	v_fmac_f32_e32 v105, v106, v105
	v_div_scale_f32 v106, vcc, v96, v104, v96
	v_mul_f32_e32 v107, v106, v105
	v_fma_f32 v108, -v0, v107, v106
	v_fmac_f32_e32 v107, v108, v105
	v_fma_f32 v0, -v0, v107, v106
	v_div_fmas_f32 v0, v0, v105, v107
	v_div_fixup_f32 v96, v0, v104, v96
	v_pk_mul_f32 v[100:101], v[96:97], v[100:101]

; DEV float bf2f(bf16_t h) { return __uint_as_float(((unsigned)h) << 16); }
; DEV float silu_f(float x) { return x / (1.f + __expf(-x)); }
; DEV void phase_G(const Params& p, int b, unsigned char* ldsraw) {
;     ...
;           if (gate) {
;             uint2 ov = *(const uint2*)d;
;             v[0] = bf2f((bf16_t)(ov.x & 0xffff)) * silu_f(acc[i][j][0]);
;             v[1] = bf2f((bf16_t)(ov.x >> 16)) * silu_f(acc[i][j][1]);
;             v[2] = bf2f((bf16_t)(ov.y & 0xffff)) * silu_f(acc[i][j][2]);
;             v[3] = bf2f((bf16_t)(ov.y >> 16)) * silu_f(acc[i][j][3]);
.LBB0_827:
	s_andn2_b64 vcc, exec, s[2:3]
	s_cbranch_vccnz .LBB0_829
	v_pk_add_f32 v[100:101], v[100:101], 1.0 op_sel_hi:[1,0]
	v_pk_add_f32 v[98:99], v[98:99], 1.0 op_sel_hi:[1,0]
	v_div_scale_f32 v0, s[2:3], v101, v101, v91
	v_rcp_f32_e32 v104, v0
	s_waitcnt vmcnt(7)
	v_lshlrev_b32_e32 v94, 16, v222
	v_fma_f32 v105, -v0, v104, 1.0
	v_fmac_f32_e32 v104, v105, v104
	v_div_scale_f32 v105, vcc, v91, v101, v91
	v_mul_f32_e32 v106, v105, v104
	v_fma_f32 v107, -v0, v106, v105
	v_fmac_f32_e32 v106, v107, v104
	v_fma_f32 v0, -v0, v106, v105
	v_div_fmas_f32 v0, v0, v104, v106
	v_div_fixup_f32 v91, v0, v101, v91
	v_div_scale_f32 v0, s[2:3], v100, v100, v90
	v_rcp_f32_e32 v101, v0
	v_and_b32_e32 v95, 0xffff0000, v222
	v_lshlrev_b32_e32 v96, 16, v223
	v_and_b32_e32 v97, 0xffff0000, v223
	v_fma_f32 v104, -v0, v101, 1.0
	v_fmac_f32_e32 v101, v104, v101
	v_div_scale_f32 v104, vcc, v90, v100, v90
	v_mul_f32_e32 v105, v104, v101
	v_fma_f32 v106, -v0, v105, v104
	v_fmac_f32_e32 v105, v106, v101
	v_fma_f32 v0, -v0, v105, v104
	v_div_fmas_f32 v0, v0, v101, v105
	v_div_fixup_f32 v90, v0, v100, v90
	v_div_scale_f32 v0, s[2:3], v99, v99, v93
	v_rcp_f32_e32 v100, v0
	v_pk_mul_f32 v[94:95], v[90:91], v[94:95]
	v_fma_f32 v101, -v0, v100, 1.0
	v_fmac_f32_e32 v100, v101, v100
	v_div_scale_f32 v101, vcc, v93, v99, v93
	v_mul_f32_e32 v104, v101, v100
	v_fma_f32 v105, -v0, v104, v101
	v_fmac_f32_e32 v104, v105, v100
	v_fma_f32 v0, -v0, v104, v101
	v_div_fmas_f32 v0, v0, v100, v104
	v_div_fixup_f32 v93, v0, v99, v93
	v_div_scale_f32 v0, s[2:3], v98, v98, v92
	v_rcp_f32_e32 v99, v0
	s_nop 0
	v_fma_f32 v100, -v0, v99, 1.0
	v_fmac_f32_e32 v99, v100, v99
	v_div_scale_f32 v100, vcc, v92, v98, v92
	v_mul_f32_e32 v101, v100, v99
	v_fma_f32 v104, -v0, v101, v100
	v_fmac_f32_e32 v101, v104, v99
	v_fma_f32 v0, -v0, v101, v100
	v_div_fmas_f32 v0, v0, v99, v101
	v_div_fixup_f32 v92, v0, v98, v92
	v_pk_mul_f32 v[96:97], v[92:93], v[96:97]

; DEV float bf2f(bf16_t h) { return __uint_as_float(((unsigned)h) << 16); }
; DEV float silu_f(float x) { return x / (1.f + __expf(-x)); }
; DEV void phase_G(const Params& p, int b, unsigned char* ldsraw) {
;     ...
;           if (gate) {
;             uint2 ov = *(const uint2*)d;
;             v[0] = bf2f((bf16_t)(ov.x & 0xffff)) * silu_f(acc[i][j][0]);
;             v[1] = bf2f((bf16_t)(ov.x >> 16)) * silu_f(acc[i][j][1]);
;             v[2] = bf2f((bf16_t)(ov.y & 0xffff)) * silu_f(acc[i][j][2]);
;             v[3] = bf2f((bf16_t)(ov.y >> 16)) * silu_f(acc[i][j][3]);
.LBB0_831:
	s_andn2_b64 vcc, exec, s[2:3]
	s_cbranch_vccnz .LBB0_833
	v_pk_add_f32 v[96:97], v[96:97], 1.0 op_sel_hi:[1,0]
	v_pk_add_f32 v[94:95], v[94:95], 1.0 op_sel_hi:[1,0]
	v_div_scale_f32 v0, s[2:3], v97, v97, v87
	v_rcp_f32_e32 v98, v0
	s_waitcnt vmcnt(7)
	v_lshlrev_b32_e32 v90, 16, v224
	v_fma_f32 v99, -v0, v98, 1.0
	v_fmac_f32_e32 v98, v99, v98
	v_div_scale_f32 v99, vcc, v87, v97, v87
	v_mul_f32_e32 v100, v99, v98
	v_fma_f32 v101, -v0, v100, v99
	v_fmac_f32_e32 v100, v101, v98
	v_fma_f32 v0, -v0, v100, v99
	v_div_fmas_f32 v0, v0, v98, v100
	v_div_fixup_f32 v87, v0, v97, v87
	v_div_scale_f32 v0, s[2:3], v96, v96, v86
	v_rcp_f32_e32 v97, v0
	v_and_b32_e32 v91, 0xffff0000, v224
	v_lshlrev_b32_e32 v92, 16, v225
	v_and_b32_e32 v93, 0xffff0000, v225
	v_fma_f32 v98, -v0, v97, 1.0
	v_fmac_f32_e32 v97, v98, v97
	v_div_scale_f32 v98, vcc, v86, v96, v86
	v_mul_f32_e32 v99, v98, v97
	v_fma_f32 v100, -v0, v99, v98
	v_fmac_f32_e32 v99, v100, v97
	v_fma_f32 v0, -v0, v99, v98
	v_div_fmas_f32 v0, v0, v97, v99
	v_div_fixup_f32 v86, v0, v96, v86
	v_div_scale_f32 v0, s[2:3], v95, v95, v89
	v_rcp_f32_e32 v96, v0
	v_pk_mul_f32 v[90:91], v[86:87], v[90:91]
	v_fma_f32 v97, -v0, v96, 1.0
	v_fmac_f32_e32 v96, v97, v96
	v_div_scale_f32 v97, vcc, v89, v95, v89
	v_mul_f32_e32 v98, v97, v96
	v_fma_f32 v99, -v0, v98, v97
	v_fmac_f32_e32 v98, v99, v96
	v_fma_f32 v0, -v0, v98, v97
	v_div_fmas_f32 v0, v0, v96, v98
	v_div_fixup_f32 v89, v0, v95, v89
	v_div_scale_f32 v0, s[2:3], v94, v94, v88
	v_rcp_f32_e32 v95, v0
	s_nop 0
	v_fma_f32 v96, -v0, v95, 1.0
	v_fmac_f32_e32 v95, v96, v95
	v_div_scale_f32 v96, vcc, v88, v94, v88
	v_mul_f32_e32 v97, v96, v95
	v_fma_f32 v98, -v0, v97, v96
	v_fmac_f32_e32 v97, v98, v95
	v_fma_f32 v0, -v0, v97, v96
	v_div_fmas_f32 v0, v0, v95, v97
	v_div_fixup_f32 v88, v0, v94, v88
	v_pk_mul_f32 v[92:93], v[88:89], v[92:93]

; DEV float bf2f(bf16_t h) { return __uint_as_float(((unsigned)h) << 16); }
; DEV float silu_f(float x) { return x / (1.f + __expf(-x)); }
; DEV void phase_G(const Params& p, int b, unsigned char* ldsraw) {
;     ...
;           if (gate) {
;             uint2 ov = *(const uint2*)d;
;             v[0] = bf2f((bf16_t)(ov.x & 0xffff)) * silu_f(acc[i][j][0]);
;             v[1] = bf2f((bf16_t)(ov.x >> 16)) * silu_f(acc[i][j][1]);
;             v[2] = bf2f((bf16_t)(ov.y & 0xffff)) * silu_f(acc[i][j][2]);
;             v[3] = bf2f((bf16_t)(ov.y >> 16)) * silu_f(acc[i][j][3]);
.LBB0_835:
	s_andn2_b64 vcc, exec, s[2:3]
	s_cbranch_vccnz .LBB0_837
	v_pk_add_f32 v[92:93], v[92:93], 1.0 op_sel_hi:[1,0]
	v_pk_add_f32 v[90:91], v[90:91], 1.0 op_sel_hi:[1,0]
	v_div_scale_f32 v0, s[2:3], v93, v93, v83
	v_rcp_f32_e32 v94, v0
	s_waitcnt vmcnt(7)
	v_lshlrev_b32_e32 v86, 16, v226
	v_fma_f32 v95, -v0, v94, 1.0
	v_fmac_f32_e32 v94, v95, v94
	v_div_scale_f32 v95, vcc, v83, v93, v83
	v_mul_f32_e32 v96, v95, v94
	v_fma_f32 v97, -v0, v96, v95
	v_fmac_f32_e32 v96, v97, v94
	v_fma_f32 v0, -v0, v96, v95
	v_div_fmas_f32 v0, v0, v94, v96
	v_div_fixup_f32 v83, v0, v93, v83
	v_div_scale_f32 v0, s[2:3], v92, v92, v82
	v_rcp_f32_e32 v93, v0
	v_and_b32_e32 v87, 0xffff0000, v226
	v_lshlrev_b32_e32 v88, 16, v227
	v_and_b32_e32 v89, 0xffff0000, v227
	v_fma_f32 v94, -v0, v93, 1.0
	v_fmac_f32_e32 v93, v94, v93
	v_div_scale_f32 v94, vcc, v82, v92, v82
	v_mul_f32_e32 v95, v94, v93
	v_fma_f32 v96, -v0, v95, v94
	v_fmac_f32_e32 v95, v96, v93
	v_fma_f32 v0, -v0, v95, v94
	v_div_fmas_f32 v0, v0, v93, v95
	v_div_fixup_f32 v82, v0, v92, v82
	v_div_scale_f32 v0, s[2:3], v91, v91, v85
	v_rcp_f32_e32 v92, v0
	v_pk_mul_f32 v[86:87], v[82:83], v[86:87]
	v_fma_f32 v93, -v0, v92, 1.0
	v_fmac_f32_e32 v92, v93, v92
	v_div_scale_f32 v93, vcc, v85, v91, v85
	v_mul_f32_e32 v94, v93, v92
	v_fma_f32 v95, -v0, v94, v93
	v_fmac_f32_e32 v94, v95, v92
	v_fma_f32 v0, -v0, v94, v93
	v_div_fmas_f32 v0, v0, v92, v94
	v_div_fixup_f32 v85, v0, v91, v85
	v_div_scale_f32 v0, s[2:3], v90, v90, v84
	v_rcp_f32_e32 v91, v0
	s_nop 0
	v_fma_f32 v92, -v0, v91, 1.0
	v_fmac_f32_e32 v91, v92, v91
	v_div_scale_f32 v92, vcc, v84, v90, v84
	v_mul_f32_e32 v93, v92, v91
	v_fma_f32 v94, -v0, v93, v92
	v_fmac_f32_e32 v93, v94, v91
	v_fma_f32 v0, -v0, v93, v92
	v_div_fmas_f32 v0, v0, v91, v93
	v_div_fixup_f32 v84, v0, v90, v84
	v_pk_mul_f32 v[88:89], v[84:85], v[88:89]

; DEV float bf2f(bf16_t h) { return __uint_as_float(((unsigned)h) << 16); }
; DEV float silu_f(float x) { return x / (1.f + __expf(-x)); }
; DEV void phase_G(const Params& p, int b, unsigned char* ldsraw) {
;     ...
;           if (gate) {
;             uint2 ov = *(const uint2*)d;
;             v[0] = bf2f((bf16_t)(ov.x & 0xffff)) * silu_f(acc[i][j][0]);
;             v[1] = bf2f((bf16_t)(ov.x >> 16)) * silu_f(acc[i][j][1]);
;             v[2] = bf2f((bf16_t)(ov.y & 0xffff)) * silu_f(acc[i][j][2]);
;             v[3] = bf2f((bf16_t)(ov.y >> 16)) * silu_f(acc[i][j][3]);
.LBB0_839:
	s_andn2_b64 vcc, exec, s[2:3]
	s_cbranch_vccnz .LBB0_841
	v_pk_add_f32 v[88:89], v[88:89], 1.0 op_sel_hi:[1,0]
	v_pk_add_f32 v[86:87], v[86:87], 1.0 op_sel_hi:[1,0]
	v_div_scale_f32 v0, s[2:3], v89, v89, v79
	v_rcp_f32_e32 v90, v0
	s_waitcnt vmcnt(7)
	v_lshlrev_b32_e32 v82, 16, v228
	v_fma_f32 v91, -v0, v90, 1.0
	v_fmac_f32_e32 v90, v91, v90
	v_div_scale_f32 v91, vcc, v79, v89, v79
	v_mul_f32_e32 v92, v91, v90
	v_fma_f32 v93, -v0, v92, v91
	v_fmac_f32_e32 v92, v93, v90
	v_fma_f32 v0, -v0, v92, v91
	v_div_fmas_f32 v0, v0, v90, v92
	v_div_fixup_f32 v79, v0, v89, v79
	v_div_scale_f32 v0, s[2:3], v88, v88, v78
	v_rcp_f32_e32 v89, v0
	v_and_b32_e32 v83, 0xffff0000, v228
	v_lshlrev_b32_e32 v84, 16, v229
	v_and_b32_e32 v85, 0xffff0000, v229
	v_fma_f32 v90, -v0, v89, 1.0
	v_fmac_f32_e32 v89, v90, v89
	v_div_scale_f32 v90, vcc, v78, v88, v78
	v_mul_f32_e32 v91, v90, v89
	v_fma_f32 v92, -v0, v91, v90
	v_fmac_f32_e32 v91, v92, v89
	v_fma_f32 v0, -v0, v91, v90
	v_div_fmas_f32 v0, v0, v89, v91
	v_div_fixup_f32 v78, v0, v88, v78
	v_div_scale_f32 v0, s[2:3], v87, v87, v81
	v_rcp_f32_e32 v88, v0
	v_pk_mul_f32 v[82:83], v[78:79], v[82:83]
	v_fma_f32 v89, -v0, v88, 1.0
	v_fmac_f32_e32 v88, v89, v88
	v_div_scale_f32 v89, vcc, v81, v87, v81
	v_mul_f32_e32 v90, v89, v88
	v_fma_f32 v91, -v0, v90, v89
	v_fmac_f32_e32 v90, v91, v88
	v_fma_f32 v0, -v0, v90, v89
	v_div_fmas_f32 v0, v0, v88, v90
	v_div_fixup_f32 v81, v0, v87, v81
	v_div_scale_f32 v0, s[2:3], v86, v86, v80
	v_rcp_f32_e32 v87, v0
	s_nop 0
	v_fma_f32 v88, -v0, v87, 1.0
	v_fmac_f32_e32 v87, v88, v87
	v_div_scale_f32 v88, vcc, v80, v86, v80
	v_mul_f32_e32 v89, v88, v87
	v_fma_f32 v90, -v0, v89, v88
	v_fmac_f32_e32 v89, v90, v87
	v_fma_f32 v0, -v0, v89, v88
	v_div_fmas_f32 v0, v0, v87, v89
	v_div_fixup_f32 v80, v0, v86, v80
	v_pk_mul_f32 v[84:85], v[80:81], v[84:85]

; DEV float bf2f(bf16_t h) { return __uint_as_float(((unsigned)h) << 16); }
; DEV float silu_f(float x) { return x / (1.f + __expf(-x)); }
; DEV void phase_G(const Params& p, int b, unsigned char* ldsraw) {
;     ...
;           if (gate) {
;             uint2 ov = *(const uint2*)d;
;             v[0] = bf2f((bf16_t)(ov.x & 0xffff)) * silu_f(acc[i][j][0]);
;             v[1] = bf2f((bf16_t)(ov.x >> 16)) * silu_f(acc[i][j][1]);
;             v[2] = bf2f((bf16_t)(ov.y & 0xffff)) * silu_f(acc[i][j][2]);
;             v[3] = bf2f((bf16_t)(ov.y >> 16)) * silu_f(acc[i][j][3]);
.LBB0_843:
	s_andn2_b64 vcc, exec, s[2:3]
	s_cbranch_vccnz .LBB0_845
	v_pk_add_f32 v[84:85], v[84:85], 1.0 op_sel_hi:[1,0]
	v_pk_add_f32 v[82:83], v[82:83], 1.0 op_sel_hi:[1,0]
	v_div_scale_f32 v0, s[2:3], v85, v85, v75
	v_rcp_f32_e32 v86, v0
	s_waitcnt vmcnt(7)
	v_lshlrev_b32_e32 v78, 16, v230
	v_fma_f32 v87, -v0, v86, 1.0
	v_fmac_f32_e32 v86, v87, v86
	v_div_scale_f32 v87, vcc, v75, v85, v75
	v_mul_f32_e32 v88, v87, v86
	v_fma_f32 v89, -v0, v88, v87
	v_fmac_f32_e32 v88, v89, v86
	v_fma_f32 v0, -v0, v88, v87
	v_div_fmas_f32 v0, v0, v86, v88
	v_div_fixup_f32 v75, v0, v85, v75
	v_div_scale_f32 v0, s[2:3], v84, v84, v74
	v_rcp_f32_e32 v85, v0
	v_and_b32_e32 v79, 0xffff0000, v230
	v_lshlrev_b32_e32 v80, 16, v231
	v_and_b32_e32 v81, 0xffff0000, v231
	v_fma_f32 v86, -v0, v85, 1.0
	v_fmac_f32_e32 v85, v86, v85
	v_div_scale_f32 v86, vcc, v74, v84, v74
	v_mul_f32_e32 v87, v86, v85
	v_fma_f32 v88, -v0, v87, v86
	v_fmac_f32_e32 v87, v88, v85
	v_fma_f32 v0, -v0, v87, v86
	v_div_fmas_f32 v0, v0, v85, v87
	v_div_fixup_f32 v74, v0, v84, v74
	v_div_scale_f32 v0, s[2:3], v83, v83, v77
	v_rcp_f32_e32 v84, v0
	v_pk_mul_f32 v[78:79], v[74:75], v[78:79]
	v_fma_f32 v85, -v0, v84, 1.0
	v_fmac_f32_e32 v84, v85, v84
	v_div_scale_f32 v85, vcc, v77, v83, v77
	v_mul_f32_e32 v86, v85, v84
	v_fma_f32 v87, -v0, v86, v85
	v_fmac_f32_e32 v86, v87, v84
	v_fma_f32 v0, -v0, v86, v85
	v_div_fmas_f32 v0, v0, v84, v86
	v_div_fixup_f32 v77, v0, v83, v77
	v_div_scale_f32 v0, s[2:3], v82, v82, v76
	v_rcp_f32_e32 v83, v0
	s_nop 0
	v_fma_f32 v84, -v0, v83, 1.0
	v_fmac_f32_e32 v83, v84, v83
	v_div_scale_f32 v84, vcc, v76, v82, v76
	v_mul_f32_e32 v85, v84, v83
	v_fma_f32 v86, -v0, v85, v84
	v_fmac_f32_e32 v85, v86, v83
	v_fma_f32 v0, -v0, v85, v84
	v_div_fmas_f32 v0, v0, v83, v85
	v_div_fixup_f32 v76, v0, v82, v76
	v_pk_mul_f32 v[80:81], v[76:77], v[80:81]

; DEV float bf2f(bf16_t h) { return __uint_as_float(((unsigned)h) << 16); }
; DEV float silu_f(float x) { return x / (1.f + __expf(-x)); }
; DEV void phase_G(const Params& p, int b, unsigned char* ldsraw) {
;     ...
;           if (gate) {
;             uint2 ov = *(const uint2*)d;
;             v[0] = bf2f((bf16_t)(ov.x & 0xffff)) * silu_f(acc[i][j][0]);
;             v[1] = bf2f((bf16_t)(ov.x >> 16)) * silu_f(acc[i][j][1]);
;             v[2] = bf2f((bf16_t)(ov.y & 0xffff)) * silu_f(acc[i][j][2]);
;             v[3] = bf2f((bf16_t)(ov.y >> 16)) * silu_f(acc[i][j][3]);
.LBB0_847:
	s_andn2_b64 vcc, exec, s[2:3]
	s_cbranch_vccnz .LBB0_849
	v_pk_add_f32 v[80:81], v[80:81], 1.0 op_sel_hi:[1,0]
	v_pk_add_f32 v[78:79], v[78:79], 1.0 op_sel_hi:[1,0]
	v_div_scale_f32 v0, s[2:3], v81, v81, v71
	v_rcp_f32_e32 v82, v0
	s_waitcnt vmcnt(7)
	v_lshlrev_b32_e32 v74, 16, v232
	v_fma_f32 v83, -v0, v82, 1.0
	v_fmac_f32_e32 v82, v83, v82
	v_div_scale_f32 v83, vcc, v71, v81, v71
	v_mul_f32_e32 v84, v83, v82
	v_fma_f32 v85, -v0, v84, v83
	v_fmac_f32_e32 v84, v85, v82
	v_fma_f32 v0, -v0, v84, v83
	v_div_fmas_f32 v0, v0, v82, v84
	v_div_fixup_f32 v71, v0, v81, v71
	v_div_scale_f32 v0, s[2:3], v80, v80, v70
	v_rcp_f32_e32 v81, v0
	v_and_b32_e32 v75, 0xffff0000, v232
	v_lshlrev_b32_e32 v76, 16, v233
	v_and_b32_e32 v77, 0xffff0000, v233
	v_fma_f32 v82, -v0, v81, 1.0
	v_fmac_f32_e32 v81, v82, v81
	v_div_scale_f32 v82, vcc, v70, v80, v70
	v_mul_f32_e32 v83, v82, v81
	v_fma_f32 v84, -v0, v83, v82
	v_fmac_f32_e32 v83, v84, v81
	v_fma_f32 v0, -v0, v83, v82
	v_div_fmas_f32 v0, v0, v81, v83
	v_div_fixup_f32 v70, v0, v80, v70
	v_div_scale_f32 v0, s[2:3], v79, v79, v73
	v_rcp_f32_e32 v80, v0
	v_pk_mul_f32 v[74:75], v[70:71], v[74:75]
	v_fma_f32 v81, -v0, v80, 1.0
	v_fmac_f32_e32 v80, v81, v80
	v_div_scale_f32 v81, vcc, v73, v79, v73
	v_mul_f32_e32 v82, v81, v80
	v_fma_f32 v83, -v0, v82, v81
	v_fmac_f32_e32 v82, v83, v80
	v_fma_f32 v0, -v0, v82, v81
	v_div_fmas_f32 v0, v0, v80, v82
	v_div_fixup_f32 v73, v0, v79, v73
	v_div_scale_f32 v0, s[2:3], v78, v78, v72
	v_rcp_f32_e32 v79, v0
	s_nop 0
	v_fma_f32 v80, -v0, v79, 1.0
	v_fmac_f32_e32 v79, v80, v79
	v_div_scale_f32 v80, vcc, v72, v78, v72
	v_mul_f32_e32 v81, v80, v79
	v_fma_f32 v82, -v0, v81, v80
	v_fmac_f32_e32 v81, v82, v79
	v_fma_f32 v0, -v0, v81, v80
	v_div_fmas_f32 v0, v0, v79, v81
	v_div_fixup_f32 v72, v0, v78, v72
	v_pk_mul_f32 v[76:77], v[72:73], v[76:77]

; DEV float bf2f(bf16_t h) { return __uint_as_float(((unsigned)h) << 16); }
; DEV float silu_f(float x) { return x / (1.f + __expf(-x)); }
; DEV void phase_G(const Params& p, int b, unsigned char* ldsraw) {
;     ...
;           if (gate) {
;             uint2 ov = *(const uint2*)d;
;             v[0] = bf2f((bf16_t)(ov.x & 0xffff)) * silu_f(acc[i][j][0]);
;             v[1] = bf2f((bf16_t)(ov.x >> 16)) * silu_f(acc[i][j][1]);
;             v[2] = bf2f((bf16_t)(ov.y & 0xffff)) * silu_f(acc[i][j][2]);
;             v[3] = bf2f((bf16_t)(ov.y >> 16)) * silu_f(acc[i][j][3]);
.LBB0_851:
	s_andn2_b64 vcc, exec, s[2:3]
	s_cbranch_vccnz .LBB0_853
	v_pk_add_f32 v[76:77], v[76:77], 1.0 op_sel_hi:[1,0]
	v_pk_add_f32 v[74:75], v[74:75], 1.0 op_sel_hi:[1,0]
	v_div_scale_f32 v0, s[2:3], v77, v77, v67
	v_rcp_f32_e32 v78, v0
	s_waitcnt vmcnt(7)
	v_lshlrev_b32_e32 v70, 16, v234
	v_fma_f32 v79, -v0, v78, 1.0
	v_fmac_f32_e32 v78, v79, v78
	v_div_scale_f32 v79, vcc, v67, v77, v67
	v_mul_f32_e32 v80, v79, v78
	v_fma_f32 v81, -v0, v80, v79
	v_fmac_f32_e32 v80, v81, v78
	v_fma_f32 v0, -v0, v80, v79
	v_div_fmas_f32 v0, v0, v78, v80
	v_div_fixup_f32 v67, v0, v77, v67
	v_div_scale_f32 v0, s[2:3], v76, v76, v66
	v_rcp_f32_e32 v77, v0
	v_and_b32_e32 v71, 0xffff0000, v234
	v_lshlrev_b32_e32 v72, 16, v235
	v_and_b32_e32 v73, 0xffff0000, v235
	v_fma_f32 v78, -v0, v77, 1.0
	v_fmac_f32_e32 v77, v78, v77
	v_div_scale_f32 v78, vcc, v66, v76, v66
	v_mul_f32_e32 v79, v78, v77
	v_fma_f32 v80, -v0, v79, v78
	v_fmac_f32_e32 v79, v80, v77
	v_fma_f32 v0, -v0, v79, v78
	v_div_fmas_f32 v0, v0, v77, v79
	v_div_fixup_f32 v66, v0, v76, v66
	v_div_scale_f32 v0, s[2:3], v75, v75, v69
	v_rcp_f32_e32 v76, v0
	v_pk_mul_f32 v[70:71], v[66:67], v[70:71]
	v_fma_f32 v77, -v0, v76, 1.0
	v_fmac_f32_e32 v76, v77, v76
	v_div_scale_f32 v77, vcc, v69, v75, v69
	v_mul_f32_e32 v78, v77, v76
	v_fma_f32 v79, -v0, v78, v77
	v_fmac_f32_e32 v78, v79, v76
	v_fma_f32 v0, -v0, v78, v77
	v_div_fmas_f32 v0, v0, v76, v78
	v_div_fixup_f32 v69, v0, v75, v69
	v_div_scale_f32 v0, s[2:3], v74, v74, v68
	v_rcp_f32_e32 v75, v0
	s_nop 0
	v_fma_f32 v76, -v0, v75, 1.0
	v_fmac_f32_e32 v75, v76, v75
	v_div_scale_f32 v76, vcc, v68, v74, v68
	v_mul_f32_e32 v77, v76, v75
	v_fma_f32 v78, -v0, v77, v76
	v_fmac_f32_e32 v77, v78, v75
	v_fma_f32 v0, -v0, v77, v76
	v_div_fmas_f32 v0, v0, v75, v77
	v_div_fixup_f32 v68, v0, v74, v68
	v_pk_mul_f32 v[72:73], v[68:69], v[72:73]

; DEV float bf2f(bf16_t h) { return __uint_as_float(((unsigned)h) << 16); }
; DEV float silu_f(float x) { return x / (1.f + __expf(-x)); }
; DEV void phase_G(const Params& p, int b, unsigned char* ldsraw) {
;     ...
;     for (int i = 0; i < 4; i++) {
;       const int t = mt * 256 + wm * 64 + i * 16 + lr;
;       if (t < LT) {
; #pragma unroll
;         for (int j = 0; j < 8; j++) {
;           bf16_t* d = dst + (size_t)t * ld + cb + wn * 128 + j * 16 + lg * 4;
;           f32x4 v;
;           if (gate) {
;             uint2 ov = *(const uint2*)d;
;             v[0] = bf2f((bf16_t)(ov.x & 0xffff)) * silu_f(acc[i][j][0]);
;             v[1] = bf2f((bf16_t)(ov.x >> 16)) * silu_f(acc[i][j][1]);
;             v[2] = bf2f((bf16_t)(ov.y & 0xffff)) * silu_f(acc[i][j][2]);
;             v[3] = bf2f((bf16_t)(ov.y >> 16)) * silu_f(acc[i][j][3]);
.LBB0_857:
	v_ashrrev_i32_e32 v70, 31, v0
	v_mul_lo_u32 v76, s1, v0
	v_mul_lo_u32 v77, s0, v70
	v_mad_u64_u32 v[70:71], s[8:9], s0, v0, 0
	v_add3_u32 v71, v71, v77, v76
	s_andn2_b64 vcc, exec, s[2:3]
	v_lshl_add_u64 v[70:71], v[70:71], 1, v[134:135]
	s_cbranch_vccnz .Lgskip_2
	global_load_dwordx2 v[220:221], v[70:71], off
	global_load_dwordx2 v[222:223], v[70:71], off offset:32
	global_load_dwordx2 v[224:225], v[70:71], off offset:64
	global_load_dwordx2 v[226:227], v[70:71], off offset:96
	global_load_dwordx2 v[228:229], v[70:71], off offset:128
	global_load_dwordx2 v[230:231], v[70:71], off offset:160
	global_load_dwordx2 v[232:233], v[70:71], off offset:192
	global_load_dwordx2 v[234:235], v[70:71], off offset:224
.Lgskip_2:
	s_cbranch_vccnz .LBB0_859
	v_pk_add_f32 v[74:75], v[74:75], 1.0 op_sel_hi:[1,0]
	v_pk_add_f32 v[72:73], v[72:73], 1.0 op_sel_hi:[1,0]
	v_div_scale_f32 v0, s[2:3], v75, v75, v63
	v_rcp_f32_e32 v76, v0
	s_waitcnt vmcnt(7)
	v_lshlrev_b32_e32 v66, 16, v220
	v_fma_f32 v77, -v0, v76, 1.0
	v_fmac_f32_e32 v76, v77, v76
	v_div_scale_f32 v77, vcc, v63, v75, v63
	v_mul_f32_e32 v78, v77, v76
	v_fma_f32 v79, -v0, v78, v77
	v_fmac_f32_e32 v78, v79, v76
	v_fma_f32 v0, -v0, v78, v77
	v_div_fmas_f32 v0, v0, v76, v78
	v_div_fixup_f32 v63, v0, v75, v63
	v_div_scale_f32 v0, s[2:3], v74, v74, v62
	v_rcp_f32_e32 v75, v0
	v_and_b32_e32 v67, 0xffff0000, v220
	v_lshlrev_b32_e32 v68, 16, v221
	v_and_b32_e32 v69, 0xffff0000, v221
	v_fma_f32 v76, -v0, v75, 1.0
	v_fmac_f32_e32 v75, v76, v75
	v_div_scale_f32 v76, vcc, v62, v74, v62
	v_mul_f32_e32 v77, v76, v75
	v_fma_f32 v78, -v0, v77, v76
	v_fmac_f32_e32 v77, v78, v75
	v_fma_f32 v0, -v0, v77, v76
	v_div_fmas_f32 v0, v0, v75, v77
	v_div_fixup_f32 v62, v0, v74, v62
	v_div_scale_f32 v0, s[2:3], v73, v73, v65
	v_rcp_f32_e32 v74, v0
	v_pk_mul_f32 v[66:67], v[62:63], v[66:67]
	v_fma_f32 v75, -v0, v74, 1.0
	v_fmac_f32_e32 v74, v75, v74
	v_div_scale_f32 v75, vcc, v65, v73, v65
	v_mul_f32_e32 v76, v75, v74
	v_fma_f32 v77, -v0, v76, v75
	v_fmac_f32_e32 v76, v77, v74
	v_fma_f32 v0, -v0, v76, v75
	v_div_fmas_f32 v0, v0, v74, v76
	v_div_fixup_f32 v65, v0, v73, v65
	v_div_scale_f32 v0, s[2:3], v72, v72, v64
	v_rcp_f32_e32 v73, v0
	s_nop 0
	v_fma_f32 v74, -v0, v73, 1.0
	v_fmac_f32_e32 v73, v74, v73
	v_div_scale_f32 v74, vcc, v64, v72, v64
	v_mul_f32_e32 v75, v74, v73
	v_fma_f32 v76, -v0, v75, v74
	v_fmac_f32_e32 v75, v76, v73
	v_fma_f32 v0, -v0, v75, v74
	v_div_fmas_f32 v0, v0, v73, v75
	v_div_fixup_f32 v64, v0, v72, v64
	v_pk_mul_f32 v[68:69], v[64:65], v[68:69]

; DEV float bf2f(bf16_t h) { return __uint_as_float(((unsigned)h) << 16); }
; DEV float silu_f(float x) { return x / (1.f + __expf(-x)); }
; DEV void phase_G(const Params& p, int b, unsigned char* ldsraw) {
;     ...
;           if (gate) {
;             uint2 ov = *(const uint2*)d;
;             v[0] = bf2f((bf16_t)(ov.x & 0xffff)) * silu_f(acc[i][j][0]);
;             v[1] = bf2f((bf16_t)(ov.x >> 16)) * silu_f(acc[i][j][1]);
;             v[2] = bf2f((bf16_t)(ov.y & 0xffff)) * silu_f(acc[i][j][2]);
;             v[3] = bf2f((bf16_t)(ov.y >> 16)) * silu_f(acc[i][j][3]);
.LBB0_861:
	s_andn2_b64 vcc, exec, s[2:3]
	s_cbranch_vccnz .LBB0_863
	v_pk_add_f32 v[68:69], v[68:69], 1.0 op_sel_hi:[1,0]
	v_pk_add_f32 v[66:67], v[66:67], 1.0 op_sel_hi:[1,0]
	v_div_scale_f32 v0, s[2:3], v69, v69, v59
	v_rcp_f32_e32 v72, v0
	s_waitcnt vmcnt(7)
	v_lshlrev_b32_e32 v62, 16, v222
	v_fma_f32 v73, -v0, v72, 1.0
	v_fmac_f32_e32 v72, v73, v72
	v_div_scale_f32 v73, vcc, v59, v69, v59
	v_mul_f32_e32 v74, v73, v72
	v_fma_f32 v75, -v0, v74, v73
	v_fmac_f32_e32 v74, v75, v72
	v_fma_f32 v0, -v0, v74, v73
	v_div_fmas_f32 v0, v0, v72, v74
	v_div_fixup_f32 v59, v0, v69, v59
	v_div_scale_f32 v0, s[2:3], v68, v68, v58
	v_rcp_f32_e32 v69, v0
	v_and_b32_e32 v63, 0xffff0000, v222
	v_lshlrev_b32_e32 v64, 16, v223
	v_and_b32_e32 v65, 0xffff0000, v223
	v_fma_f32 v72, -v0, v69, 1.0
	v_fmac_f32_e32 v69, v72, v69
	v_div_scale_f32 v72, vcc, v58, v68, v58
	v_mul_f32_e32 v73, v72, v69
	v_fma_f32 v74, -v0, v73, v72
	v_fmac_f32_e32 v73, v74, v69
	v_fma_f32 v0, -v0, v73, v72
	v_div_fmas_f32 v0, v0, v69, v73
	v_div_fixup_f32 v58, v0, v68, v58
	v_div_scale_f32 v0, s[2:3], v67, v67, v61
	v_rcp_f32_e32 v68, v0
	v_pk_mul_f32 v[62:63], v[58:59], v[62:63]
	v_fma_f32 v69, -v0, v68, 1.0
	v_fmac_f32_e32 v68, v69, v68
	v_div_scale_f32 v69, vcc, v61, v67, v61
	v_mul_f32_e32 v72, v69, v68
	v_fma_f32 v73, -v0, v72, v69
	v_fmac_f32_e32 v72, v73, v68
	v_fma_f32 v0, -v0, v72, v69
	v_div_fmas_f32 v0, v0, v68, v72
	v_div_fixup_f32 v61, v0, v67, v61
	v_div_scale_f32 v0, s[2:3], v66, v66, v60
	v_rcp_f32_e32 v67, v0
	s_nop 0
	v_fma_f32 v68, -v0, v67, 1.0
	v_fmac_f32_e32 v67, v68, v67
	v_div_scale_f32 v68, vcc, v60, v66, v60
	v_mul_f32_e32 v69, v68, v67
	v_fma_f32 v72, -v0, v69, v68
	v_fmac_f32_e32 v69, v72, v67
	v_fma_f32 v0, -v0, v69, v68
	v_div_fmas_f32 v0, v0, v67, v69
	v_div_fixup_f32 v60, v0, v66, v60
	v_pk_mul_f32 v[64:65], v[60:61], v[64:65]

; DEV float bf2f(bf16_t h) { return __uint_as_float(((unsigned)h) << 16); }
; DEV float silu_f(float x) { return x / (1.f + __expf(-x)); }
; DEV void phase_G(const Params& p, int b, unsigned char* ldsraw) {
;     ...
;           if (gate) {
;             uint2 ov = *(const uint2*)d;
;             v[0] = bf2f((bf16_t)(ov.x & 0xffff)) * silu_f(acc[i][j][0]);
;             v[1] = bf2f((bf16_t)(ov.x >> 16)) * silu_f(acc[i][j][1]);
;             v[2] = bf2f((bf16_t)(ov.y & 0xffff)) * silu_f(acc[i][j][2]);
;             v[3] = bf2f((bf16_t)(ov.y >> 16)) * silu_f(acc[i][j][3]);
.LBB0_865:
	s_andn2_b64 vcc, exec, s[2:3]
	s_cbranch_vccnz .LBB0_867
	v_pk_add_f32 v[64:65], v[64:65], 1.0 op_sel_hi:[1,0]
	v_pk_add_f32 v[62:63], v[62:63], 1.0 op_sel_hi:[1,0]
	v_div_scale_f32 v0, s[2:3], v65, v65, v55
	v_rcp_f32_e32 v66, v0
	s_waitcnt vmcnt(7)
	v_lshlrev_b32_e32 v58, 16, v224
	v_fma_f32 v67, -v0, v66, 1.0
	v_fmac_f32_e32 v66, v67, v66
	v_div_scale_f32 v67, vcc, v55, v65, v55
	v_mul_f32_e32 v68, v67, v66
	v_fma_f32 v69, -v0, v68, v67
	v_fmac_f32_e32 v68, v69, v66
	v_fma_f32 v0, -v0, v68, v67
	v_div_fmas_f32 v0, v0, v66, v68
	v_div_fixup_f32 v55, v0, v65, v55
	v_div_scale_f32 v0, s[2:3], v64, v64, v54
	v_rcp_f32_e32 v65, v0
	v_and_b32_e32 v59, 0xffff0000, v224
	v_lshlrev_b32_e32 v60, 16, v225
	v_and_b32_e32 v61, 0xffff0000, v225
	v_fma_f32 v66, -v0, v65, 1.0
	v_fmac_f32_e32 v65, v66, v65
	v_div_scale_f32 v66, vcc, v54, v64, v54
	v_mul_f32_e32 v67, v66, v65
	v_fma_f32 v68, -v0, v67, v66
	v_fmac_f32_e32 v67, v68, v65
	v_fma_f32 v0, -v0, v67, v66
	v_div_fmas_f32 v0, v0, v65, v67
	v_div_fixup_f32 v54, v0, v64, v54
	v_div_scale_f32 v0, s[2:3], v63, v63, v57
	v_rcp_f32_e32 v64, v0
	v_pk_mul_f32 v[58:59], v[54:55], v[58:59]
	v_fma_f32 v65, -v0, v64, 1.0
	v_fmac_f32_e32 v64, v65, v64
	v_div_scale_f32 v65, vcc, v57, v63, v57
	v_mul_f32_e32 v66, v65, v64
	v_fma_f32 v67, -v0, v66, v65
	v_fmac_f32_e32 v66, v67, v64
	v_fma_f32 v0, -v0, v66, v65
	v_div_fmas_f32 v0, v0, v64, v66
	v_div_fixup_f32 v57, v0, v63, v57
	v_div_scale_f32 v0, s[2:3], v62, v62, v56
	v_rcp_f32_e32 v63, v0
	s_nop 0
	v_fma_f32 v64, -v0, v63, 1.0
	v_fmac_f32_e32 v63, v64, v63
	v_div_scale_f32 v64, vcc, v56, v62, v56
	v_mul_f32_e32 v65, v64, v63
	v_fma_f32 v66, -v0, v65, v64
	v_fmac_f32_e32 v65, v66, v63
	v_fma_f32 v0, -v0, v65, v64
	v_div_fmas_f32 v0, v0, v63, v65
	v_div_fixup_f32 v56, v0, v62, v56
	v_pk_mul_f32 v[60:61], v[56:57], v[60:61]

; DEV float bf2f(bf16_t h) { return __uint_as_float(((unsigned)h) << 16); }
; DEV float silu_f(float x) { return x / (1.f + __expf(-x)); }
; DEV void phase_G(const Params& p, int b, unsigned char* ldsraw) {
;     ...
;           if (gate) {
;             uint2 ov = *(const uint2*)d;
;             v[0] = bf2f((bf16_t)(ov.x & 0xffff)) * silu_f(acc[i][j][0]);
;             v[1] = bf2f((bf16_t)(ov.x >> 16)) * silu_f(acc[i][j][1]);
;             v[2] = bf2f((bf16_t)(ov.y & 0xffff)) * silu_f(acc[i][j][2]);
;             v[3] = bf2f((bf16_t)(ov.y >> 16)) * silu_f(acc[i][j][3]);
.LBB0_869:
	s_andn2_b64 vcc, exec, s[2:3]
	s_cbranch_vccnz .LBB0_871
	v_pk_add_f32 v[60:61], v[60:61], 1.0 op_sel_hi:[1,0]
	v_pk_add_f32 v[58:59], v[58:59], 1.0 op_sel_hi:[1,0]
	v_div_scale_f32 v0, s[2:3], v61, v61, v51
	v_rcp_f32_e32 v62, v0
	s_waitcnt vmcnt(7)
	v_lshlrev_b32_e32 v54, 16, v226
	v_fma_f32 v63, -v0, v62, 1.0
	v_fmac_f32_e32 v62, v63, v62
	v_div_scale_f32 v63, vcc, v51, v61, v51
	v_mul_f32_e32 v64, v63, v62
	v_fma_f32 v65, -v0, v64, v63
	v_fmac_f32_e32 v64, v65, v62
	v_fma_f32 v0, -v0, v64, v63
	v_div_fmas_f32 v0, v0, v62, v64
	v_div_fixup_f32 v51, v0, v61, v51
	v_div_scale_f32 v0, s[2:3], v60, v60, v50
	v_rcp_f32_e32 v61, v0
	v_and_b32_e32 v55, 0xffff0000, v226
	v_lshlrev_b32_e32 v56, 16, v227
	v_and_b32_e32 v57, 0xffff0000, v227
	v_fma_f32 v62, -v0, v61, 1.0
	v_fmac_f32_e32 v61, v62, v61
	v_div_scale_f32 v62, vcc, v50, v60, v50
	v_mul_f32_e32 v63, v62, v61
	v_fma_f32 v64, -v0, v63, v62
	v_fmac_f32_e32 v63, v64, v61
	v_fma_f32 v0, -v0, v63, v62
	v_div_fmas_f32 v0, v0, v61, v63
	v_div_fixup_f32 v50, v0, v60, v50
	v_div_scale_f32 v0, s[2:3], v59, v59, v53
	v_rcp_f32_e32 v60, v0
	v_pk_mul_f32 v[54:55], v[50:51], v[54:55]
	v_fma_f32 v61, -v0, v60, 1.0
	v_fmac_f32_e32 v60, v61, v60
	v_div_scale_f32 v61, vcc, v53, v59, v53
	v_mul_f32_e32 v62, v61, v60
	v_fma_f32 v63, -v0, v62, v61
	v_fmac_f32_e32 v62, v63, v60
	v_fma_f32 v0, -v0, v62, v61
	v_div_fmas_f32 v0, v0, v60, v62
	v_div_fixup_f32 v53, v0, v59, v53
	v_div_scale_f32 v0, s[2:3], v58, v58, v52
	v_rcp_f32_e32 v59, v0
	s_nop 0
	v_fma_f32 v60, -v0, v59, 1.0
	v_fmac_f32_e32 v59, v60, v59
	v_div_scale_f32 v60, vcc, v52, v58, v52
	v_mul_f32_e32 v61, v60, v59
	v_fma_f32 v62, -v0, v61, v60
	v_fmac_f32_e32 v61, v62, v59
	v_fma_f32 v0, -v0, v61, v60
	v_div_fmas_f32 v0, v0, v59, v61
	v_div_fixup_f32 v52, v0, v58, v52
	v_pk_mul_f32 v[56:57], v[52:53], v[56:57]

; DEV float bf2f(bf16_t h) { return __uint_as_float(((unsigned)h) << 16); }
; DEV float silu_f(float x) { return x / (1.f + __expf(-x)); }
; DEV void phase_G(const Params& p, int b, unsigned char* ldsraw) {
;     ...
;           if (gate) {
;             uint2 ov = *(const uint2*)d;
;             v[0] = bf2f((bf16_t)(ov.x & 0xffff)) * silu_f(acc[i][j][0]);
;             v[1] = bf2f((bf16_t)(ov.x >> 16)) * silu_f(acc[i][j][1]);
;             v[2] = bf2f((bf16_t)(ov.y & 0xffff)) * silu_f(acc[i][j][2]);
;             v[3] = bf2f((bf16_t)(ov.y >> 16)) * silu_f(acc[i][j][3]);
.LBB0_873:
	s_andn2_b64 vcc, exec, s[2:3]
	s_cbranch_vccnz .LBB0_875
	v_pk_add_f32 v[56:57], v[56:57], 1.0 op_sel_hi:[1,0]
	v_pk_add_f32 v[54:55], v[54:55], 1.0 op_sel_hi:[1,0]
	v_div_scale_f32 v0, s[2:3], v57, v57, v47
	v_rcp_f32_e32 v58, v0
	s_waitcnt vmcnt(7)
	v_lshlrev_b32_e32 v50, 16, v228
	v_fma_f32 v59, -v0, v58, 1.0
	v_fmac_f32_e32 v58, v59, v58
	v_div_scale_f32 v59, vcc, v47, v57, v47
	v_mul_f32_e32 v60, v59, v58
	v_fma_f32 v61, -v0, v60, v59
	v_fmac_f32_e32 v60, v61, v58
	v_fma_f32 v0, -v0, v60, v59
	v_div_fmas_f32 v0, v0, v58, v60
	v_div_fixup_f32 v47, v0, v57, v47
	v_div_scale_f32 v0, s[2:3], v56, v56, v46
	v_rcp_f32_e32 v57, v0
	v_and_b32_e32 v51, 0xffff0000, v228
	v_lshlrev_b32_e32 v52, 16, v229
	v_and_b32_e32 v53, 0xffff0000, v229
	v_fma_f32 v58, -v0, v57, 1.0
	v_fmac_f32_e32 v57, v58, v57
	v_div_scale_f32 v58, vcc, v46, v56, v46
	v_mul_f32_e32 v59, v58, v57
	v_fma_f32 v60, -v0, v59, v58
	v_fmac_f32_e32 v59, v60, v57
	v_fma_f32 v0, -v0, v59, v58
	v_div_fmas_f32 v0, v0, v57, v59
	v_div_fixup_f32 v46, v0, v56, v46
	v_div_scale_f32 v0, s[2:3], v55, v55, v49
	v_rcp_f32_e32 v56, v0
	v_pk_mul_f32 v[50:51], v[46:47], v[50:51]
	v_fma_f32 v57, -v0, v56, 1.0
	v_fmac_f32_e32 v56, v57, v56
	v_div_scale_f32 v57, vcc, v49, v55, v49
	v_mul_f32_e32 v58, v57, v56
	v_fma_f32 v59, -v0, v58, v57
	v_fmac_f32_e32 v58, v59, v56
	v_fma_f32 v0, -v0, v58, v57
	v_div_fmas_f32 v0, v0, v56, v58
	v_div_fixup_f32 v49, v0, v55, v49
	v_div_scale_f32 v0, s[2:3], v54, v54, v48
	v_rcp_f32_e32 v55, v0
	s_nop 0
	v_fma_f32 v56, -v0, v55, 1.0
	v_fmac_f32_e32 v55, v56, v55
	v_div_scale_f32 v56, vcc, v48, v54, v48
	v_mul_f32_e32 v57, v56, v55
	v_fma_f32 v58, -v0, v57, v56
	v_fmac_f32_e32 v57, v58, v55
	v_fma_f32 v0, -v0, v57, v56
	v_div_fmas_f32 v0, v0, v55, v57
	v_div_fixup_f32 v48, v0, v54, v48
	v_pk_mul_f32 v[52:53], v[48:49], v[52:53]

; DEV float bf2f(bf16_t h) { return __uint_as_float(((unsigned)h) << 16); }
; DEV float silu_f(float x) { return x / (1.f + __expf(-x)); }
; DEV void phase_G(const Params& p, int b, unsigned char* ldsraw) {
;     ...
;           if (gate) {
;             uint2 ov = *(const uint2*)d;
;             v[0] = bf2f((bf16_t)(ov.x & 0xffff)) * silu_f(acc[i][j][0]);
;             v[1] = bf2f((bf16_t)(ov.x >> 16)) * silu_f(acc[i][j][1]);
;             v[2] = bf2f((bf16_t)(ov.y & 0xffff)) * silu_f(acc[i][j][2]);
;             v[3] = bf2f((bf16_t)(ov.y >> 16)) * silu_f(acc[i][j][3]);
.LBB0_877:
	s_andn2_b64 vcc, exec, s[2:3]
	s_cbranch_vccnz .LBB0_879
	v_pk_add_f32 v[52:53], v[52:53], 1.0 op_sel_hi:[1,0]
	v_pk_add_f32 v[50:51], v[50:51], 1.0 op_sel_hi:[1,0]
	v_div_scale_f32 v0, s[2:3], v53, v53, v43
	v_rcp_f32_e32 v54, v0
	s_waitcnt vmcnt(7)
	v_lshlrev_b32_e32 v46, 16, v230
	v_fma_f32 v55, -v0, v54, 1.0
	v_fmac_f32_e32 v54, v55, v54
	v_div_scale_f32 v55, vcc, v43, v53, v43
	v_mul_f32_e32 v56, v55, v54
	v_fma_f32 v57, -v0, v56, v55
	v_fmac_f32_e32 v56, v57, v54
	v_fma_f32 v0, -v0, v56, v55
	v_div_fmas_f32 v0, v0, v54, v56
	v_div_fixup_f32 v43, v0, v53, v43
	v_div_scale_f32 v0, s[2:3], v52, v52, v42
	v_rcp_f32_e32 v53, v0
	v_and_b32_e32 v47, 0xffff0000, v230
	v_lshlrev_b32_e32 v48, 16, v231
	v_and_b32_e32 v49, 0xffff0000, v231
	v_fma_f32 v54, -v0, v53, 1.0
	v_fmac_f32_e32 v53, v54, v53
	v_div_scale_f32 v54, vcc, v42, v52, v42
	v_mul_f32_e32 v55, v54, v53
	v_fma_f32 v56, -v0, v55, v54
	v_fmac_f32_e32 v55, v56, v53
	v_fma_f32 v0, -v0, v55, v54
	v_div_fmas_f32 v0, v0, v53, v55
	v_div_fixup_f32 v42, v0, v52, v42
	v_div_scale_f32 v0, s[2:3], v51, v51, v45
	v_rcp_f32_e32 v52, v0
	v_pk_mul_f32 v[46:47], v[42:43], v[46:47]
	v_fma_f32 v53, -v0, v52, 1.0
	v_fmac_f32_e32 v52, v53, v52
	v_div_scale_f32 v53, vcc, v45, v51, v45
	v_mul_f32_e32 v54, v53, v52
	v_fma_f32 v55, -v0, v54, v53
	v_fmac_f32_e32 v54, v55, v52
	v_fma_f32 v0, -v0, v54, v53
	v_div_fmas_f32 v0, v0, v52, v54
	v_div_fixup_f32 v45, v0, v51, v45
	v_div_scale_f32 v0, s[2:3], v50, v50, v44
	v_rcp_f32_e32 v51, v0
	s_nop 0
	v_fma_f32 v52, -v0, v51, 1.0
	v_fmac_f32_e32 v51, v52, v51
	v_div_scale_f32 v52, vcc, v44, v50, v44
	v_mul_f32_e32 v53, v52, v51
	v_fma_f32 v54, -v0, v53, v52
	v_fmac_f32_e32 v53, v54, v51
	v_fma_f32 v0, -v0, v53, v52
	v_div_fmas_f32 v0, v0, v51, v53
	v_div_fixup_f32 v44, v0, v50, v44
	v_pk_mul_f32 v[48:49], v[44:45], v[48:49]

; DEV float bf2f(bf16_t h) { return __uint_as_float(((unsigned)h) << 16); }
; DEV float silu_f(float x) { return x / (1.f + __expf(-x)); }
; DEV void phase_G(const Params& p, int b, unsigned char* ldsraw) {
;     ...
;           if (gate) {
;             uint2 ov = *(const uint2*)d;
;             v[0] = bf2f((bf16_t)(ov.x & 0xffff)) * silu_f(acc[i][j][0]);
;             v[1] = bf2f((bf16_t)(ov.x >> 16)) * silu_f(acc[i][j][1]);
;             v[2] = bf2f((bf16_t)(ov.y & 0xffff)) * silu_f(acc[i][j][2]);
;             v[3] = bf2f((bf16_t)(ov.y >> 16)) * silu_f(acc[i][j][3]);
.LBB0_881:
	s_andn2_b64 vcc, exec, s[2:3]
	s_cbranch_vccnz .LBB0_883
	v_pk_add_f32 v[48:49], v[48:49], 1.0 op_sel_hi:[1,0]
	v_pk_add_f32 v[46:47], v[46:47], 1.0 op_sel_hi:[1,0]
	v_div_scale_f32 v0, s[2:3], v49, v49, v39
	v_rcp_f32_e32 v50, v0
	s_waitcnt vmcnt(7)
	v_lshlrev_b32_e32 v42, 16, v232
	v_fma_f32 v51, -v0, v50, 1.0
	v_fmac_f32_e32 v50, v51, v50
	v_div_scale_f32 v51, vcc, v39, v49, v39
	v_mul_f32_e32 v52, v51, v50
	v_fma_f32 v53, -v0, v52, v51
	v_fmac_f32_e32 v52, v53, v50
	v_fma_f32 v0, -v0, v52, v51
	v_div_fmas_f32 v0, v0, v50, v52
	v_div_fixup_f32 v39, v0, v49, v39
	v_div_scale_f32 v0, s[2:3], v48, v48, v38
	v_rcp_f32_e32 v49, v0
	v_and_b32_e32 v43, 0xffff0000, v232
	v_lshlrev_b32_e32 v44, 16, v233
	v_and_b32_e32 v45, 0xffff0000, v233
	v_fma_f32 v50, -v0, v49, 1.0
	v_fmac_f32_e32 v49, v50, v49
	v_div_scale_f32 v50, vcc, v38, v48, v38
	v_mul_f32_e32 v51, v50, v49
	v_fma_f32 v52, -v0, v51, v50
	v_fmac_f32_e32 v51, v52, v49
	v_fma_f32 v0, -v0, v51, v50
	v_div_fmas_f32 v0, v0, v49, v51
	v_div_fixup_f32 v38, v0, v48, v38
	v_div_scale_f32 v0, s[2:3], v47, v47, v41
	v_rcp_f32_e32 v48, v0
	v_pk_mul_f32 v[42:43], v[38:39], v[42:43]
	v_fma_f32 v49, -v0, v48, 1.0
	v_fmac_f32_e32 v48, v49, v48
	v_div_scale_f32 v49, vcc, v41, v47, v41
	v_mul_f32_e32 v50, v49, v48
	v_fma_f32 v51, -v0, v50, v49
	v_fmac_f32_e32 v50, v51, v48
	v_fma_f32 v0, -v0, v50, v49
	v_div_fmas_f32 v0, v0, v48, v50
	v_div_fixup_f32 v41, v0, v47, v41
	v_div_scale_f32 v0, s[2:3], v46, v46, v40
	v_rcp_f32_e32 v47, v0
	s_nop 0
	v_fma_f32 v48, -v0, v47, 1.0
	v_fmac_f32_e32 v47, v48, v47
	v_div_scale_f32 v48, vcc, v40, v46, v40
	v_mul_f32_e32 v49, v48, v47
	v_fma_f32 v50, -v0, v49, v48
	v_fmac_f32_e32 v49, v50, v47
	v_fma_f32 v0, -v0, v49, v48
	v_div_fmas_f32 v0, v0, v47, v49
	v_div_fixup_f32 v40, v0, v46, v40
	v_pk_mul_f32 v[44:45], v[40:41], v[44:45]

; DEV float bf2f(bf16_t h) { return __uint_as_float(((unsigned)h) << 16); }
; DEV float silu_f(float x) { return x / (1.f + __expf(-x)); }
; DEV void phase_G(const Params& p, int b, unsigned char* ldsraw) {
;     ...
;           if (gate) {
;             uint2 ov = *(const uint2*)d;
;             v[0] = bf2f((bf16_t)(ov.x & 0xffff)) * silu_f(acc[i][j][0]);
;             v[1] = bf2f((bf16_t)(ov.x >> 16)) * silu_f(acc[i][j][1]);
;             v[2] = bf2f((bf16_t)(ov.y & 0xffff)) * silu_f(acc[i][j][2]);
;             v[3] = bf2f((bf16_t)(ov.y >> 16)) * silu_f(acc[i][j][3]);
.LBB0_885:
	s_andn2_b64 vcc, exec, s[2:3]
	s_cbranch_vccnz .LBB0_887
	v_pk_add_f32 v[44:45], v[44:45], 1.0 op_sel_hi:[1,0]
	v_pk_add_f32 v[42:43], v[42:43], 1.0 op_sel_hi:[1,0]
	v_div_scale_f32 v0, s[2:3], v45, v45, v35
	v_rcp_f32_e32 v46, v0
	s_waitcnt vmcnt(7)
	v_lshlrev_b32_e32 v38, 16, v234
	v_fma_f32 v47, -v0, v46, 1.0
	v_fmac_f32_e32 v46, v47, v46
	v_div_scale_f32 v47, vcc, v35, v45, v35
	v_mul_f32_e32 v48, v47, v46
	v_fma_f32 v49, -v0, v48, v47
	v_fmac_f32_e32 v48, v49, v46
	v_fma_f32 v0, -v0, v48, v47
	v_div_fmas_f32 v0, v0, v46, v48
	v_div_fixup_f32 v35, v0, v45, v35
	v_div_scale_f32 v0, s[2:3], v44, v44, v34
	v_rcp_f32_e32 v45, v0
	v_and_b32_e32 v39, 0xffff0000, v234
	v_lshlrev_b32_e32 v40, 16, v235
	v_and_b32_e32 v41, 0xffff0000, v235
	v_fma_f32 v46, -v0, v45, 1.0
	v_fmac_f32_e32 v45, v46, v45
	v_div_scale_f32 v46, vcc, v34, v44, v34
	v_mul_f32_e32 v47, v46, v45
	v_fma_f32 v48, -v0, v47, v46
	v_fmac_f32_e32 v47, v48, v45
	v_fma_f32 v0, -v0, v47, v46
	v_div_fmas_f32 v0, v0, v45, v47
	v_div_fixup_f32 v34, v0, v44, v34
	v_div_scale_f32 v0, s[2:3], v43, v43, v37
	v_rcp_f32_e32 v44, v0
	v_pk_mul_f32 v[38:39], v[34:35], v[38:39]
	v_fma_f32 v45, -v0, v44, 1.0
	v_fmac_f32_e32 v44, v45, v44
	v_div_scale_f32 v45, vcc, v37, v43, v37
	v_mul_f32_e32 v46, v45, v44
	v_fma_f32 v47, -v0, v46, v45
	v_fmac_f32_e32 v46, v47, v44
	v_fma_f32 v0, -v0, v46, v45
	v_div_fmas_f32 v0, v0, v44, v46
	v_div_fixup_f32 v37, v0, v43, v37
	v_div_scale_f32 v0, s[2:3], v42, v42, v36
	v_rcp_f32_e32 v43, v0
	s_nop 0
	v_fma_f32 v44, -v0, v43, 1.0
	v_fmac_f32_e32 v43, v44, v43
	v_div_scale_f32 v44, vcc, v36, v42, v36
	v_mul_f32_e32 v45, v44, v43
	v_fma_f32 v46, -v0, v45, v44
	v_fmac_f32_e32 v45, v46, v43
	v_fma_f32 v0, -v0, v45, v44
	v_div_fmas_f32 v0, v0, v43, v45
	v_div_fixup_f32 v36, v0, v42, v36
	v_pk_mul_f32 v[40:41], v[36:37], v[40:41]

; DEV float bf2f(bf16_t h) { return __uint_as_float(((unsigned)h) << 16); }
; DEV float silu_f(float x) { return x / (1.f + __expf(-x)); }
; DEV void phase_G(const Params& p, int b, unsigned char* ldsraw) {
;     ...
;     for (int i = 0; i < 4; i++) {
;       const int t = mt * 256 + wm * 64 + i * 16 + lr;
;       if (t < LT) {
; #pragma unroll
;         for (int j = 0; j < 8; j++) {
;           bf16_t* d = dst + (size_t)t * ld + cb + wn * 128 + j * 16 + lg * 4;
;           f32x4 v;
;           if (gate) {
;             uint2 ov = *(const uint2*)d;
;             v[0] = bf2f((bf16_t)(ov.x & 0xffff)) * silu_f(acc[i][j][0]);
;             v[1] = bf2f((bf16_t)(ov.x >> 16)) * silu_f(acc[i][j][1]);
;             v[2] = bf2f((bf16_t)(ov.y & 0xffff)) * silu_f(acc[i][j][2]);
;             v[3] = bf2f((bf16_t)(ov.y >> 16)) * silu_f(acc[i][j][3]);
.LBB0_891:
	v_ashrrev_i32_e32 v38, 31, v0
	v_mul_lo_u32 v44, s1, v0
	v_mul_lo_u32 v45, s0, v38
	v_mad_u64_u32 v[38:39], s[0:1], s0, v0, 0
	v_add3_u32 v39, v39, v45, v44
	s_andn2_b64 vcc, exec, s[2:3]
	v_lshl_add_u64 v[38:39], v[38:39], 1, v[134:135]
	s_cbranch_vccnz .Lgskip_3
	global_load_dwordx2 v[220:221], v[38:39], off
	global_load_dwordx2 v[222:223], v[38:39], off offset:32
	global_load_dwordx2 v[224:225], v[38:39], off offset:64
	global_load_dwordx2 v[226:227], v[38:39], off offset:96
	global_load_dwordx2 v[228:229], v[38:39], off offset:128
	global_load_dwordx2 v[230:231], v[38:39], off offset:160
	global_load_dwordx2 v[232:233], v[38:39], off offset:192
	global_load_dwordx2 v[234:235], v[38:39], off offset:224
.Lgskip_3:
	s_cbranch_vccnz .LBB0_893
	v_pk_add_f32 v[42:43], v[42:43], 1.0 op_sel_hi:[1,0]
	v_pk_add_f32 v[40:41], v[40:41], 1.0 op_sel_hi:[1,0]
	v_div_scale_f32 v0, s[0:1], v43, v43, v31
	v_rcp_f32_e32 v44, v0
	s_waitcnt vmcnt(7)
	v_lshlrev_b32_e32 v34, 16, v220
	v_fma_f32 v45, -v0, v44, 1.0
	v_fmac_f32_e32 v44, v45, v44
	v_div_scale_f32 v45, vcc, v31, v43, v31
	v_mul_f32_e32 v46, v45, v44
	v_fma_f32 v47, -v0, v46, v45
	v_fmac_f32_e32 v46, v47, v44
	v_fma_f32 v0, -v0, v46, v45
	v_div_fmas_f32 v0, v0, v44, v46
	v_div_fixup_f32 v31, v0, v43, v31
	v_div_scale_f32 v0, s[0:1], v42, v42, v30
	v_rcp_f32_e32 v43, v0
	v_and_b32_e32 v35, 0xffff0000, v220
	v_lshlrev_b32_e32 v36, 16, v221
	v_and_b32_e32 v37, 0xffff0000, v221
	v_fma_f32 v44, -v0, v43, 1.0
	v_fmac_f32_e32 v43, v44, v43
	v_div_scale_f32 v44, vcc, v30, v42, v30
	v_mul_f32_e32 v45, v44, v43
	v_fma_f32 v46, -v0, v45, v44
	v_fmac_f32_e32 v45, v46, v43
	v_fma_f32 v0, -v0, v45, v44
	v_div_fmas_f32 v0, v0, v43, v45
	v_div_fixup_f32 v30, v0, v42, v30
	v_div_scale_f32 v0, s[0:1], v41, v41, v33
	v_rcp_f32_e32 v42, v0
	v_pk_mul_f32 v[34:35], v[30:31], v[34:35]
	v_fma_f32 v43, -v0, v42, 1.0
	v_fmac_f32_e32 v42, v43, v42
	v_div_scale_f32 v43, vcc, v33, v41, v33
	v_mul_f32_e32 v44, v43, v42
	v_fma_f32 v45, -v0, v44, v43
	v_fmac_f32_e32 v44, v45, v42
	v_fma_f32 v0, -v0, v44, v43
	v_div_fmas_f32 v0, v0, v42, v44
	v_div_fixup_f32 v33, v0, v41, v33
	v_div_scale_f32 v0, s[0:1], v40, v40, v32
	v_rcp_f32_e32 v41, v0
	s_nop 0
	v_fma_f32 v42, -v0, v41, 1.0
	v_fmac_f32_e32 v41, v42, v41
	v_div_scale_f32 v42, vcc, v32, v40, v32
	v_mul_f32_e32 v43, v42, v41
	v_fma_f32 v44, -v0, v43, v42
	v_fmac_f32_e32 v43, v44, v41
	v_fma_f32 v0, -v0, v43, v42
	v_div_fmas_f32 v0, v0, v41, v43
	v_div_fixup_f32 v32, v0, v40, v32
	v_pk_mul_f32 v[36:37], v[32:33], v[36:37]

; DEV float bf2f(bf16_t h) { return __uint_as_float(((unsigned)h) << 16); }
; DEV uint2 pack4(f32x4 v) { uint2 r; r.x = pack2(v[0], v[1]); r.y = pack2(v[2], v[3]); return r; }
; DEV float sigmoid_f(float x) { return 1.f / (1.f + __expf(-x)); }
; DEV float silu_f(float x) { return x / (1.f + __expf(-x)); }
; DEV void phase_G(const Params& p, int b, unsigned char* ldsraw) {
;     ...
;         for (int j = 0; j < 8; j++) {
;           bf16_t* d = dst + (size_t)t * ld + cb + wn * 128 + j * 16 + lg * 4;
;           f32x4 v;
;           if (gate) {
;             uint2 ov = *(const uint2*)d;
;             v[0] = bf2f((bf16_t)(ov.x & 0xffff)) * silu_f(acc[i][j][0]);
;             v[1] = bf2f((bf16_t)(ov.x >> 16)) * silu_f(acc[i][j][1]);
;             v[2] = bf2f((bf16_t)(ov.y & 0xffff)) * silu_f(acc[i][j][2]);
;             v[3] = bf2f((bf16_t)(ov.y >> 16)) * silu_f(acc[i][j][3]);
;           } else {
; #pragma unroll
;             for (int r = 0; r < 4; r++) v[r] = sigmoid_f(acc[i][j][r]);
;           }
;           *(uint2*)d = pack4(v);
;         }
.LBB0_895:
	s_andn2_b64 vcc, exec, s[0:1]
	s_cbranch_vccnz .LBB0_897
	v_pk_add_f32 v[36:37], v[36:37], 1.0 op_sel_hi:[1,0]
	v_pk_add_f32 v[34:35], v[34:35], 1.0 op_sel_hi:[1,0]
	v_div_scale_f32 v0, s[0:1], v37, v37, v27
	v_rcp_f32_e32 v40, v0
	s_waitcnt vmcnt(7)
	v_lshlrev_b32_e32 v30, 16, v222
	v_fma_f32 v41, -v0, v40, 1.0
	v_fmac_f32_e32 v40, v41, v40
	v_div_scale_f32 v41, vcc, v27, v37, v27
	v_mul_f32_e32 v42, v41, v40
	v_fma_f32 v43, -v0, v42, v41
	v_fmac_f32_e32 v42, v43, v40
	v_fma_f32 v0, -v0, v42, v41
	v_div_fmas_f32 v0, v0, v40, v42
	v_div_fixup_f32 v27, v0, v37, v27
	v_div_scale_f32 v0, s[0:1], v36, v36, v26
	v_rcp_f32_e32 v37, v0
	v_and_b32_e32 v31, 0xffff0000, v222
	v_lshlrev_b32_e32 v32, 16, v223
	v_and_b32_e32 v33, 0xffff0000, v223
	v_fma_f32 v40, -v0, v37, 1.0
	v_fmac_f32_e32 v37, v40, v37
	v_div_scale_f32 v40, vcc, v26, v36, v26
	v_mul_f32_e32 v41, v40, v37
	v_fma_f32 v42, -v0, v41, v40
	v_fmac_f32_e32 v41, v42, v37
	v_fma_f32 v0, -v0, v41, v40
	v_div_fmas_f32 v0, v0, v37, v41
	v_div_fixup_f32 v26, v0, v36, v26
	v_div_scale_f32 v0, s[0:1], v35, v35, v29
	v_rcp_f32_e32 v36, v0
	v_pk_mul_f32 v[30:31], v[26:27], v[30:31]
	v_fma_f32 v37, -v0, v36, 1.0
	v_fmac_f32_e32 v36, v37, v36
	v_div_scale_f32 v37, vcc, v29, v35, v29
	v_mul_f32_e32 v40, v37, v36
	v_fma_f32 v41, -v0, v40, v37
	v_fmac_f32_e32 v40, v41, v36
	v_fma_f32 v0, -v0, v40, v37
	v_div_fmas_f32 v0, v0, v36, v40
	v_div_fixup_f32 v29, v0, v35, v29
	v_div_scale_f32 v0, s[0:1], v34, v34, v28
	v_rcp_f32_e32 v35, v0
	s_nop 0
	v_fma_f32 v36, -v0, v35, 1.0
	v_fmac_f32_e32 v35, v36, v35
	v_div_scale_f32 v36, vcc, v28, v34, v28
	v_mul_f32_e32 v37, v36, v35
	v_fma_f32 v40, -v0, v37, v36
	v_fmac_f32_e32 v37, v40, v35
	v_fma_f32 v0, -v0, v37, v36
	v_div_fmas_f32 v0, v0, v35, v37
	v_div_fixup_f32 v28, v0, v34, v28
	v_pk_mul_f32 v[32:33], v[28:29], v[32:33]

; DEV float bf2f(bf16_t h) { return __uint_as_float(((unsigned)h) << 16); }
; DEV uint2 pack4(f32x4 v) { uint2 r; r.x = pack2(v[0], v[1]); r.y = pack2(v[2], v[3]); return r; }
; DEV float sigmoid_f(float x) { return 1.f / (1.f + __expf(-x)); }
; DEV float silu_f(float x) { return x / (1.f + __expf(-x)); }
; DEV void phase_G(const Params& p, int b, unsigned char* ldsraw) {
;     ...
;         for (int j = 0; j < 8; j++) {
;           bf16_t* d = dst + (size_t)t * ld + cb + wn * 128 + j * 16 + lg * 4;
;           f32x4 v;
;           if (gate) {
;             uint2 ov = *(const uint2*)d;
;             v[0] = bf2f((bf16_t)(ov.x & 0xffff)) * silu_f(acc[i][j][0]);
;             v[1] = bf2f((bf16_t)(ov.x >> 16)) * silu_f(acc[i][j][1]);
;             v[2] = bf2f((bf16_t)(ov.y & 0xffff)) * silu_f(acc[i][j][2]);
;             v[3] = bf2f((bf16_t)(ov.y >> 16)) * silu_f(acc[i][j][3]);
;           } else {
; #pragma unroll
;             for (int r = 0; r < 4; r++) v[r] = sigmoid_f(acc[i][j][r]);
;           }
;           *(uint2*)d = pack4(v);
;         }
.LBB0_899:
	s_andn2_b64 vcc, exec, s[0:1]
	s_cbranch_vccnz .LBB0_901
	v_pk_add_f32 v[32:33], v[32:33], 1.0 op_sel_hi:[1,0]
	v_pk_add_f32 v[30:31], v[30:31], 1.0 op_sel_hi:[1,0]
	v_div_scale_f32 v0, s[0:1], v33, v33, v23
	v_rcp_f32_e32 v34, v0
	s_waitcnt vmcnt(7)
	v_lshlrev_b32_e32 v26, 16, v224
	v_fma_f32 v35, -v0, v34, 1.0
	v_fmac_f32_e32 v34, v35, v34
	v_div_scale_f32 v35, vcc, v23, v33, v23
	v_mul_f32_e32 v36, v35, v34
	v_fma_f32 v37, -v0, v36, v35
	v_fmac_f32_e32 v36, v37, v34
	v_fma_f32 v0, -v0, v36, v35
	v_div_fmas_f32 v0, v0, v34, v36
	v_div_fixup_f32 v23, v0, v33, v23
	v_div_scale_f32 v0, s[0:1], v32, v32, v22
	v_rcp_f32_e32 v33, v0
	v_and_b32_e32 v27, 0xffff0000, v224
	v_lshlrev_b32_e32 v28, 16, v225
	v_and_b32_e32 v29, 0xffff0000, v225
	v_fma_f32 v34, -v0, v33, 1.0
	v_fmac_f32_e32 v33, v34, v33
	v_div_scale_f32 v34, vcc, v22, v32, v22
	v_mul_f32_e32 v35, v34, v33
	v_fma_f32 v36, -v0, v35, v34
	v_fmac_f32_e32 v35, v36, v33
	v_fma_f32 v0, -v0, v35, v34
	v_div_fmas_f32 v0, v0, v33, v35
	v_div_fixup_f32 v22, v0, v32, v22
	v_div_scale_f32 v0, s[0:1], v31, v31, v25
	v_rcp_f32_e32 v32, v0
	v_pk_mul_f32 v[26:27], v[22:23], v[26:27]
	v_fma_f32 v33, -v0, v32, 1.0
	v_fmac_f32_e32 v32, v33, v32
	v_div_scale_f32 v33, vcc, v25, v31, v25
	v_mul_f32_e32 v34, v33, v32
	v_fma_f32 v35, -v0, v34, v33
	v_fmac_f32_e32 v34, v35, v32
	v_fma_f32 v0, -v0, v34, v33
	v_div_fmas_f32 v0, v0, v32, v34
	v_div_fixup_f32 v25, v0, v31, v25
	v_div_scale_f32 v0, s[0:1], v30, v30, v24
	v_rcp_f32_e32 v31, v0
	s_nop 0
	v_fma_f32 v32, -v0, v31, 1.0
	v_fmac_f32_e32 v31, v32, v31
	v_div_scale_f32 v32, vcc, v24, v30, v24
	v_mul_f32_e32 v33, v32, v31
	v_fma_f32 v34, -v0, v33, v32
	v_fmac_f32_e32 v33, v34, v31
	v_fma_f32 v0, -v0, v33, v32
	v_div_fmas_f32 v0, v0, v31, v33
	v_div_fixup_f32 v24, v0, v30, v24
	v_pk_mul_f32 v[28:29], v[24:25], v[28:29]

; DEV float bf2f(bf16_t h) { return __uint_as_float(((unsigned)h) << 16); }
; DEV uint2 pack4(f32x4 v) { uint2 r; r.x = pack2(v[0], v[1]); r.y = pack2(v[2], v[3]); return r; }
; DEV float sigmoid_f(float x) { return 1.f / (1.f + __expf(-x)); }
; DEV float silu_f(float x) { return x / (1.f + __expf(-x)); }
; DEV void phase_G(const Params& p, int b, unsigned char* ldsraw) {
;     ...
;         for (int j = 0; j < 8; j++) {
;           bf16_t* d = dst + (size_t)t * ld + cb + wn * 128 + j * 16 + lg * 4;
;           f32x4 v;
;           if (gate) {
;             uint2 ov = *(const uint2*)d;
;             v[0] = bf2f((bf16_t)(ov.x & 0xffff)) * silu_f(acc[i][j][0]);
;             v[1] = bf2f((bf16_t)(ov.x >> 16)) * silu_f(acc[i][j][1]);
;             v[2] = bf2f((bf16_t)(ov.y & 0xffff)) * silu_f(acc[i][j][2]);
;             v[3] = bf2f((bf16_t)(ov.y >> 16)) * silu_f(acc[i][j][3]);
;           } else {
; #pragma unroll
;             for (int r = 0; r < 4; r++) v[r] = sigmoid_f(acc[i][j][r]);
;           }
;           *(uint2*)d = pack4(v);
;         }
.LBB0_903:
	s_andn2_b64 vcc, exec, s[0:1]
	s_cbranch_vccnz .LBB0_905
	v_pk_add_f32 v[28:29], v[28:29], 1.0 op_sel_hi:[1,0]
	v_pk_add_f32 v[26:27], v[26:27], 1.0 op_sel_hi:[1,0]
	v_div_scale_f32 v0, s[0:1], v29, v29, v19
	v_rcp_f32_e32 v30, v0
	s_waitcnt vmcnt(7)
	v_lshlrev_b32_e32 v22, 16, v226
	v_fma_f32 v31, -v0, v30, 1.0
	v_fmac_f32_e32 v30, v31, v30
	v_div_scale_f32 v31, vcc, v19, v29, v19
	v_mul_f32_e32 v32, v31, v30
	v_fma_f32 v33, -v0, v32, v31
	v_fmac_f32_e32 v32, v33, v30
	v_fma_f32 v0, -v0, v32, v31
	v_div_fmas_f32 v0, v0, v30, v32
	v_div_fixup_f32 v19, v0, v29, v19
	v_div_scale_f32 v0, s[0:1], v28, v28, v18
	v_rcp_f32_e32 v29, v0
	v_and_b32_e32 v23, 0xffff0000, v226
	v_lshlrev_b32_e32 v24, 16, v227
	v_and_b32_e32 v25, 0xffff0000, v227
	v_fma_f32 v30, -v0, v29, 1.0
	v_fmac_f32_e32 v29, v30, v29
	v_div_scale_f32 v30, vcc, v18, v28, v18
	v_mul_f32_e32 v31, v30, v29
	v_fma_f32 v32, -v0, v31, v30
	v_fmac_f32_e32 v31, v32, v29
	v_fma_f32 v0, -v0, v31, v30
	v_div_fmas_f32 v0, v0, v29, v31
	v_div_fixup_f32 v18, v0, v28, v18
	v_div_scale_f32 v0, s[0:1], v27, v27, v21
	v_rcp_f32_e32 v28, v0
	v_pk_mul_f32 v[22:23], v[18:19], v[22:23]
	v_fma_f32 v29, -v0, v28, 1.0
	v_fmac_f32_e32 v28, v29, v28
	v_div_scale_f32 v29, vcc, v21, v27, v21
	v_mul_f32_e32 v30, v29, v28
	v_fma_f32 v31, -v0, v30, v29
	v_fmac_f32_e32 v30, v31, v28
	v_fma_f32 v0, -v0, v30, v29
	v_div_fmas_f32 v0, v0, v28, v30
	v_div_fixup_f32 v21, v0, v27, v21
	v_div_scale_f32 v0, s[0:1], v26, v26, v20
	v_rcp_f32_e32 v27, v0
	s_nop 0
	v_fma_f32 v28, -v0, v27, 1.0
	v_fmac_f32_e32 v27, v28, v27
	v_div_scale_f32 v28, vcc, v20, v26, v20
	v_mul_f32_e32 v29, v28, v27
	v_fma_f32 v30, -v0, v29, v28
	v_fmac_f32_e32 v29, v30, v27
	v_fma_f32 v0, -v0, v29, v28
	v_div_fmas_f32 v0, v0, v27, v29
	v_div_fixup_f32 v20, v0, v26, v20
	v_pk_mul_f32 v[24:25], v[20:21], v[24:25]

; DEV float bf2f(bf16_t h) { return __uint_as_float(((unsigned)h) << 16); }
; DEV uint2 pack4(f32x4 v) { uint2 r; r.x = pack2(v[0], v[1]); r.y = pack2(v[2], v[3]); return r; }
; DEV float sigmoid_f(float x) { return 1.f / (1.f + __expf(-x)); }
; DEV float silu_f(float x) { return x / (1.f + __expf(-x)); }
; DEV void phase_G(const Params& p, int b, unsigned char* ldsraw) {
;     ...
;         for (int j = 0; j < 8; j++) {
;           bf16_t* d = dst + (size_t)t * ld + cb + wn * 128 + j * 16 + lg * 4;
;           f32x4 v;
;           if (gate) {
;             uint2 ov = *(const uint2*)d;
;             v[0] = bf2f((bf16_t)(ov.x & 0xffff)) * silu_f(acc[i][j][0]);
;             v[1] = bf2f((bf16_t)(ov.x >> 16)) * silu_f(acc[i][j][1]);
;             v[2] = bf2f((bf16_t)(ov.y & 0xffff)) * silu_f(acc[i][j][2]);
;             v[3] = bf2f((bf16_t)(ov.y >> 16)) * silu_f(acc[i][j][3]);
;           } else {
; #pragma unroll
;             for (int r = 0; r < 4; r++) v[r] = sigmoid_f(acc[i][j][r]);
;           }
;           *(uint2*)d = pack4(v);
;         }
.LBB0_907:
	s_andn2_b64 vcc, exec, s[0:1]
	s_cbranch_vccnz .LBB0_909
	v_pk_add_f32 v[24:25], v[24:25], 1.0 op_sel_hi:[1,0]
	v_pk_add_f32 v[22:23], v[22:23], 1.0 op_sel_hi:[1,0]
	v_div_scale_f32 v0, s[0:1], v25, v25, v15
	v_rcp_f32_e32 v26, v0
	s_waitcnt vmcnt(7)
	v_lshlrev_b32_e32 v18, 16, v228
	v_fma_f32 v27, -v0, v26, 1.0
	v_fmac_f32_e32 v26, v27, v26
	v_div_scale_f32 v27, vcc, v15, v25, v15
	v_mul_f32_e32 v28, v27, v26
	v_fma_f32 v29, -v0, v28, v27
	v_fmac_f32_e32 v28, v29, v26
	v_fma_f32 v0, -v0, v28, v27
	v_div_fmas_f32 v0, v0, v26, v28
	v_div_fixup_f32 v15, v0, v25, v15
	v_div_scale_f32 v0, s[0:1], v24, v24, v14
	v_rcp_f32_e32 v25, v0
	v_and_b32_e32 v19, 0xffff0000, v228
	v_lshlrev_b32_e32 v20, 16, v229
	v_and_b32_e32 v21, 0xffff0000, v229
	v_fma_f32 v26, -v0, v25, 1.0
	v_fmac_f32_e32 v25, v26, v25
	v_div_scale_f32 v26, vcc, v14, v24, v14
	v_mul_f32_e32 v27, v26, v25
	v_fma_f32 v28, -v0, v27, v26
	v_fmac_f32_e32 v27, v28, v25
	v_fma_f32 v0, -v0, v27, v26
	v_div_fmas_f32 v0, v0, v25, v27
	v_div_fixup_f32 v14, v0, v24, v14
	v_div_scale_f32 v0, s[0:1], v23, v23, v17
	v_rcp_f32_e32 v24, v0
	v_pk_mul_f32 v[18:19], v[14:15], v[18:19]
	v_fma_f32 v25, -v0, v24, 1.0
	v_fmac_f32_e32 v24, v25, v24
	v_div_scale_f32 v25, vcc, v17, v23, v17
	v_mul_f32_e32 v26, v25, v24
	v_fma_f32 v27, -v0, v26, v25
	v_fmac_f32_e32 v26, v27, v24
	v_fma_f32 v0, -v0, v26, v25
	v_div_fmas_f32 v0, v0, v24, v26
	v_div_fixup_f32 v17, v0, v23, v17
	v_div_scale_f32 v0, s[0:1], v22, v22, v16
	v_rcp_f32_e32 v23, v0
	s_nop 0
	v_fma_f32 v24, -v0, v23, 1.0
	v_fmac_f32_e32 v23, v24, v23
	v_div_scale_f32 v24, vcc, v16, v22, v16
	v_mul_f32_e32 v25, v24, v23
	v_fma_f32 v26, -v0, v25, v24
	v_fmac_f32_e32 v25, v26, v23
	v_fma_f32 v0, -v0, v25, v24
	v_div_fmas_f32 v0, v0, v23, v25
	v_div_fixup_f32 v16, v0, v22, v16
	v_pk_mul_f32 v[20:21], v[16:17], v[20:21]

; DEV float bf2f(bf16_t h) { return __uint_as_float(((unsigned)h) << 16); }
; DEV uint2 pack4(f32x4 v) { uint2 r; r.x = pack2(v[0], v[1]); r.y = pack2(v[2], v[3]); return r; }
; DEV float sigmoid_f(float x) { return 1.f / (1.f + __expf(-x)); }
; DEV float silu_f(float x) { return x / (1.f + __expf(-x)); }
; DEV void phase_G(const Params& p, int b, unsigned char* ldsraw) {
;     ...
;         for (int j = 0; j < 8; j++) {
;           bf16_t* d = dst + (size_t)t * ld + cb + wn * 128 + j * 16 + lg * 4;
;           f32x4 v;
;           if (gate) {
;             uint2 ov = *(const uint2*)d;
;             v[0] = bf2f((bf16_t)(ov.x & 0xffff)) * silu_f(acc[i][j][0]);
;             v[1] = bf2f((bf16_t)(ov.x >> 16)) * silu_f(acc[i][j][1]);
;             v[2] = bf2f((bf16_t)(ov.y & 0xffff)) * silu_f(acc[i][j][2]);
;             v[3] = bf2f((bf16_t)(ov.y >> 16)) * silu_f(acc[i][j][3]);
;           } else {
; #pragma unroll
;             for (int r = 0; r < 4; r++) v[r] = sigmoid_f(acc[i][j][r]);
;           }
;           *(uint2*)d = pack4(v);
;         }
.LBB0_911:
	s_andn2_b64 vcc, exec, s[0:1]
	s_cbranch_vccnz .LBB0_913
	v_pk_add_f32 v[20:21], v[20:21], 1.0 op_sel_hi:[1,0]
	v_pk_add_f32 v[18:19], v[18:19], 1.0 op_sel_hi:[1,0]
	v_div_scale_f32 v0, s[0:1], v21, v21, v11
	v_rcp_f32_e32 v22, v0
	s_waitcnt vmcnt(7)
	v_lshlrev_b32_e32 v14, 16, v230
	v_fma_f32 v23, -v0, v22, 1.0
	v_fmac_f32_e32 v22, v23, v22
	v_div_scale_f32 v23, vcc, v11, v21, v11
	v_mul_f32_e32 v24, v23, v22
	v_fma_f32 v25, -v0, v24, v23
	v_fmac_f32_e32 v24, v25, v22
	v_fma_f32 v0, -v0, v24, v23
	v_div_fmas_f32 v0, v0, v22, v24
	v_div_fixup_f32 v11, v0, v21, v11
	v_div_scale_f32 v0, s[0:1], v20, v20, v10
	v_rcp_f32_e32 v21, v0
	v_and_b32_e32 v15, 0xffff0000, v230
	v_lshlrev_b32_e32 v16, 16, v231
	v_and_b32_e32 v17, 0xffff0000, v231
	v_fma_f32 v22, -v0, v21, 1.0
	v_fmac_f32_e32 v21, v22, v21
	v_div_scale_f32 v22, vcc, v10, v20, v10
	v_mul_f32_e32 v23, v22, v21
	v_fma_f32 v24, -v0, v23, v22
	v_fmac_f32_e32 v23, v24, v21
	v_fma_f32 v0, -v0, v23, v22
	v_div_fmas_f32 v0, v0, v21, v23
	v_div_fixup_f32 v10, v0, v20, v10
	v_div_scale_f32 v0, s[0:1], v19, v19, v13
	v_rcp_f32_e32 v20, v0
	v_pk_mul_f32 v[14:15], v[10:11], v[14:15]
	v_fma_f32 v21, -v0, v20, 1.0
	v_fmac_f32_e32 v20, v21, v20
	v_div_scale_f32 v21, vcc, v13, v19, v13
	v_mul_f32_e32 v22, v21, v20
	v_fma_f32 v23, -v0, v22, v21
	v_fmac_f32_e32 v22, v23, v20
	v_fma_f32 v0, -v0, v22, v21
	v_div_fmas_f32 v0, v0, v20, v22
	v_div_fixup_f32 v13, v0, v19, v13
	v_div_scale_f32 v0, s[0:1], v18, v18, v12
	v_rcp_f32_e32 v19, v0
	s_nop 0
	v_fma_f32 v20, -v0, v19, 1.0
	v_fmac_f32_e32 v19, v20, v19
	v_div_scale_f32 v20, vcc, v12, v18, v12
	v_mul_f32_e32 v21, v20, v19
	v_fma_f32 v22, -v0, v21, v20
	v_fmac_f32_e32 v21, v22, v19
	v_fma_f32 v0, -v0, v21, v20
	v_div_fmas_f32 v0, v0, v19, v21
	v_div_fixup_f32 v12, v0, v18, v12
	v_pk_mul_f32 v[16:17], v[12:13], v[16:17]

; DEV float bf2f(bf16_t h) { return __uint_as_float(((unsigned)h) << 16); }
; DEV uint2 pack4(f32x4 v) { uint2 r; r.x = pack2(v[0], v[1]); r.y = pack2(v[2], v[3]); return r; }
; DEV float sigmoid_f(float x) { return 1.f / (1.f + __expf(-x)); }
; DEV float silu_f(float x) { return x / (1.f + __expf(-x)); }
; DEV void phase_G(const Params& p, int b, unsigned char* ldsraw) {
;     ...
;         for (int j = 0; j < 8; j++) {
;           bf16_t* d = dst + (size_t)t * ld + cb + wn * 128 + j * 16 + lg * 4;
;           f32x4 v;
;           if (gate) {
;             uint2 ov = *(const uint2*)d;
;             v[0] = bf2f((bf16_t)(ov.x & 0xffff)) * silu_f(acc[i][j][0]);
;             v[1] = bf2f((bf16_t)(ov.x >> 16)) * silu_f(acc[i][j][1]);
;             v[2] = bf2f((bf16_t)(ov.y & 0xffff)) * silu_f(acc[i][j][2]);
;             v[3] = bf2f((bf16_t)(ov.y >> 16)) * silu_f(acc[i][j][3]);
;           } else {
; #pragma unroll
;             for (int r = 0; r < 4; r++) v[r] = sigmoid_f(acc[i][j][r]);
;           }
;           *(uint2*)d = pack4(v);
;         }
.LBB0_915:
	s_andn2_b64 vcc, exec, s[0:1]
	s_cbranch_vccnz .LBB0_917
	v_pk_add_f32 v[16:17], v[16:17], 1.0 op_sel_hi:[1,0]
	v_pk_add_f32 v[14:15], v[14:15], 1.0 op_sel_hi:[1,0]
	v_div_scale_f32 v0, s[0:1], v17, v17, v7
	v_rcp_f32_e32 v18, v0
	s_waitcnt vmcnt(7)
	v_lshlrev_b32_e32 v10, 16, v232
	v_fma_f32 v19, -v0, v18, 1.0
	v_fmac_f32_e32 v18, v19, v18
	v_div_scale_f32 v19, vcc, v7, v17, v7
	v_mul_f32_e32 v20, v19, v18
	v_fma_f32 v21, -v0, v20, v19
	v_fmac_f32_e32 v20, v21, v18
	v_fma_f32 v0, -v0, v20, v19
	v_div_fmas_f32 v0, v0, v18, v20
	v_div_fixup_f32 v7, v0, v17, v7
	v_div_scale_f32 v0, s[0:1], v16, v16, v6
	v_rcp_f32_e32 v17, v0
	v_and_b32_e32 v11, 0xffff0000, v232
	v_lshlrev_b32_e32 v12, 16, v233
	v_and_b32_e32 v13, 0xffff0000, v233
	v_fma_f32 v18, -v0, v17, 1.0
	v_fmac_f32_e32 v17, v18, v17
	v_div_scale_f32 v18, vcc, v6, v16, v6
	v_mul_f32_e32 v19, v18, v17
	v_fma_f32 v20, -v0, v19, v18
	v_fmac_f32_e32 v19, v20, v17
	v_fma_f32 v0, -v0, v19, v18
	v_div_fmas_f32 v0, v0, v17, v19
	v_div_fixup_f32 v6, v0, v16, v6
	v_div_scale_f32 v0, s[0:1], v15, v15, v9
	v_rcp_f32_e32 v16, v0
	v_pk_mul_f32 v[10:11], v[6:7], v[10:11]
	v_fma_f32 v17, -v0, v16, 1.0
	v_fmac_f32_e32 v16, v17, v16
	v_div_scale_f32 v17, vcc, v9, v15, v9
	v_mul_f32_e32 v18, v17, v16
	v_fma_f32 v19, -v0, v18, v17
	v_fmac_f32_e32 v18, v19, v16
	v_fma_f32 v0, -v0, v18, v17
	v_div_fmas_f32 v0, v0, v16, v18
	v_div_fixup_f32 v9, v0, v15, v9
	v_div_scale_f32 v0, s[0:1], v14, v14, v8
	v_rcp_f32_e32 v15, v0
	s_nop 0
	v_fma_f32 v16, -v0, v15, 1.0
	v_fmac_f32_e32 v15, v16, v15
	v_div_scale_f32 v16, vcc, v8, v14, v8
	v_mul_f32_e32 v17, v16, v15
	v_fma_f32 v18, -v0, v17, v16
	v_fmac_f32_e32 v17, v18, v15
	v_fma_f32 v0, -v0, v17, v16
	v_div_fmas_f32 v0, v0, v15, v17
	v_div_fixup_f32 v8, v0, v14, v8
	v_pk_mul_f32 v[12:13], v[8:9], v[12:13]

; DEV float bf2f(bf16_t h) { return __uint_as_float(((unsigned)h) << 16); }
; DEV uint2 pack4(f32x4 v) { uint2 r; r.x = pack2(v[0], v[1]); r.y = pack2(v[2], v[3]); return r; }
; DEV float sigmoid_f(float x) { return 1.f / (1.f + __expf(-x)); }
; DEV float silu_f(float x) { return x / (1.f + __expf(-x)); }
; DEV void phase_G(const Params& p, int b, unsigned char* ldsraw) {
;     ...
;         for (int j = 0; j < 8; j++) {
;           bf16_t* d = dst + (size_t)t * ld + cb + wn * 128 + j * 16 + lg * 4;
;           f32x4 v;
;           if (gate) {
;             uint2 ov = *(const uint2*)d;
;             v[0] = bf2f((bf16_t)(ov.x & 0xffff)) * silu_f(acc[i][j][0]);
;             v[1] = bf2f((bf16_t)(ov.x >> 16)) * silu_f(acc[i][j][1]);
;             v[2] = bf2f((bf16_t)(ov.y & 0xffff)) * silu_f(acc[i][j][2]);
;             v[3] = bf2f((bf16_t)(ov.y >> 16)) * silu_f(acc[i][j][3]);
;           } else {
; #pragma unroll
;             for (int r = 0; r < 4; r++) v[r] = sigmoid_f(acc[i][j][r]);
;           }
;           *(uint2*)d = pack4(v);
;         }
.LBB0_919:
	s_andn2_b64 vcc, exec, s[0:1]
	s_cbranch_vccnz .LBB0_775
	v_pk_add_f32 v[12:13], v[12:13], 1.0 op_sel_hi:[1,0]
	v_pk_add_f32 v[10:11], v[10:11], 1.0 op_sel_hi:[1,0]
	v_div_scale_f32 v0, s[0:1], v13, v13, v3
	v_rcp_f32_e32 v14, v0
	s_waitcnt vmcnt(7)
	v_lshlrev_b32_e32 v6, 16, v234
	v_fma_f32 v15, -v0, v14, 1.0
	v_fmac_f32_e32 v14, v15, v14
	v_div_scale_f32 v15, vcc, v3, v13, v3
	v_mul_f32_e32 v16, v15, v14
	v_fma_f32 v17, -v0, v16, v15
	v_fmac_f32_e32 v16, v17, v14
	v_fma_f32 v0, -v0, v16, v15
	v_div_fmas_f32 v0, v0, v14, v16
	v_div_fixup_f32 v3, v0, v13, v3
	v_div_scale_f32 v0, s[0:1], v12, v12, v2
	v_rcp_f32_e32 v13, v0
	v_and_b32_e32 v7, 0xffff0000, v234
	v_lshlrev_b32_e32 v8, 16, v235
	v_and_b32_e32 v9, 0xffff0000, v235
	v_fma_f32 v14, -v0, v13, 1.0
	v_fmac_f32_e32 v13, v14, v13
	v_div_scale_f32 v14, vcc, v2, v12, v2
	v_mul_f32_e32 v15, v14, v13
	v_fma_f32 v16, -v0, v15, v14
	v_fmac_f32_e32 v15, v16, v13
	v_fma_f32 v0, -v0, v15, v14
	v_div_fmas_f32 v0, v0, v13, v15
	v_div_fixup_f32 v2, v0, v12, v2
	v_div_scale_f32 v0, s[0:1], v11, v11, v5
	v_rcp_f32_e32 v12, v0
	v_pk_mul_f32 v[6:7], v[2:3], v[6:7]
	v_fma_f32 v13, -v0, v12, 1.0
	v_fmac_f32_e32 v12, v13, v12
	v_div_scale_f32 v13, vcc, v5, v11, v5
	v_mul_f32_e32 v14, v13, v12
	v_fma_f32 v15, -v0, v14, v13
	v_fmac_f32_e32 v14, v15, v12
	v_fma_f32 v0, -v0, v14, v13
	v_div_fmas_f32 v0, v0, v12, v14
	v_div_fixup_f32 v5, v0, v11, v5
	v_div_scale_f32 v0, s[0:1], v10, v10, v4
	v_rcp_f32_e32 v11, v0
	s_nop 0
	v_fma_f32 v12, -v0, v11, 1.0
	v_fmac_f32_e32 v11, v12, v11
	v_div_scale_f32 v12, vcc, v4, v10, v4
	v_mul_f32_e32 v13, v12, v11
	v_fma_f32 v14, -v0, v13, v12
	v_fmac_f32_e32 v13, v14, v11
	v_fma_f32 v0, -v0, v13, v12
	v_div_fmas_f32 v0, v0, v11, v13
	v_div_fixup_f32 v4, v0, v10, v4
	v_pk_mul_f32 v[8:9], v[4:5], v[8:9]
	s_branch .LBB0_775

; #define MFMA(a, b, c) __builtin_amdgcn_mfma_f32_16x16x32_bf16(a, b, c, 0, 0, 0)
; template <int BN, bool TRANS>
; DEV void gemm256_kstep(f32x4 (&acc)[4][BN / 32], const bf16_t* as, const bf16_t* bs, int sw) {
;   constexpr int LS = 64, NJ = BN / 32;
;   bf16x8 a[4];
; #pragma unroll
;   for (int i = 0; i < 4; i++) a[i] = *(const bf16x8*)(as + i * 16 * LS + sw);
; #pragma unroll
;   for (int j = 0; j < NJ; j++) {
;     bf16x8 bb = *(const bf16x8*)(bs + j * 16 * LS + sw);
; #pragma unroll
;     for (int i = 0; i < 4; i++) acc[i][j] = TRANS ? MFMA(a[i], bb, acc[i][j]) : MFMA(bb, a[i], acc[i][j]);
;   }
; }
; template <int BN, bool TRANS = false>
; DEV void gemm256_acc(f32x4 (&acc)[4][BN / 32], const bf16_t* __restrict__ A, int lda, int m_valid,
;                      const bf16_t* __restrict__ Bt, int ldb, int K, bf16_t* lds) {
;     ...
;   for (int kt = 0; kt < nk; kt++) {
;     const int cur = kt & 1;
;     gemm256_kstep<BN, TRANS>(acc, As + cur * A_SZ + aoff, Bs + cur * B_SZ + boff, sw0);
;     __builtin_amdgcn_sched_barrier(0);
;     LSTORE(cur ^ 1)
;     {
;       const int kn = (kt + 2 < nk) ? kt + 2 : nk - 1;
;       GLOAD(kn * 64)
;     }
;     __builtin_amdgcn_sched_barrier(0);
;     gemm256_kstep<BN, TRANS>(acc, As + cur * A_SZ + aoff, Bs + cur * B_SZ + boff, sw1);
;     __syncthreads();
;   }
.Lg128_979:
	s_min_u32 s14, s13, 13
	s_lshl_b32 s82, s14, 7
	s_and_b32 s14, s13, 1
	v_lshl_add_u32 v204, s14, 15, v169
	v_lshl_add_u32 v205, s14, 14, v168
	v_add_u32_e32 v204, v204, v174
	v_add_u32_e32 v205, v205, v174
	s_xor_b32 s14, s14, 1
	s_lshl_b32 s15, s14, 15
	v_lshl_add_u32 v206, s14, 14, v168
	s_lshl_b32 s14, s14, 14
	s_add_i32 s14, s14, 0x10000
	s_waitcnt lgkmcnt(3)
	v_mfma_f32_16x16x32_bf16 v[86:89], v[236:239], v[176:179], v[86:89]
	v_mfma_f32_16x16x32_bf16 v[66:69], v[236:239], v[182:185], v[66:69]
	v_mfma_f32_16x16x32_bf16 v[30:33], v[236:239], v[186:189], v[30:33]
	v_mfma_f32_16x16x32_bf16 v[14:17], v[236:239], v[190:193], v[14:17]
	ds_read_b128 v[236:239], v205
	ds_read_b128 v[220:223], v204
	v_add3_u32 v252, s15, v170, v167
	s_waitcnt vmcnt(5)
	ds_write_b128 v252, v[42:45]
	v_lshl_add_u64 v[42:43], v[154:155], 0, s[82:83]
	global_load_dwordx4 v[42:45], v[42:43], off offset:256
	s_waitcnt lgkmcnt(5)
	v_mfma_f32_16x16x32_bf16 v[82:85], v[240:243], v[176:179], v[82:85]
	v_mfma_f32_16x16x32_bf16 v[62:65], v[240:243], v[182:185], v[62:65]
	v_mfma_f32_16x16x32_bf16 v[26:29], v[240:243], v[186:189], v[26:29]
	v_mfma_f32_16x16x32_bf16 v[10:13], v[240:243], v[190:193], v[10:13]
	ds_read_b128 v[240:243], v205 offset:2048
	ds_read_b128 v[224:227], v204 offset:2048
	v_add3_u32 v252, s15, v171, v167
	s_waitcnt vmcnt(5)
	ds_write_b128 v252, v[46:49]
	v_lshl_add_u64 v[46:47], v[156:157], 0, s[82:83]
	global_load_dwordx4 v[46:49], v[46:47], off offset:256
	v_add3_u32 v252, s15, v172, v167
	s_waitcnt vmcnt(5)
	ds_write_b128 v252, v[50:53]
	v_lshl_add_u64 v[50:51], v[158:159], 0, s[82:83]
	global_load_dwordx4 v[50:53], v[50:51], off offset:256
	s_waitcnt lgkmcnt(8)
	v_mfma_f32_16x16x32_bf16 v[78:81], v[244:247], v[176:179], v[78:81]
	v_mfma_f32_16x16x32_bf16 v[38:41], v[244:247], v[182:185], v[38:41]
	v_mfma_f32_16x16x32_bf16 v[22:25], v[244:247], v[186:189], v[22:25]
	v_mfma_f32_16x16x32_bf16 v[6:9], v[244:247], v[190:193], v[6:9]
	ds_read_b128 v[244:247], v205 offset:4096
	ds_read_b128 v[228:231], v204 offset:4096
	v_add3_u32 v252, s15, v173, v167
	s_waitcnt vmcnt(5)
	ds_write_b128 v252, v[54:57]
	v_lshl_add_u64 v[54:55], v[160:161], 0, s[82:83]
	global_load_dwordx4 v[54:57], v[54:55], off offset:256
	v_add3_u32 v252, s14, v170, v167
	s_waitcnt vmcnt(5)
	ds_write_b128 v252, v[58:61]
	v_lshl_add_u64 v[58:59], v[162:163], 0, s[82:83]
	global_load_dwordx4 v[58:61], v[58:59], off offset:256
	s_waitcnt lgkmcnt(11)
	v_mfma_f32_16x16x32_bf16 v[74:77], v[248:251], v[176:179], v[74:77]
	v_mfma_f32_16x16x32_bf16 v[34:37], v[248:251], v[182:185], v[34:37]
	v_mfma_f32_16x16x32_bf16 v[18:21], v[248:251], v[186:189], v[18:21]
	v_mfma_f32_16x16x32_bf16 v[2:5], v[248:251], v[190:193], v[2:5]
	ds_read_b128 v[248:251], v205 offset:6144
	ds_read_b128 v[232:235], v204 offset:6144
	v_add3_u32 v252, s14, v171, v167
	s_waitcnt vmcnt(5)
	ds_write_b128 v252, v[70:73]
	v_lshl_add_u64 v[70:71], v[164:165], 0, s[82:83]
	global_load_dwordx4 v[70:73], v[70:71], off offset:256
	v_lshlrev_b32_e32 v203, 1, v0
	v_add3_u32 v216, v169, s15, v203
	v_add_u32_e32 v206, v206, v203
	s_waitcnt lgkmcnt(0)
	s_barrier
	ds_read_b128 v[176:179], v216
	ds_read_b128 v[182:185], v216 offset:2048
	ds_read_b128 v[186:189], v216 offset:4096
	ds_read_b128 v[190:193], v216 offset:6144
	v_mfma_f32_16x16x32_bf16 v[86:89], v[236:239], v[220:223], v[86:89]
	v_mfma_f32_16x16x32_bf16 v[66:69], v[236:239], v[224:227], v[66:69]
	v_mfma_f32_16x16x32_bf16 v[30:33], v[236:239], v[228:231], v[30:33]
	v_mfma_f32_16x16x32_bf16 v[14:17], v[236:239], v[232:235], v[14:17]
	ds_read_b128 v[236:239], v206
	v_mfma_f32_16x16x32_bf16 v[82:85], v[240:243], v[220:223], v[82:85]
	v_mfma_f32_16x16x32_bf16 v[62:65], v[240:243], v[224:227], v[62:65]
	v_mfma_f32_16x16x32_bf16 v[26:29], v[240:243], v[228:231], v[26:29]
	v_mfma_f32_16x16x32_bf16 v[10:13], v[240:243], v[232:235], v[10:13]
	ds_read_b128 v[240:243], v206 offset:2048
	v_mfma_f32_16x16x32_bf16 v[78:81], v[244:247], v[220:223], v[78:81]
	v_mfma_f32_16x16x32_bf16 v[38:41], v[244:247], v[224:227], v[38:41]
	v_mfma_f32_16x16x32_bf16 v[22:25], v[244:247], v[228:231], v[22:25]
	v_mfma_f32_16x16x32_bf16 v[6:9], v[244:247], v[232:235], v[6:9]
	ds_read_b128 v[244:247], v206 offset:4096
	v_mfma_f32_16x16x32_bf16 v[74:77], v[248:251], v[220:223], v[74:77]
	v_mfma_f32_16x16x32_bf16 v[34:37], v[248:251], v[224:227], v[34:37]
	v_mfma_f32_16x16x32_bf16 v[18:21], v[248:251], v[228:231], v[18:21]
	v_mfma_f32_16x16x32_bf16 v[2:5], v[248:251], v[232:235], v[2:5]
	ds_read_b128 v[248:251], v206 offset:6144
	s_add_i32 s13, s13, 1
	s_cmp_lg_u32 s13, 16
	s_cbranch_scc1 .Lg128_979
; DEV float bf2f(bf16_t h) { return __uint_as_float(((unsigned)h) << 16); }
; DEV void phase_Y(const Params& p, unsigned char* ldsraw) {
;     ...
; #pragma unroll
;       for (int i = 0; i < 4; i++) {
;         const int t = row0 + wm * 64 + i * 16 + lr;
; #pragma unroll
;         for (int j = 0; j < 4; j++) {
;           uint2 gv = *(const uint2*)(G + (size_t)t * 3072 + br * 1024 + nt * 128 + wn * 64 + j * 16 + lg * 4);
;           y[i][j][0] += bf2f((bf16_t)(gv.x & 0xffff)) * acc[i][j][0];
;           y[i][j][1] += bf2f((bf16_t)(gv.x >> 16)) * acc[i][j][1];
;           y[i][j][2] += bf2f((bf16_t)(gv.y & 0xffff)) * acc[i][j][2];
;           y[i][j][3] += bf2f((bf16_t)(gv.y >> 16)) * acc[i][j][3];
;         }
;       }
	s_waitcnt lgkmcnt(0)
	s_waitcnt vmcnt(5)
	v_mov_b32_e32 v44, v181
	s_lshl_b32 s12, s12, 1
	v_ashrrev_i32_e32 v42, 1, v44
	v_and_b32_e32 v0, 64, v44
	v_and_b32_e32 v42, 0xffffffc0, v42
	s_add_u32 s12, s9, s12
	v_add_u32_e32 v42, s0, v42
	s_addc_u32 s13, s10, 0
	v_lshlrev_b32_e32 v0, 1, v0
	s_waitcnt vmcnt(3)
	v_and_or_b32 v50, v44, 15, v42
	v_lshl_add_u64 v[42:43], s[12:13], 0, v[0:1]
	v_lshrrev_b32_e32 v0, 1, v44
	v_and_b32_e32 v0, 24, v0
	v_lshl_add_u64 v[42:43], v[42:43], 0, v[0:1]
	v_mad_i64_i32 v[44:45], s[12:13], v50, s72, v[42:43]
	global_load_dwordx2 v[220:221], v[44:45], off
	global_load_dwordx2 v[222:223], v[44:45], off offset:32
	global_load_dwordx2 v[224:225], v[44:45], off offset:64
	global_load_dwordx2 v[226:227], v[44:45], off offset:96
	v_or_b32_e32 v0, 16, v50
	s_add_i32 s11, s11, 1
	s_cmp_eq_u32 s11, 3
	s_waitcnt vmcnt(3)
	v_lshlrev_b32_e32 v48, 16, v220
	v_and_b32_e32 v49, 0xffff0000, v220
	v_lshlrev_b32_e32 v46, 16, v221
	v_and_b32_e32 v47, 0xffff0000, v221
	v_pk_fma_f32 v[152:153], v[88:89], v[46:47], v[152:153]
	v_pk_fma_f32 v[150:151], v[86:87], v[48:49], v[150:151]
	s_waitcnt vmcnt(2)
	v_lshlrev_b32_e32 v48, 16, v222
	v_and_b32_e32 v49, 0xffff0000, v222
	v_lshlrev_b32_e32 v46, 16, v223
	v_and_b32_e32 v47, 0xffff0000, v223
	v_pk_fma_f32 v[148:149], v[84:85], v[46:47], v[148:149]
	v_pk_fma_f32 v[146:147], v[82:83], v[48:49], v[146:147]
	s_waitcnt vmcnt(1)
	v_lshlrev_b32_e32 v48, 16, v224
	v_and_b32_e32 v49, 0xffff0000, v224
	v_lshlrev_b32_e32 v46, 16, v225
	v_and_b32_e32 v47, 0xffff0000, v225
	v_pk_fma_f32 v[144:145], v[80:81], v[46:47], v[144:145]
	s_waitcnt vmcnt(0)
	v_lshlrev_b32_e32 v46, 16, v226
	v_and_b32_e32 v47, 0xffff0000, v226
	v_lshlrev_b32_e32 v44, 16, v227
	v_and_b32_e32 v45, 0xffff0000, v227
	v_pk_fma_f32 v[140:141], v[76:77], v[44:45], v[140:141]
	v_mad_i64_i32 v[44:45], s[12:13], v0, s72, v[42:43]
	v_pk_fma_f32 v[138:139], v[74:75], v[46:47], v[138:139]
	global_load_dwordx2 v[220:221], v[44:45], off
	global_load_dwordx2 v[222:223], v[44:45], off offset:32
	global_load_dwordx2 v[224:225], v[44:45], off offset:64
	global_load_dwordx2 v[226:227], v[44:45], off offset:96
	v_pk_fma_f32 v[142:143], v[78:79], v[48:49], v[142:143]
	v_or_b32_e32 v0, 32, v50
	s_waitcnt vmcnt(3)
	v_lshlrev_b32_e32 v48, 16, v220
	v_and_b32_e32 v49, 0xffff0000, v220
	v_lshlrev_b32_e32 v46, 16, v221
	v_and_b32_e32 v47, 0xffff0000, v221
	v_pk_fma_f32 v[136:137], v[68:69], v[46:47], v[136:137]
	v_pk_fma_f32 v[134:135], v[66:67], v[48:49], v[134:135]
	s_waitcnt vmcnt(2)
	v_lshlrev_b32_e32 v48, 16, v222
	v_and_b32_e32 v49, 0xffff0000, v222
	v_lshlrev_b32_e32 v46, 16, v223
	v_and_b32_e32 v47, 0xffff0000, v223
	v_pk_fma_f32 v[132:133], v[64:65], v[46:47], v[132:133]
	v_pk_fma_f32 v[130:131], v[62:63], v[48:49], v[130:131]
	s_waitcnt vmcnt(1)
	v_lshlrev_b32_e32 v48, 16, v224
	v_and_b32_e32 v49, 0xffff0000, v224
	v_pk_fma_f32 v[126:127], v[38:39], v[48:49], v[126:127]
	v_lshlrev_b32_e32 v38, 16, v225
	v_and_b32_e32 v39, 0xffff0000, v225
	v_pk_fma_f32 v[128:129], v[40:41], v[38:39], v[128:129]
	s_waitcnt vmcnt(0)
	v_lshlrev_b32_e32 v40, 16, v226
	v_and_b32_e32 v41, 0xffff0000, v226
	v_pk_fma_f32 v[122:123], v[34:35], v[40:41], v[122:123]
	v_lshlrev_b32_e32 v34, 16, v227
	v_and_b32_e32 v35, 0xffff0000, v227
	v_pk_fma_f32 v[124:125], v[36:37], v[34:35], v[124:125]
	v_mad_i64_i32 v[34:35], s[12:13], v0, s72, v[42:43]
	global_load_dwordx2 v[220:221], v[34:35], off
	global_load_dwordx2 v[222:223], v[34:35], off offset:32
	global_load_dwordx2 v[224:225], v[34:35], off offset:64
	global_load_dwordx2 v[226:227], v[34:35], off offset:96
	v_or_b32_e32 v0, 48, v50
	s_waitcnt vmcnt(3)
	v_lshlrev_b32_e32 v38, 16, v220
	v_and_b32_e32 v39, 0xffff0000, v220
	v_pk_fma_f32 v[118:119], v[30:31], v[38:39], v[118:119]
	v_lshlrev_b32_e32 v30, 16, v221
	v_and_b32_e32 v31, 0xffff0000, v221
	v_pk_fma_f32 v[120:121], v[32:33], v[30:31], v[120:121]
	s_waitcnt vmcnt(2)
	v_lshlrev_b32_e32 v32, 16, v222
	v_and_b32_e32 v33, 0xffff0000, v222
	v_pk_fma_f32 v[114:115], v[26:27], v[32:33], v[114:115]
	v_lshlrev_b32_e32 v26, 16, v223
	v_and_b32_e32 v27, 0xffff0000, v223
	v_pk_fma_f32 v[116:117], v[28:29], v[26:27], v[116:117]
	s_waitcnt vmcnt(1)
	v_lshlrev_b32_e32 v28, 16, v224
	v_and_b32_e32 v29, 0xffff0000, v224
	v_pk_fma_f32 v[110:111], v[22:23], v[28:29], v[110:111]
	v_lshlrev_b32_e32 v22, 16, v225
	v_and_b32_e32 v23, 0xffff0000, v225
	v_pk_fma_f32 v[112:113], v[24:25], v[22:23], v[112:113]
	s_waitcnt vmcnt(0)
	v_lshlrev_b32_e32 v24, 16, v226
	v_and_b32_e32 v25, 0xffff0000, v226
	v_pk_fma_f32 v[106:107], v[18:19], v[24:25], v[106:107]
	v_lshlrev_b32_e32 v18, 16, v227
	v_and_b32_e32 v19, 0xffff0000, v227
	v_pk_fma_f32 v[108:109], v[20:21], v[18:19], v[108:109]
	v_mad_i64_i32 v[18:19], s[12:13], v0, s72, v[42:43]
	global_load_dwordx2 v[220:221], v[18:19], off
	global_load_dwordx2 v[222:223], v[18:19], off offset:32
	global_load_dwordx2 v[224:225], v[18:19], off offset:64
	global_load_dwordx2 v[226:227], v[18:19], off offset:96
	s_waitcnt vmcnt(3)
	v_lshlrev_b32_e32 v22, 16, v220
	v_and_b32_e32 v23, 0xffff0000, v220
	v_pk_fma_f32 v[102:103], v[14:15], v[22:23], v[102:103]
	v_lshlrev_b32_e32 v14, 16, v221
	v_and_b32_e32 v15, 0xffff0000, v221
	v_pk_fma_f32 v[104:105], v[16:17], v[14:15], v[104:105]
	s_waitcnt vmcnt(2)
	v_lshlrev_b32_e32 v16, 16, v222
	v_and_b32_e32 v17, 0xffff0000, v222
	v_pk_fma_f32 v[98:99], v[10:11], v[16:17], v[98:99]
	v_lshlrev_b32_e32 v10, 16, v223
	v_and_b32_e32 v11, 0xffff0000, v223
	v_pk_fma_f32 v[100:101], v[12:13], v[10:11], v[100:101]
	s_waitcnt vmcnt(1)
	v_lshlrev_b32_e32 v12, 16, v224
	v_and_b32_e32 v13, 0xffff0000, v224
	v_pk_fma_f32 v[94:95], v[6:7], v[12:13], v[94:95]
	v_lshlrev_b32_e32 v6, 16, v225
	v_and_b32_e32 v7, 0xffff0000, v225
	v_pk_fma_f32 v[96:97], v[8:9], v[6:7], v[96:97]
	s_waitcnt vmcnt(0)
	v_lshlrev_b32_e32 v8, 16, v226
	v_and_b32_e32 v9, 0xffff0000, v226
	v_pk_fma_f32 v[90:91], v[2:3], v[8:9], v[90:91]
	v_lshlrev_b32_e32 v2, 16, v227
	v_and_b32_e32 v3, 0xffff0000, v227
	v_pk_fma_f32 v[92:93], v[4:5], v[2:3], v[92:93]
	v_mov_b32_e32 v46, v224
	v_mov_b32_e32 v47, v225
	v_mov_b32_e32 v36, v220
	v_mov_b32_e32 v37, v221
	v_mov_b32_e32 v30, v222
	v_mov_b32_e32 v31, v223
	v_mov_b32_e32 v26, v224
	v_mov_b32_e32 v27, v225
	v_mov_b32_e32 v20, v220
	v_mov_b32_e32 v21, v221
	v_mov_b32_e32 v14, v222
	v_mov_b32_e32 v15, v223
	v_mov_b32_e32 v10, v224
	v_mov_b32_e32 v11, v225
	v_mov_b32_e32 v6, v226
	v_mov_b32_e32 v7, v227
	s_cbranch_scc0 .LBB0_978
; DEV int get_tid() { int t = threadIdx.x; asm volatile("" : "+v"(t)); return t; }
; DEV uint2 pack4(f32x4 v) { uint2 r; r.x = pack2(v[0], v[1]); r.y = pack2(v[2], v[3]); return r; }
; DEV void phase_Y(const Params& p, unsigned char* ldsraw) {
;     ...
;     const int tid = get_tid(), lane = tid & 63, wave = tid >> 6, wm = wave >> 1, wn = wave & 1; const int lr = lane & 15, lg = lane >> 4;
; #pragma unroll
;     for (int i = 0; i < 4; i++) {
;       const int t = row0 + wm * 64 + i * 16 + lr;
; #pragma unroll
;       for (int j = 0; j < 4; j++)
;         *(uint2*)(Y + (size_t)t * 1024 + nt * 128 + wn * 64 + j * 16 + lg * 4) = pack4(y[i][j]);
;     }
	v_mov_b32_e32 v3, v181
	v_cvt_pk_bf16_f32 v8, v150, v151
	v_ashrrev_i32_e32 v2, 1, v3
	v_and_b32_e32 v2, 0xffffffc0, v2
	v_and_b32_e32 v0, 64, v3
	v_add_u32_e32 v2, s0, v2
	s_add_u32 s0, s90, s4
	s_addc_u32 s1, s91, s5
	v_lshlrev_b32_e32 v0, 1, v0
	v_and_or_b32 v2, v3, 15, v2
	v_lshl_add_u64 v[4:5], s[0:1], 0, v[0:1]
	v_lshrrev_b32_e32 v0, 1, v3
	v_and_b32_e32 v0, 24, v0
	v_ashrrev_i32_e32 v3, 31, v2
	v_lshl_add_u64 v[4:5], v[4:5], 0, v[0:1]
	v_lshlrev_b64 v[6:7], 11, v[2:3]
	v_lshl_add_u64 v[6:7], v[4:5], 0, v[6:7]
	v_cvt_pk_bf16_f32 v9, v152, v153
	global_store_dwordx2 v[6:7], v[8:9], off
	v_cvt_pk_bf16_f32 v8, v146, v147
	v_cvt_pk_bf16_f32 v9, v148, v149
	global_store_dwordx2 v[6:7], v[8:9], off offset:32
	v_cvt_pk_bf16_f32 v8, v142, v143
	v_cvt_pk_bf16_f32 v9, v144, v145
	global_store_dwordx2 v[6:7], v[8:9], off offset:64
	v_cvt_pk_bf16_f32 v8, v138, v139
	v_cvt_pk_bf16_f32 v9, v140, v141
	global_store_dwordx2 v[6:7], v[8:9], off offset:96
	v_or_b32_e32 v6, 16, v2
	v_ashrrev_i32_e32 v7, 31, v6
	v_lshlrev_b64 v[6:7], 11, v[6:7]
	v_lshl_add_u64 v[6:7], v[4:5], 0, v[6:7]
	v_cvt_pk_bf16_f32 v8, v134, v135
	v_cvt_pk_bf16_f32 v9, v136, v137
	global_store_dwordx2 v[6:7], v[8:9], off
	v_cvt_pk_bf16_f32 v8, v130, v131
	v_cvt_pk_bf16_f32 v9, v132, v133
	global_store_dwordx2 v[6:7], v[8:9], off offset:32
	v_cvt_pk_bf16_f32 v8, v126, v127
	v_cvt_pk_bf16_f32 v9, v128, v129
	global_store_dwordx2 v[6:7], v[8:9], off offset:64
	v_cvt_pk_bf16_f32 v8, v122, v123
	v_cvt_pk_bf16_f32 v9, v124, v125
	global_store_dwordx2 v[6:7], v[8:9], off offset:96
	v_or_b32_e32 v6, 32, v2
	v_or_b32_e32 v2, 48, v2
	v_ashrrev_i32_e32 v7, 31, v6
	v_ashrrev_i32_e32 v3, 31, v2
	v_lshlrev_b64 v[6:7], 11, v[6:7]
	v_lshlrev_b64 v[2:3], 11, v[2:3]
	v_lshl_add_u64 v[6:7], v[4:5], 0, v[6:7]
	v_cvt_pk_bf16_f32 v8, v118, v119
	v_cvt_pk_bf16_f32 v9, v120, v121
	v_lshl_add_u64 v[2:3], v[4:5], 0, v[2:3]
	v_cvt_pk_bf16_f32 v4, v102, v103
	v_cvt_pk_bf16_f32 v5, v104, v105
	global_store_dwordx2 v[6:7], v[8:9], off
	v_cvt_pk_bf16_f32 v8, v114, v115
	v_cvt_pk_bf16_f32 v9, v116, v117
	global_store_dwordx2 v[2:3], v[4:5], off
	v_cvt_pk_bf16_f32 v4, v98, v99
	v_cvt_pk_bf16_f32 v5, v100, v101
	global_store_dwordx2 v[6:7], v[8:9], off offset:32
	v_cvt_pk_bf16_f32 v8, v110, v111
	v_cvt_pk_bf16_f32 v9, v112, v113
	global_store_dwordx2 v[2:3], v[4:5], off offset:32
	v_cvt_pk_bf16_f32 v4, v94, v95
	v_cvt_pk_bf16_f32 v5, v96, v97
	global_store_dwordx2 v[6:7], v[8:9], off offset:64
	v_cvt_pk_bf16_f32 v8, v106, v107
	v_cvt_pk_bf16_f32 v9, v108, v109
	global_store_dwordx2 v[2:3], v[4:5], off offset:64
	v_cvt_pk_bf16_f32 v4, v90, v91
	v_cvt_pk_bf16_f32 v5, v92, v93
	s_mov_b64 s[0:1], 0
	global_store_dwordx2 v[6:7], v[8:9], off offset:96
	global_store_dwordx2 v[2:3], v[4:5], off offset:96
